# v82 + GEMM K-loops: redundant lgkmcnt(0) after each barrier dropped, vmcnt(8)/lgkmcnt(0) pairs merged (128 fewer SALU waits per 2 K-tiles x8 loops)
# baseline (speedup 1.0000x reference)
.LBB0_228:
	s_ashr_i32 s39, s38, 31
	s_lshl_b64 s[40:41], s[38:39], 19
	v_readlane_b32 s42, v238, 7
	v_readlane_b32 s43, v238, 8
	s_add_u32 s40, s42, s40
	s_addc_u32 s41, s43, s41
	s_and_b64 s[42:43], s[2:3], exec
	s_cselect_b32 s5, s41, s1
	s_cselect_b32 s7, s40, s0
	s_ashr_i32 s37, s36, 31
	s_lshl_b64 s[42:43], s[36:37], 19
	s_add_u32 s42, s64, s42
	s_addc_u32 s43, s65, s43
	s_and_b64 s[44:45], s[2:3], exec
	s_cselect_b32 s33, s43, s9
	s_cselect_b32 s37, s42, s8
	s_add_u32 s0, s0, 0x40080
	s_addc_u32 s1, s1, 0
	s_add_u32 s39, s8, 0x100
	s_addc_u32 s46, s9, 0
	s_mov_b32 s47, -2
	ds_read_b128 v[144:147], v170
	ds_read_b128 v[148:151], v170 offset:1024
	ds_read_b128 v[152:155], v170 offset:2048
	ds_read_b128 v[156:159], v170 offset:3072
	ds_read_b128 v[162:165], v171
	ds_read_b128 v[174:177], v171 offset:1024
	ds_read_b128 v[178:181], v171 offset:2048
	ds_read_b128 v[182:185], v171 offset:3072
	s_add_u32 s8, s0, 0xfffc0080
	s_addc_u32 s9, s1, -1
	s_cmp_eq_u32 s47, 12
	s_cselect_b32 s45, s5, s9
	s_cselect_b32 s44, s7, s8
	s_cselect_b32 s9, s33, s46
	s_cselect_b32 s8, s37, s39
	v_lshl_add_u64 v[218:219], s[0:1], 0, v[136:137]
	s_add_i32 m0, s67, 0xc000
	ds_read_b128 v[186:189], v172
	ds_read_b128 v[190:193], v172 offset:1024
	ds_read_b128 v[194:197], v172 offset:2048
	ds_read_b128 v[198:201], v172 offset:3072
	ds_read_b128 v[202:205], v172 offset:4096
	ds_read_b128 v[206:209], v172 offset:5120
	ds_read_b128 v[210:213], v172 offset:6144
	ds_read_b128 v[214:217], v172 offset:7168
	global_load_lds_dwordx4 v[218:219], off
	v_lshl_add_u64 v[218:219], s[0:1], 0, v[138:139]
	s_add_i32 m0, s67, 0xe000
	s_nop 0
	global_load_lds_dwordx4 v[218:219], off
	s_waitcnt vmcnt(8) lgkmcnt(0)
	s_barrier
	v_mfma_f32_16x16x32_bf16 v[124:127], v[144:147], v[186:189], 0
	v_mfma_f32_16x16x32_bf16 v[120:123], v[152:155], v[186:189], 0
	v_mfma_f32_16x16x32_bf16 v[108:111], v[144:147], v[194:197], 0
	v_mfma_f32_16x16x32_bf16 v[104:107], v[152:155], v[194:197], 0
	v_mfma_f32_16x16x32_bf16 v[92:95], v[144:147], v[202:205], 0
	v_mfma_f32_16x16x32_bf16 v[88:91], v[152:155], v[202:205], 0
	v_mfma_f32_16x16x32_bf16 v[76:79], v[144:147], v[210:213], 0
	v_mfma_f32_16x16x32_bf16 v[72:75], v[152:155], v[210:213], 0
	v_mfma_f32_16x16x32_bf16 v[124:127], v[148:151], v[190:193], v[124:127]
	v_mfma_f32_16x16x32_bf16 v[120:123], v[156:159], v[190:193], v[120:123]
	v_mfma_f32_16x16x32_bf16 v[108:111], v[148:151], v[198:201], v[108:111]
	v_mfma_f32_16x16x32_bf16 v[104:107], v[156:159], v[198:201], v[104:107]
	v_mfma_f32_16x16x32_bf16 v[92:95], v[148:151], v[206:209], v[92:95]
	v_mfma_f32_16x16x32_bf16 v[88:91], v[156:159], v[206:209], v[88:91]
	v_mfma_f32_16x16x32_bf16 v[76:79], v[148:151], v[214:217], v[76:79]
	v_mfma_f32_16x16x32_bf16 v[72:75], v[156:159], v[214:217], v[72:75]
	v_mfma_f32_16x16x32_bf16 v[116:119], v[162:165], v[186:189], 0
	v_mfma_f32_16x16x32_bf16 v[112:115], v[178:181], v[186:189], 0
	v_mfma_f32_16x16x32_bf16 v[100:103], v[162:165], v[194:197], 0
	v_mfma_f32_16x16x32_bf16 v[96:99], v[178:181], v[194:197], 0
	v_mfma_f32_16x16x32_bf16 v[84:87], v[162:165], v[202:205], 0
	v_mfma_f32_16x16x32_bf16 v[80:83], v[178:181], v[202:205], 0
	v_mfma_f32_16x16x32_bf16 v[68:71], v[162:165], v[210:213], 0
	v_mfma_f32_16x16x32_bf16 v[64:67], v[178:181], v[210:213], 0
	v_mfma_f32_16x16x32_bf16 v[116:119], v[174:177], v[190:193], v[116:119]
	v_mfma_f32_16x16x32_bf16 v[112:115], v[182:185], v[190:193], v[112:115]
	v_mfma_f32_16x16x32_bf16 v[100:103], v[174:177], v[198:201], v[100:103]
	v_mfma_f32_16x16x32_bf16 v[96:99], v[182:185], v[198:201], v[96:99]
	v_mfma_f32_16x16x32_bf16 v[84:87], v[174:177], v[206:209], v[84:87]
	v_mfma_f32_16x16x32_bf16 v[80:83], v[182:185], v[206:209], v[80:83]
	v_mfma_f32_16x16x32_bf16 v[68:71], v[174:177], v[214:217], v[68:71]
	v_mfma_f32_16x16x32_bf16 v[64:67], v[182:185], v[214:217], v[64:67]
	s_barrier
	s_add_i32 s52, s79, s66
	v_lshl_add_u64 v[218:219], s[8:9], 0, v[130:131]
	s_mov_b32 m0, s52
	ds_read_b128 v[186:189], v172 offset:16384
	ds_read_b128 v[190:193], v172 offset:17408
	ds_read_b128 v[194:197], v172 offset:18432
	ds_read_b128 v[198:201], v172 offset:19456
	ds_read_b128 v[202:205], v172 offset:20480
	ds_read_b128 v[206:209], v172 offset:21504
	ds_read_b128 v[210:213], v172 offset:22528
	ds_read_b128 v[214:217], v172 offset:23552
	global_load_lds_dwordx4 v[218:219], off
	s_add_i32 m0, s52, 0x2000
	s_add_u32 s52, s8, 0x40000
	v_lshl_add_u64 v[220:221], s[8:9], 0, v[134:135]
	s_addc_u32 s53, s9, 0
	s_add_i32 s56, s85, s66
	global_load_lds_dwordx4 v[220:221], off
	v_lshl_add_u64 v[222:223], s[52:53], 0, v[130:131]
	s_mov_b32 m0, s56
	v_lshl_add_u64 v[224:225], s[44:45], 0, v[132:133]
	global_load_lds_dwordx4 v[222:223], off
	v_lshl_add_u64 v[222:223], s[52:53], 0, v[134:135]
	s_add_i32 m0, s56, 0x2000
	s_nop 0
	global_load_lds_dwordx4 v[222:223], off
	v_lshl_add_u64 v[222:223], s[44:45], 0, v[128:129]
	s_mov_b32 m0, s67
	s_nop 0
	global_load_lds_dwordx4 v[222:223], off
	s_mov_b32 m0, s72
	s_nop 0
	global_load_lds_dwordx4 v[224:225], off
	s_waitcnt vmcnt(8) lgkmcnt(0)
	s_barrier
	v_mfma_f32_16x16x32_bf16 v[60:63], v[144:147], v[186:189], 0
	v_mfma_f32_16x16x32_bf16 v[56:59], v[152:155], v[186:189], 0
	v_mfma_f32_16x16x32_bf16 v[44:47], v[144:147], v[194:197], 0
	v_mfma_f32_16x16x32_bf16 v[40:43], v[152:155], v[194:197], 0
	v_mfma_f32_16x16x32_bf16 v[28:31], v[144:147], v[202:205], 0
	v_mfma_f32_16x16x32_bf16 v[24:27], v[152:155], v[202:205], 0
	v_mfma_f32_16x16x32_bf16 v[12:15], v[144:147], v[210:213], 0
	v_mfma_f32_16x16x32_bf16 v[8:11], v[152:155], v[210:213], 0
	v_mfma_f32_16x16x32_bf16 v[60:63], v[148:151], v[190:193], v[60:63]
	v_mfma_f32_16x16x32_bf16 v[56:59], v[156:159], v[190:193], v[56:59]
	v_mfma_f32_16x16x32_bf16 v[44:47], v[148:151], v[198:201], v[44:47]
	v_mfma_f32_16x16x32_bf16 v[40:43], v[156:159], v[198:201], v[40:43]
	v_mfma_f32_16x16x32_bf16 v[28:31], v[148:151], v[206:209], v[28:31]
	v_mfma_f32_16x16x32_bf16 v[24:27], v[156:159], v[206:209], v[24:27]
	v_mfma_f32_16x16x32_bf16 v[12:15], v[148:151], v[214:217], v[12:15]
	v_mfma_f32_16x16x32_bf16 v[8:11], v[156:159], v[214:217], v[8:11]
	v_mfma_f32_16x16x32_bf16 v[52:55], v[162:165], v[186:189], 0
	v_mfma_f32_16x16x32_bf16 v[48:51], v[178:181], v[186:189], 0
	v_mfma_f32_16x16x32_bf16 v[36:39], v[162:165], v[194:197], 0
	v_mfma_f32_16x16x32_bf16 v[32:35], v[178:181], v[194:197], 0
	v_mfma_f32_16x16x32_bf16 v[20:23], v[162:165], v[202:205], 0
	v_mfma_f32_16x16x32_bf16 v[16:19], v[178:181], v[202:205], 0
	v_mfma_f32_16x16x32_bf16 v[4:7], v[162:165], v[210:213], 0
	v_mfma_f32_16x16x32_bf16 v[0:3], v[178:181], v[210:213], 0
	v_mfma_f32_16x16x32_bf16 v[52:55], v[174:177], v[190:193], v[52:55]
	v_mfma_f32_16x16x32_bf16 v[48:51], v[182:185], v[190:193], v[48:51]
	v_mfma_f32_16x16x32_bf16 v[36:39], v[174:177], v[198:201], v[36:39]
	v_mfma_f32_16x16x32_bf16 v[32:35], v[182:185], v[198:201], v[32:35]
	v_mfma_f32_16x16x32_bf16 v[20:23], v[174:177], v[206:209], v[20:23]
	v_mfma_f32_16x16x32_bf16 v[16:19], v[182:185], v[206:209], v[16:19]
	v_mfma_f32_16x16x32_bf16 v[4:7], v[174:177], v[214:217], v[4:7]
	v_mfma_f32_16x16x32_bf16 v[0:3], v[182:185], v[214:217], v[0:3]
	s_barrier
	s_add_i32 s52, 0, 0x18000
	s_add_i32 s53, 0, 0x1c000
	v_add_u32_e32 v156, s52, v168
	v_add_u32_e32 v173, s53, v168
	ds_read_b128 v[144:147], v156
	ds_read_b128 v[148:151], v156 offset:1024
	ds_read_b128 v[152:155], v156 offset:2048
	ds_read_b128 v[156:159], v156 offset:3072
	ds_read_b128 v[162:165], v173
	ds_read_b128 v[174:177], v173 offset:1024
	ds_read_b128 v[178:181], v173 offset:2048
	ds_read_b128 v[182:185], v173 offset:3072
	s_add_u32 s44, s44, 0x40000
	s_addc_u32 s45, s45, 0
	s_mov_b32 m0, s73
	v_lshl_add_u64 v[226:227], s[44:45], 0, v[128:129]
	ds_read_b128 v[186:189], v172 offset:32768
	ds_read_b128 v[190:193], v172 offset:33792
	ds_read_b128 v[194:197], v172 offset:34816
	ds_read_b128 v[198:201], v172 offset:35840
	ds_read_b128 v[202:205], v172 offset:36864
	ds_read_b128 v[206:209], v172 offset:37888
	ds_read_b128 v[210:213], v172 offset:38912
	ds_read_b128 v[214:217], v172 offset:39936
	global_load_lds_dwordx4 v[226:227], off
	v_lshl_add_u64 v[226:227], s[44:45], 0, v[132:133]
	s_mov_b32 m0, s74
	s_nop 0
	global_load_lds_dwordx4 v[226:227], off
	s_waitcnt vmcnt(8) lgkmcnt(0)
	s_barrier
	v_mfma_f32_16x16x32_bf16 v[124:127], v[144:147], v[186:189], v[124:127]
	v_mfma_f32_16x16x32_bf16 v[120:123], v[152:155], v[186:189], v[120:123]
	v_mfma_f32_16x16x32_bf16 v[108:111], v[144:147], v[194:197], v[108:111]
	v_mfma_f32_16x16x32_bf16 v[104:107], v[152:155], v[194:197], v[104:107]
	v_mfma_f32_16x16x32_bf16 v[92:95], v[144:147], v[202:205], v[92:95]
	v_mfma_f32_16x16x32_bf16 v[88:91], v[152:155], v[202:205], v[88:91]
	v_mfma_f32_16x16x32_bf16 v[76:79], v[144:147], v[210:213], v[76:79]
	v_mfma_f32_16x16x32_bf16 v[72:75], v[152:155], v[210:213], v[72:75]
	v_mfma_f32_16x16x32_bf16 v[124:127], v[148:151], v[190:193], v[124:127]
	v_mfma_f32_16x16x32_bf16 v[120:123], v[156:159], v[190:193], v[120:123]
	v_mfma_f32_16x16x32_bf16 v[108:111], v[148:151], v[198:201], v[108:111]
	v_mfma_f32_16x16x32_bf16 v[104:107], v[156:159], v[198:201], v[104:107]
	v_mfma_f32_16x16x32_bf16 v[92:95], v[148:151], v[206:209], v[92:95]
	v_mfma_f32_16x16x32_bf16 v[88:91], v[156:159], v[206:209], v[88:91]
	v_mfma_f32_16x16x32_bf16 v[76:79], v[148:151], v[214:217], v[76:79]
	v_mfma_f32_16x16x32_bf16 v[72:75], v[156:159], v[214:217], v[72:75]
	v_mfma_f32_16x16x32_bf16 v[116:119], v[162:165], v[186:189], v[116:119]
	v_mfma_f32_16x16x32_bf16 v[112:115], v[178:181], v[186:189], v[112:115]
	v_mfma_f32_16x16x32_bf16 v[100:103], v[162:165], v[194:197], v[100:103]
	v_mfma_f32_16x16x32_bf16 v[96:99], v[178:181], v[194:197], v[96:99]
	v_mfma_f32_16x16x32_bf16 v[84:87], v[162:165], v[202:205], v[84:87]
	v_mfma_f32_16x16x32_bf16 v[80:83], v[178:181], v[202:205], v[80:83]
	v_mfma_f32_16x16x32_bf16 v[68:71], v[162:165], v[210:213], v[68:71]
	v_mfma_f32_16x16x32_bf16 v[64:67], v[178:181], v[210:213], v[64:67]
	v_mfma_f32_16x16x32_bf16 v[116:119], v[174:177], v[190:193], v[116:119]
	v_mfma_f32_16x16x32_bf16 v[112:115], v[182:185], v[190:193], v[112:115]
	v_mfma_f32_16x16x32_bf16 v[100:103], v[174:177], v[198:201], v[100:103]
	v_mfma_f32_16x16x32_bf16 v[96:99], v[182:185], v[198:201], v[96:99]
	v_mfma_f32_16x16x32_bf16 v[84:87], v[174:177], v[206:209], v[84:87]
	v_mfma_f32_16x16x32_bf16 v[80:83], v[182:185], v[206:209], v[80:83]
	v_mfma_f32_16x16x32_bf16 v[68:71], v[174:177], v[214:217], v[68:71]
	v_mfma_f32_16x16x32_bf16 v[64:67], v[182:185], v[214:217], v[64:67]
	s_barrier
	s_add_i32 s44, s52, s66
	v_lshl_add_u64 v[218:219], v[218:219], 0, s[30:31]
	s_mov_b32 m0, s44
	ds_read_b128 v[186:189], v172 offset:49152
	ds_read_b128 v[190:193], v172 offset:50176
	ds_read_b128 v[194:197], v172 offset:51200
	ds_read_b128 v[198:201], v172 offset:52224
	ds_read_b128 v[202:205], v172 offset:53248
	ds_read_b128 v[206:209], v172 offset:54272
	ds_read_b128 v[210:213], v172 offset:55296
	ds_read_b128 v[214:217], v172 offset:56320
	global_load_lds_dwordx4 v[218:219], off
	s_add_i32 m0, s44, 0x2000
	s_add_u32 s8, s8, 0x40080
	v_lshl_add_u64 v[218:219], v[220:221], 0, s[30:31]
	s_addc_u32 s9, s9, 0
	s_add_i32 s44, s53, s66
	global_load_lds_dwordx4 v[218:219], off
	v_lshl_add_u64 v[218:219], s[8:9], 0, v[130:131]
	s_mov_b32 m0, s44
	s_nop 0
	global_load_lds_dwordx4 v[218:219], off
	v_lshl_add_u64 v[218:219], s[8:9], 0, v[134:135]
	s_add_i32 m0, s44, 0x2000
	s_nop 0
	global_load_lds_dwordx4 v[218:219], off
	v_lshl_add_u64 v[218:219], v[222:223], 0, s[30:31]
	s_mov_b32 m0, s77
	s_nop 0
	global_load_lds_dwordx4 v[218:219], off
	v_lshl_add_u64 v[218:219], v[224:225], 0, s[30:31]
	s_mov_b32 m0, s78
	s_nop 0
	global_load_lds_dwordx4 v[218:219], off
	s_waitcnt vmcnt(8) lgkmcnt(0)
	s_barrier
	v_mfma_f32_16x16x32_bf16 v[60:63], v[144:147], v[186:189], v[60:63]
	v_mfma_f32_16x16x32_bf16 v[56:59], v[152:155], v[186:189], v[56:59]
	v_mfma_f32_16x16x32_bf16 v[44:47], v[144:147], v[194:197], v[44:47]
	v_mfma_f32_16x16x32_bf16 v[40:43], v[152:155], v[194:197], v[40:43]
	v_mfma_f32_16x16x32_bf16 v[28:31], v[144:147], v[202:205], v[28:31]
	v_mfma_f32_16x16x32_bf16 v[24:27], v[152:155], v[202:205], v[24:27]
	v_mfma_f32_16x16x32_bf16 v[12:15], v[144:147], v[210:213], v[12:15]
	v_mfma_f32_16x16x32_bf16 v[8:11], v[152:155], v[210:213], v[8:11]
	v_mfma_f32_16x16x32_bf16 v[60:63], v[148:151], v[190:193], v[60:63]
	v_mfma_f32_16x16x32_bf16 v[56:59], v[156:159], v[190:193], v[56:59]
	v_mfma_f32_16x16x32_bf16 v[44:47], v[148:151], v[198:201], v[44:47]
	v_mfma_f32_16x16x32_bf16 v[40:43], v[156:159], v[198:201], v[40:43]
	v_mfma_f32_16x16x32_bf16 v[28:31], v[148:151], v[206:209], v[28:31]
	v_mfma_f32_16x16x32_bf16 v[24:27], v[156:159], v[206:209], v[24:27]
	v_mfma_f32_16x16x32_bf16 v[12:15], v[148:151], v[214:217], v[12:15]
	v_mfma_f32_16x16x32_bf16 v[8:11], v[156:159], v[214:217], v[8:11]
	v_mfma_f32_16x16x32_bf16 v[52:55], v[162:165], v[186:189], v[52:55]
	v_mfma_f32_16x16x32_bf16 v[48:51], v[178:181], v[186:189], v[48:51]
	v_mfma_f32_16x16x32_bf16 v[36:39], v[162:165], v[194:197], v[36:39]
	v_mfma_f32_16x16x32_bf16 v[32:35], v[178:181], v[194:197], v[32:35]
	v_mfma_f32_16x16x32_bf16 v[20:23], v[162:165], v[202:205], v[20:23]
	v_mfma_f32_16x16x32_bf16 v[16:19], v[178:181], v[202:205], v[16:19]
	v_mfma_f32_16x16x32_bf16 v[4:7], v[162:165], v[210:213], v[4:7]
	v_mfma_f32_16x16x32_bf16 v[0:3], v[178:181], v[210:213], v[0:3]
	v_mfma_f32_16x16x32_bf16 v[52:55], v[174:177], v[190:193], v[52:55]
	v_mfma_f32_16x16x32_bf16 v[48:51], v[182:185], v[190:193], v[48:51]
	v_mfma_f32_16x16x32_bf16 v[36:39], v[174:177], v[198:201], v[36:39]
	v_mfma_f32_16x16x32_bf16 v[32:35], v[182:185], v[198:201], v[32:35]
	v_mfma_f32_16x16x32_bf16 v[20:23], v[174:177], v[206:209], v[20:23]
	v_mfma_f32_16x16x32_bf16 v[16:19], v[182:185], v[206:209], v[16:19]
	v_mfma_f32_16x16x32_bf16 v[4:7], v[174:177], v[214:217], v[4:7]
	v_mfma_f32_16x16x32_bf16 v[0:3], v[182:185], v[214:217], v[0:3]
	s_barrier
	s_add_i32 s47, s47, 2
	s_add_u32 s0, s0, 0x100
	s_addc_u32 s1, s1, 0
	s_add_u32 s39, s39, 0x100
	s_addc_u32 s46, s46, 0
	s_cmp_gt_u32 s47, 13
	s_cbranch_scc0 .LBB0_229
	s_branch .Lpeel_exit_1
.LBB0_229:
	ds_read_b128 v[144:147], v170
	ds_read_b128 v[148:151], v170 offset:1024
	ds_read_b128 v[152:155], v170 offset:2048
	ds_read_b128 v[156:159], v170 offset:3072
	ds_read_b128 v[162:165], v171
	ds_read_b128 v[174:177], v171 offset:1024
	ds_read_b128 v[178:181], v171 offset:2048
	ds_read_b128 v[182:185], v171 offset:3072
	s_add_u32 s8, s0, 0xfffc0080
	s_addc_u32 s9, s1, -1
	s_cmp_eq_u32 s47, 12
	s_cselect_b32 s45, s5, s9
	s_cselect_b32 s44, s7, s8
	s_cselect_b32 s9, s33, s46
	s_cselect_b32 s8, s37, s39
	v_lshl_add_u64 v[218:219], s[0:1], 0, v[136:137]
	s_add_i32 m0, s67, 0xc000
	ds_read_b128 v[186:189], v172
	ds_read_b128 v[190:193], v172 offset:1024
	ds_read_b128 v[194:197], v172 offset:2048
	ds_read_b128 v[198:201], v172 offset:3072
	ds_read_b128 v[202:205], v172 offset:4096
	ds_read_b128 v[206:209], v172 offset:5120
	ds_read_b128 v[210:213], v172 offset:6144
	ds_read_b128 v[214:217], v172 offset:7168
	global_load_lds_dwordx4 v[218:219], off
	v_lshl_add_u64 v[218:219], s[0:1], 0, v[138:139]
	s_add_i32 m0, s67, 0xe000
	s_nop 0
	global_load_lds_dwordx4 v[218:219], off
	s_waitcnt vmcnt(8) lgkmcnt(0)
	s_barrier
	v_mfma_f32_16x16x32_bf16 v[124:127], v[144:147], v[186:189], v[124:127]
	v_mfma_f32_16x16x32_bf16 v[120:123], v[152:155], v[186:189], v[120:123]
	v_mfma_f32_16x16x32_bf16 v[108:111], v[144:147], v[194:197], v[108:111]
	v_mfma_f32_16x16x32_bf16 v[104:107], v[152:155], v[194:197], v[104:107]
	v_mfma_f32_16x16x32_bf16 v[92:95], v[144:147], v[202:205], v[92:95]
	v_mfma_f32_16x16x32_bf16 v[88:91], v[152:155], v[202:205], v[88:91]
	v_mfma_f32_16x16x32_bf16 v[76:79], v[144:147], v[210:213], v[76:79]
	v_mfma_f32_16x16x32_bf16 v[72:75], v[152:155], v[210:213], v[72:75]
	v_mfma_f32_16x16x32_bf16 v[124:127], v[148:151], v[190:193], v[124:127]
	v_mfma_f32_16x16x32_bf16 v[120:123], v[156:159], v[190:193], v[120:123]
	v_mfma_f32_16x16x32_bf16 v[108:111], v[148:151], v[198:201], v[108:111]
	v_mfma_f32_16x16x32_bf16 v[104:107], v[156:159], v[198:201], v[104:107]
	v_mfma_f32_16x16x32_bf16 v[92:95], v[148:151], v[206:209], v[92:95]
	v_mfma_f32_16x16x32_bf16 v[88:91], v[156:159], v[206:209], v[88:91]
	v_mfma_f32_16x16x32_bf16 v[76:79], v[148:151], v[214:217], v[76:79]
	v_mfma_f32_16x16x32_bf16 v[72:75], v[156:159], v[214:217], v[72:75]
	v_mfma_f32_16x16x32_bf16 v[116:119], v[162:165], v[186:189], v[116:119]
	v_mfma_f32_16x16x32_bf16 v[112:115], v[178:181], v[186:189], v[112:115]
	v_mfma_f32_16x16x32_bf16 v[100:103], v[162:165], v[194:197], v[100:103]
	v_mfma_f32_16x16x32_bf16 v[96:99], v[178:181], v[194:197], v[96:99]
	v_mfma_f32_16x16x32_bf16 v[84:87], v[162:165], v[202:205], v[84:87]
	v_mfma_f32_16x16x32_bf16 v[80:83], v[178:181], v[202:205], v[80:83]
	v_mfma_f32_16x16x32_bf16 v[68:71], v[162:165], v[210:213], v[68:71]
	v_mfma_f32_16x16x32_bf16 v[64:67], v[178:181], v[210:213], v[64:67]
	v_mfma_f32_16x16x32_bf16 v[116:119], v[174:177], v[190:193], v[116:119]
	v_mfma_f32_16x16x32_bf16 v[112:115], v[182:185], v[190:193], v[112:115]
	v_mfma_f32_16x16x32_bf16 v[100:103], v[174:177], v[198:201], v[100:103]
	v_mfma_f32_16x16x32_bf16 v[96:99], v[182:185], v[198:201], v[96:99]
	v_mfma_f32_16x16x32_bf16 v[84:87], v[174:177], v[206:209], v[84:87]
	v_mfma_f32_16x16x32_bf16 v[80:83], v[182:185], v[206:209], v[80:83]
	v_mfma_f32_16x16x32_bf16 v[68:71], v[174:177], v[214:217], v[68:71]
	v_mfma_f32_16x16x32_bf16 v[64:67], v[182:185], v[214:217], v[64:67]
	s_barrier
	s_add_i32 s52, s79, s66
	v_lshl_add_u64 v[218:219], s[8:9], 0, v[130:131]
	s_mov_b32 m0, s52
	ds_read_b128 v[186:189], v172 offset:16384
	ds_read_b128 v[190:193], v172 offset:17408
	ds_read_b128 v[194:197], v172 offset:18432
	ds_read_b128 v[198:201], v172 offset:19456
	ds_read_b128 v[202:205], v172 offset:20480
	ds_read_b128 v[206:209], v172 offset:21504
	ds_read_b128 v[210:213], v172 offset:22528
	ds_read_b128 v[214:217], v172 offset:23552
	global_load_lds_dwordx4 v[218:219], off
	s_add_i32 m0, s52, 0x2000
	s_add_u32 s52, s8, 0x40000
	v_lshl_add_u64 v[220:221], s[8:9], 0, v[134:135]
	s_addc_u32 s53, s9, 0
	s_add_i32 s56, s85, s66
	global_load_lds_dwordx4 v[220:221], off
	v_lshl_add_u64 v[222:223], s[52:53], 0, v[130:131]
	s_mov_b32 m0, s56
	v_lshl_add_u64 v[224:225], s[44:45], 0, v[132:133]
	global_load_lds_dwordx4 v[222:223], off
	v_lshl_add_u64 v[222:223], s[52:53], 0, v[134:135]
	s_add_i32 m0, s56, 0x2000
	s_nop 0
	global_load_lds_dwordx4 v[222:223], off
	v_lshl_add_u64 v[222:223], s[44:45], 0, v[128:129]
	s_mov_b32 m0, s67
	s_nop 0
	global_load_lds_dwordx4 v[222:223], off
	s_mov_b32 m0, s72
	s_nop 0
	global_load_lds_dwordx4 v[224:225], off
	s_waitcnt vmcnt(8) lgkmcnt(0)
	s_barrier
	v_mfma_f32_16x16x32_bf16 v[60:63], v[144:147], v[186:189], v[60:63]
	v_mfma_f32_16x16x32_bf16 v[56:59], v[152:155], v[186:189], v[56:59]
	v_mfma_f32_16x16x32_bf16 v[44:47], v[144:147], v[194:197], v[44:47]
	v_mfma_f32_16x16x32_bf16 v[40:43], v[152:155], v[194:197], v[40:43]
	v_mfma_f32_16x16x32_bf16 v[28:31], v[144:147], v[202:205], v[28:31]
	v_mfma_f32_16x16x32_bf16 v[24:27], v[152:155], v[202:205], v[24:27]
	v_mfma_f32_16x16x32_bf16 v[12:15], v[144:147], v[210:213], v[12:15]
	v_mfma_f32_16x16x32_bf16 v[8:11], v[152:155], v[210:213], v[8:11]
	v_mfma_f32_16x16x32_bf16 v[60:63], v[148:151], v[190:193], v[60:63]
	v_mfma_f32_16x16x32_bf16 v[56:59], v[156:159], v[190:193], v[56:59]
	v_mfma_f32_16x16x32_bf16 v[44:47], v[148:151], v[198:201], v[44:47]
	v_mfma_f32_16x16x32_bf16 v[40:43], v[156:159], v[198:201], v[40:43]
	v_mfma_f32_16x16x32_bf16 v[28:31], v[148:151], v[206:209], v[28:31]
	v_mfma_f32_16x16x32_bf16 v[24:27], v[156:159], v[206:209], v[24:27]
	v_mfma_f32_16x16x32_bf16 v[12:15], v[148:151], v[214:217], v[12:15]
	v_mfma_f32_16x16x32_bf16 v[8:11], v[156:159], v[214:217], v[8:11]
	v_mfma_f32_16x16x32_bf16 v[52:55], v[162:165], v[186:189], v[52:55]
	v_mfma_f32_16x16x32_bf16 v[48:51], v[178:181], v[186:189], v[48:51]
	v_mfma_f32_16x16x32_bf16 v[36:39], v[162:165], v[194:197], v[36:39]
	v_mfma_f32_16x16x32_bf16 v[32:35], v[178:181], v[194:197], v[32:35]
	v_mfma_f32_16x16x32_bf16 v[20:23], v[162:165], v[202:205], v[20:23]
	v_mfma_f32_16x16x32_bf16 v[16:19], v[178:181], v[202:205], v[16:19]
	v_mfma_f32_16x16x32_bf16 v[4:7], v[162:165], v[210:213], v[4:7]
	v_mfma_f32_16x16x32_bf16 v[0:3], v[178:181], v[210:213], v[0:3]
	v_mfma_f32_16x16x32_bf16 v[52:55], v[174:177], v[190:193], v[52:55]
	v_mfma_f32_16x16x32_bf16 v[48:51], v[182:185], v[190:193], v[48:51]
	v_mfma_f32_16x16x32_bf16 v[36:39], v[174:177], v[198:201], v[36:39]
	v_mfma_f32_16x16x32_bf16 v[32:35], v[182:185], v[198:201], v[32:35]
	v_mfma_f32_16x16x32_bf16 v[20:23], v[174:177], v[206:209], v[20:23]
	v_mfma_f32_16x16x32_bf16 v[16:19], v[182:185], v[206:209], v[16:19]
	v_mfma_f32_16x16x32_bf16 v[4:7], v[174:177], v[214:217], v[4:7]
	v_mfma_f32_16x16x32_bf16 v[0:3], v[182:185], v[214:217], v[0:3]
	s_barrier
	s_add_i32 s52, 0, 0x18000
	s_add_i32 s53, 0, 0x1c000
	v_add_u32_e32 v156, s52, v168
	v_add_u32_e32 v173, s53, v168
	ds_read_b128 v[144:147], v156
	ds_read_b128 v[148:151], v156 offset:1024
	ds_read_b128 v[152:155], v156 offset:2048
	ds_read_b128 v[156:159], v156 offset:3072
	ds_read_b128 v[162:165], v173
	ds_read_b128 v[174:177], v173 offset:1024
	ds_read_b128 v[178:181], v173 offset:2048
	ds_read_b128 v[182:185], v173 offset:3072
	s_add_u32 s44, s44, 0x40000
	s_addc_u32 s45, s45, 0
	s_mov_b32 m0, s73
	v_lshl_add_u64 v[226:227], s[44:45], 0, v[128:129]
	ds_read_b128 v[186:189], v172 offset:32768
	ds_read_b128 v[190:193], v172 offset:33792
	ds_read_b128 v[194:197], v172 offset:34816
	ds_read_b128 v[198:201], v172 offset:35840
	ds_read_b128 v[202:205], v172 offset:36864
	ds_read_b128 v[206:209], v172 offset:37888
	ds_read_b128 v[210:213], v172 offset:38912
	ds_read_b128 v[214:217], v172 offset:39936
	global_load_lds_dwordx4 v[226:227], off
	v_lshl_add_u64 v[226:227], s[44:45], 0, v[132:133]
	s_mov_b32 m0, s74
	s_nop 0
	global_load_lds_dwordx4 v[226:227], off
	s_waitcnt vmcnt(8) lgkmcnt(0)
	s_barrier
	v_mfma_f32_16x16x32_bf16 v[124:127], v[144:147], v[186:189], v[124:127]
	v_mfma_f32_16x16x32_bf16 v[120:123], v[152:155], v[186:189], v[120:123]
	v_mfma_f32_16x16x32_bf16 v[108:111], v[144:147], v[194:197], v[108:111]
	v_mfma_f32_16x16x32_bf16 v[104:107], v[152:155], v[194:197], v[104:107]
	v_mfma_f32_16x16x32_bf16 v[92:95], v[144:147], v[202:205], v[92:95]
	v_mfma_f32_16x16x32_bf16 v[88:91], v[152:155], v[202:205], v[88:91]
	v_mfma_f32_16x16x32_bf16 v[76:79], v[144:147], v[210:213], v[76:79]
	v_mfma_f32_16x16x32_bf16 v[72:75], v[152:155], v[210:213], v[72:75]
	v_mfma_f32_16x16x32_bf16 v[124:127], v[148:151], v[190:193], v[124:127]
	v_mfma_f32_16x16x32_bf16 v[120:123], v[156:159], v[190:193], v[120:123]
	v_mfma_f32_16x16x32_bf16 v[108:111], v[148:151], v[198:201], v[108:111]
	v_mfma_f32_16x16x32_bf16 v[104:107], v[156:159], v[198:201], v[104:107]
	v_mfma_f32_16x16x32_bf16 v[92:95], v[148:151], v[206:209], v[92:95]
	v_mfma_f32_16x16x32_bf16 v[88:91], v[156:159], v[206:209], v[88:91]
	v_mfma_f32_16x16x32_bf16 v[76:79], v[148:151], v[214:217], v[76:79]
	v_mfma_f32_16x16x32_bf16 v[72:75], v[156:159], v[214:217], v[72:75]
	v_mfma_f32_16x16x32_bf16 v[116:119], v[162:165], v[186:189], v[116:119]
	v_mfma_f32_16x16x32_bf16 v[112:115], v[178:181], v[186:189], v[112:115]
	v_mfma_f32_16x16x32_bf16 v[100:103], v[162:165], v[194:197], v[100:103]
	v_mfma_f32_16x16x32_bf16 v[96:99], v[178:181], v[194:197], v[96:99]
	v_mfma_f32_16x16x32_bf16 v[84:87], v[162:165], v[202:205], v[84:87]
	v_mfma_f32_16x16x32_bf16 v[80:83], v[178:181], v[202:205], v[80:83]
	v_mfma_f32_16x16x32_bf16 v[68:71], v[162:165], v[210:213], v[68:71]
	v_mfma_f32_16x16x32_bf16 v[64:67], v[178:181], v[210:213], v[64:67]
	v_mfma_f32_16x16x32_bf16 v[116:119], v[174:177], v[190:193], v[116:119]
	v_mfma_f32_16x16x32_bf16 v[112:115], v[182:185], v[190:193], v[112:115]
	v_mfma_f32_16x16x32_bf16 v[100:103], v[174:177], v[198:201], v[100:103]
	v_mfma_f32_16x16x32_bf16 v[96:99], v[182:185], v[198:201], v[96:99]
	v_mfma_f32_16x16x32_bf16 v[84:87], v[174:177], v[206:209], v[84:87]
	v_mfma_f32_16x16x32_bf16 v[80:83], v[182:185], v[206:209], v[80:83]
	v_mfma_f32_16x16x32_bf16 v[68:71], v[174:177], v[214:217], v[68:71]
	v_mfma_f32_16x16x32_bf16 v[64:67], v[182:185], v[214:217], v[64:67]
	s_barrier
	s_add_i32 s44, s52, s66
	v_lshl_add_u64 v[218:219], v[218:219], 0, s[30:31]
	s_mov_b32 m0, s44
	ds_read_b128 v[186:189], v172 offset:49152
	ds_read_b128 v[190:193], v172 offset:50176
	ds_read_b128 v[194:197], v172 offset:51200
	ds_read_b128 v[198:201], v172 offset:52224
	ds_read_b128 v[202:205], v172 offset:53248
	ds_read_b128 v[206:209], v172 offset:54272
	ds_read_b128 v[210:213], v172 offset:55296
	ds_read_b128 v[214:217], v172 offset:56320
	global_load_lds_dwordx4 v[218:219], off
	s_add_i32 m0, s44, 0x2000
	s_add_u32 s8, s8, 0x40080
	v_lshl_add_u64 v[218:219], v[220:221], 0, s[30:31]
	s_addc_u32 s9, s9, 0
	s_add_i32 s44, s53, s66
	global_load_lds_dwordx4 v[218:219], off
	v_lshl_add_u64 v[218:219], s[8:9], 0, v[130:131]
	s_mov_b32 m0, s44
	s_nop 0
	global_load_lds_dwordx4 v[218:219], off
	v_lshl_add_u64 v[218:219], s[8:9], 0, v[134:135]
	s_add_i32 m0, s44, 0x2000
	s_nop 0
	global_load_lds_dwordx4 v[218:219], off
	v_lshl_add_u64 v[218:219], v[222:223], 0, s[30:31]
	s_mov_b32 m0, s77
	s_nop 0
	global_load_lds_dwordx4 v[218:219], off
	v_lshl_add_u64 v[218:219], v[224:225], 0, s[30:31]
	s_mov_b32 m0, s78
	s_nop 0
	global_load_lds_dwordx4 v[218:219], off
	s_waitcnt vmcnt(8) lgkmcnt(0)
	s_barrier
	v_mfma_f32_16x16x32_bf16 v[60:63], v[144:147], v[186:189], v[60:63]
	v_mfma_f32_16x16x32_bf16 v[56:59], v[152:155], v[186:189], v[56:59]
	v_mfma_f32_16x16x32_bf16 v[44:47], v[144:147], v[194:197], v[44:47]
	v_mfma_f32_16x16x32_bf16 v[40:43], v[152:155], v[194:197], v[40:43]
	v_mfma_f32_16x16x32_bf16 v[28:31], v[144:147], v[202:205], v[28:31]
	v_mfma_f32_16x16x32_bf16 v[24:27], v[152:155], v[202:205], v[24:27]
	v_mfma_f32_16x16x32_bf16 v[12:15], v[144:147], v[210:213], v[12:15]
	v_mfma_f32_16x16x32_bf16 v[8:11], v[152:155], v[210:213], v[8:11]
	v_mfma_f32_16x16x32_bf16 v[60:63], v[148:151], v[190:193], v[60:63]
	v_mfma_f32_16x16x32_bf16 v[56:59], v[156:159], v[190:193], v[56:59]
	v_mfma_f32_16x16x32_bf16 v[44:47], v[148:151], v[198:201], v[44:47]
	v_mfma_f32_16x16x32_bf16 v[40:43], v[156:159], v[198:201], v[40:43]
	v_mfma_f32_16x16x32_bf16 v[28:31], v[148:151], v[206:209], v[28:31]
	v_mfma_f32_16x16x32_bf16 v[24:27], v[156:159], v[206:209], v[24:27]
	v_mfma_f32_16x16x32_bf16 v[12:15], v[148:151], v[214:217], v[12:15]
	v_mfma_f32_16x16x32_bf16 v[8:11], v[156:159], v[214:217], v[8:11]
	v_mfma_f32_16x16x32_bf16 v[52:55], v[162:165], v[186:189], v[52:55]
	v_mfma_f32_16x16x32_bf16 v[48:51], v[178:181], v[186:189], v[48:51]
	v_mfma_f32_16x16x32_bf16 v[36:39], v[162:165], v[194:197], v[36:39]
	v_mfma_f32_16x16x32_bf16 v[32:35], v[178:181], v[194:197], v[32:35]
	v_mfma_f32_16x16x32_bf16 v[20:23], v[162:165], v[202:205], v[20:23]
	v_mfma_f32_16x16x32_bf16 v[16:19], v[178:181], v[202:205], v[16:19]
	v_mfma_f32_16x16x32_bf16 v[4:7], v[162:165], v[210:213], v[4:7]
	v_mfma_f32_16x16x32_bf16 v[0:3], v[178:181], v[210:213], v[0:3]
	v_mfma_f32_16x16x32_bf16 v[52:55], v[174:177], v[190:193], v[52:55]
	v_mfma_f32_16x16x32_bf16 v[48:51], v[182:185], v[190:193], v[48:51]
	v_mfma_f32_16x16x32_bf16 v[36:39], v[174:177], v[198:201], v[36:39]
	v_mfma_f32_16x16x32_bf16 v[32:35], v[182:185], v[198:201], v[32:35]
	v_mfma_f32_16x16x32_bf16 v[20:23], v[174:177], v[206:209], v[20:23]
	v_mfma_f32_16x16x32_bf16 v[16:19], v[182:185], v[206:209], v[16:19]
	v_mfma_f32_16x16x32_bf16 v[4:7], v[174:177], v[214:217], v[4:7]
	v_mfma_f32_16x16x32_bf16 v[0:3], v[182:185], v[214:217], v[0:3]
	s_barrier
	s_add_i32 s47, s47, 2
	s_add_u32 s0, s0, 0x100
	s_addc_u32 s1, s1, 0
	s_add_u32 s39, s39, 0x100
	s_addc_u32 s46, s46, 0
	s_cmp_gt_u32 s47, 13
	s_cbranch_scc0 .LBB0_229

.LBB0_550:
	s_add_u32 s59, s16, 0x100
	s_addc_u32 s60, s17, 0
	s_mov_b32 s61, -2
	s_waitcnt lgkmcnt(0)
	ds_read_b128 v[128:131], v188
	ds_read_b128 v[132:135], v188 offset:1024
	ds_read_b128 v[136:139], v188 offset:2048
	ds_read_b128 v[140:143], v188 offset:3072
	ds_read_b128 v[144:147], v189
	ds_read_b128 v[148:151], v189 offset:1024
	ds_read_b128 v[152:155], v189 offset:2048
	ds_read_b128 v[156:159], v189 offset:3072
	s_add_u32 s16, s0, 0x100
	s_addc_u32 s17, s1, 0
	s_cmp_eq_u32 s61, 16
	s_cselect_b32 s35, s7, s17
	s_cselect_b32 s34, s6, s16
	s_cselect_b32 s29, s15, s60
	s_cselect_b32 s28, s14, s59
	v_lshl_add_u64 v[220:221], s[0:1], 0, v[170:171]
	s_add_i32 m0, s39, 0xc000
	ds_read_b128 v[178:181], v190
	ds_read_b128 v[192:195], v190 offset:1024
	ds_read_b128 v[196:199], v190 offset:2048
	ds_read_b128 v[200:203], v190 offset:3072
	ds_read_b128 v[204:207], v190 offset:4096
	ds_read_b128 v[208:211], v190 offset:5120
	ds_read_b128 v[212:215], v190 offset:6144
	ds_read_b128 v[216:219], v190 offset:7168
	global_load_lds_dwordx4 v[220:221], off
	v_lshl_add_u64 v[220:221], s[0:1], 0, v[172:173]
	s_add_i32 m0, s39, 0xe000
	s_nop 0
	global_load_lds_dwordx4 v[220:221], off
	s_waitcnt vmcnt(8) lgkmcnt(0)
	s_barrier
	v_mfma_f32_16x16x32_bf16 v[124:127], v[128:131], v[178:181], 0
	v_mfma_f32_16x16x32_bf16 v[120:123], v[136:139], v[178:181], 0
	v_mfma_f32_16x16x32_bf16 v[108:111], v[128:131], v[196:199], 0
	v_mfma_f32_16x16x32_bf16 v[104:107], v[136:139], v[196:199], 0
	v_mfma_f32_16x16x32_bf16 v[92:95], v[128:131], v[204:207], 0
	v_mfma_f32_16x16x32_bf16 v[88:91], v[136:139], v[204:207], 0
	v_mfma_f32_16x16x32_bf16 v[76:79], v[128:131], v[212:215], 0
	v_mfma_f32_16x16x32_bf16 v[72:75], v[136:139], v[212:215], 0
	v_mfma_f32_16x16x32_bf16 v[124:127], v[132:135], v[192:195], v[124:127]
	v_mfma_f32_16x16x32_bf16 v[120:123], v[140:143], v[192:195], v[120:123]
	v_mfma_f32_16x16x32_bf16 v[108:111], v[132:135], v[200:203], v[108:111]
	v_mfma_f32_16x16x32_bf16 v[104:107], v[140:143], v[200:203], v[104:107]
	v_mfma_f32_16x16x32_bf16 v[92:95], v[132:135], v[208:211], v[92:95]
	v_mfma_f32_16x16x32_bf16 v[88:91], v[140:143], v[208:211], v[88:91]
	v_mfma_f32_16x16x32_bf16 v[76:79], v[132:135], v[216:219], v[76:79]
	v_mfma_f32_16x16x32_bf16 v[72:75], v[140:143], v[216:219], v[72:75]
	v_mfma_f32_16x16x32_bf16 v[116:119], v[144:147], v[178:181], 0
	v_mfma_f32_16x16x32_bf16 v[112:115], v[152:155], v[178:181], 0
	v_mfma_f32_16x16x32_bf16 v[100:103], v[144:147], v[196:199], 0
	v_mfma_f32_16x16x32_bf16 v[96:99], v[152:155], v[196:199], 0
	v_mfma_f32_16x16x32_bf16 v[84:87], v[144:147], v[204:207], 0
	v_mfma_f32_16x16x32_bf16 v[80:83], v[152:155], v[204:207], 0
	v_mfma_f32_16x16x32_bf16 v[68:71], v[144:147], v[212:215], 0
	v_mfma_f32_16x16x32_bf16 v[64:67], v[152:155], v[212:215], 0
	v_mfma_f32_16x16x32_bf16 v[116:119], v[148:151], v[192:195], v[116:119]
	v_mfma_f32_16x16x32_bf16 v[112:115], v[156:159], v[192:195], v[112:115]
	v_mfma_f32_16x16x32_bf16 v[100:103], v[148:151], v[200:203], v[100:103]
	v_mfma_f32_16x16x32_bf16 v[96:99], v[156:159], v[200:203], v[96:99]
	v_mfma_f32_16x16x32_bf16 v[84:87], v[148:151], v[208:211], v[84:87]
	v_mfma_f32_16x16x32_bf16 v[80:83], v[156:159], v[208:211], v[80:83]
	v_mfma_f32_16x16x32_bf16 v[68:71], v[148:151], v[216:219], v[68:71]
	v_mfma_f32_16x16x32_bf16 v[64:67], v[156:159], v[216:219], v[64:67]
	s_barrier
	s_add_i32 s0, s50, s38
	v_lshl_add_u64 v[220:221], s[28:29], 0, v[164:165]
	s_mov_b32 m0, s0
	ds_read_b128 v[178:181], v190 offset:16384
	ds_read_b128 v[192:195], v190 offset:17408
	ds_read_b128 v[196:199], v190 offset:18432
	ds_read_b128 v[200:203], v190 offset:19456
	ds_read_b128 v[204:207], v190 offset:20480
	ds_read_b128 v[208:211], v190 offset:21504
	ds_read_b128 v[212:215], v190 offset:22528
	ds_read_b128 v[216:219], v190 offset:23552
	global_load_lds_dwordx4 v[220:221], off
	s_add_i32 m0, s0, 0x2000
	s_add_u32 s0, s28, 0x50000
	v_lshl_add_u64 v[222:223], s[28:29], 0, v[168:169]
	s_addc_u32 s1, s29, 0
	s_add_i32 s62, s51, s38
	global_load_lds_dwordx4 v[222:223], off
	v_lshl_add_u64 v[224:225], s[0:1], 0, v[164:165]
	s_mov_b32 m0, s62
	v_lshl_add_u64 v[226:227], s[34:35], 0, v[166:167]
	global_load_lds_dwordx4 v[224:225], off
	v_lshl_add_u64 v[224:225], s[0:1], 0, v[168:169]
	s_add_i32 m0, s62, 0x2000
	s_nop 0
	global_load_lds_dwordx4 v[224:225], off
	v_lshl_add_u64 v[224:225], s[34:35], 0, v[162:163]
	s_mov_b32 m0, s39
	s_nop 0
	global_load_lds_dwordx4 v[224:225], off
	s_mov_b32 m0, s40
	s_nop 0
	global_load_lds_dwordx4 v[226:227], off
	s_waitcnt vmcnt(8) lgkmcnt(0)
	s_barrier
	v_mfma_f32_16x16x32_bf16 v[60:63], v[128:131], v[178:181], 0
	v_mfma_f32_16x16x32_bf16 v[56:59], v[136:139], v[178:181], 0
	v_mfma_f32_16x16x32_bf16 v[44:47], v[128:131], v[196:199], 0
	v_mfma_f32_16x16x32_bf16 v[40:43], v[136:139], v[196:199], 0
	v_mfma_f32_16x16x32_bf16 v[28:31], v[128:131], v[204:207], 0
	v_mfma_f32_16x16x32_bf16 v[24:27], v[136:139], v[204:207], 0
	v_mfma_f32_16x16x32_bf16 v[12:15], v[128:131], v[212:215], 0
	v_mfma_f32_16x16x32_bf16 v[8:11], v[136:139], v[212:215], 0
	v_mfma_f32_16x16x32_bf16 v[60:63], v[132:135], v[192:195], v[60:63]
	v_mfma_f32_16x16x32_bf16 v[56:59], v[140:143], v[192:195], v[56:59]
	v_mfma_f32_16x16x32_bf16 v[44:47], v[132:135], v[200:203], v[44:47]
	v_mfma_f32_16x16x32_bf16 v[40:43], v[140:143], v[200:203], v[40:43]
	v_mfma_f32_16x16x32_bf16 v[28:31], v[132:135], v[208:211], v[28:31]
	v_mfma_f32_16x16x32_bf16 v[24:27], v[140:143], v[208:211], v[24:27]
	v_mfma_f32_16x16x32_bf16 v[12:15], v[132:135], v[216:219], v[12:15]
	v_mfma_f32_16x16x32_bf16 v[8:11], v[140:143], v[216:219], v[8:11]
	v_mfma_f32_16x16x32_bf16 v[52:55], v[144:147], v[178:181], 0
	v_mfma_f32_16x16x32_bf16 v[48:51], v[152:155], v[178:181], 0
	v_mfma_f32_16x16x32_bf16 v[36:39], v[144:147], v[196:199], 0
	v_mfma_f32_16x16x32_bf16 v[32:35], v[152:155], v[196:199], 0
	v_mfma_f32_16x16x32_bf16 v[20:23], v[144:147], v[204:207], 0
	v_mfma_f32_16x16x32_bf16 v[16:19], v[152:155], v[204:207], 0
	v_mfma_f32_16x16x32_bf16 v[4:7], v[144:147], v[212:215], 0
	v_mfma_f32_16x16x32_bf16 v[0:3], v[152:155], v[212:215], 0
	v_mfma_f32_16x16x32_bf16 v[52:55], v[148:151], v[192:195], v[52:55]
	v_mfma_f32_16x16x32_bf16 v[48:51], v[156:159], v[192:195], v[48:51]
	v_mfma_f32_16x16x32_bf16 v[36:39], v[148:151], v[200:203], v[36:39]
	v_mfma_f32_16x16x32_bf16 v[32:35], v[156:159], v[200:203], v[32:35]
	v_mfma_f32_16x16x32_bf16 v[20:23], v[148:151], v[208:211], v[20:23]
	v_mfma_f32_16x16x32_bf16 v[16:19], v[156:159], v[208:211], v[16:19]
	v_mfma_f32_16x16x32_bf16 v[4:7], v[148:151], v[216:219], v[4:7]
	v_mfma_f32_16x16x32_bf16 v[0:3], v[156:159], v[216:219], v[0:3]
	s_barrier
	s_add_i32 s62, 0, 0x18000
	s_add_i32 s63, 0, 0x1c000
	v_add_u32_e32 v140, s62, v183
	v_add_u32_e32 v156, s63, v183
	ds_read_b128 v[128:131], v140
	ds_read_b128 v[132:135], v140 offset:1024
	ds_read_b128 v[136:139], v140 offset:2048
	ds_read_b128 v[140:143], v140 offset:3072
	ds_read_b128 v[144:147], v156
	ds_read_b128 v[148:151], v156 offset:1024
	ds_read_b128 v[152:155], v156 offset:2048
	ds_read_b128 v[156:159], v156 offset:3072
	s_add_u32 s0, s34, 0x50000
	s_addc_u32 s1, s35, 0
	s_mov_b32 m0, s41
	v_lshl_add_u64 v[228:229], s[0:1], 0, v[162:163]
	ds_read_b128 v[178:181], v190 offset:32768
	ds_read_b128 v[192:195], v190 offset:33792
	ds_read_b128 v[196:199], v190 offset:34816
	ds_read_b128 v[200:203], v190 offset:35840
	ds_read_b128 v[204:207], v190 offset:36864
	ds_read_b128 v[208:211], v190 offset:37888
	ds_read_b128 v[212:215], v190 offset:38912
	ds_read_b128 v[216:219], v190 offset:39936
	global_load_lds_dwordx4 v[228:229], off
	v_lshl_add_u64 v[228:229], s[0:1], 0, v[166:167]
	s_mov_b32 m0, s42
	s_nop 0
	global_load_lds_dwordx4 v[228:229], off
	s_waitcnt vmcnt(8) lgkmcnt(0)
	s_barrier
	v_mfma_f32_16x16x32_bf16 v[124:127], v[128:131], v[178:181], v[124:127]
	v_mfma_f32_16x16x32_bf16 v[120:123], v[136:139], v[178:181], v[120:123]
	v_mfma_f32_16x16x32_bf16 v[108:111], v[128:131], v[196:199], v[108:111]
	v_mfma_f32_16x16x32_bf16 v[104:107], v[136:139], v[196:199], v[104:107]
	v_mfma_f32_16x16x32_bf16 v[92:95], v[128:131], v[204:207], v[92:95]
	v_mfma_f32_16x16x32_bf16 v[88:91], v[136:139], v[204:207], v[88:91]
	v_mfma_f32_16x16x32_bf16 v[76:79], v[128:131], v[212:215], v[76:79]
	v_mfma_f32_16x16x32_bf16 v[72:75], v[136:139], v[212:215], v[72:75]
	v_mfma_f32_16x16x32_bf16 v[124:127], v[132:135], v[192:195], v[124:127]
	v_mfma_f32_16x16x32_bf16 v[120:123], v[140:143], v[192:195], v[120:123]
	v_mfma_f32_16x16x32_bf16 v[108:111], v[132:135], v[200:203], v[108:111]
	v_mfma_f32_16x16x32_bf16 v[104:107], v[140:143], v[200:203], v[104:107]
	v_mfma_f32_16x16x32_bf16 v[92:95], v[132:135], v[208:211], v[92:95]
	v_mfma_f32_16x16x32_bf16 v[88:91], v[140:143], v[208:211], v[88:91]
	v_mfma_f32_16x16x32_bf16 v[76:79], v[132:135], v[216:219], v[76:79]
	v_mfma_f32_16x16x32_bf16 v[72:75], v[140:143], v[216:219], v[72:75]
	v_mfma_f32_16x16x32_bf16 v[116:119], v[144:147], v[178:181], v[116:119]
	v_mfma_f32_16x16x32_bf16 v[112:115], v[152:155], v[178:181], v[112:115]
	v_mfma_f32_16x16x32_bf16 v[100:103], v[144:147], v[196:199], v[100:103]
	v_mfma_f32_16x16x32_bf16 v[96:99], v[152:155], v[196:199], v[96:99]
	v_mfma_f32_16x16x32_bf16 v[84:87], v[144:147], v[204:207], v[84:87]
	v_mfma_f32_16x16x32_bf16 v[80:83], v[152:155], v[204:207], v[80:83]
	v_mfma_f32_16x16x32_bf16 v[68:71], v[144:147], v[212:215], v[68:71]
	v_mfma_f32_16x16x32_bf16 v[64:67], v[152:155], v[212:215], v[64:67]
	v_mfma_f32_16x16x32_bf16 v[116:119], v[148:151], v[192:195], v[116:119]
	v_mfma_f32_16x16x32_bf16 v[112:115], v[156:159], v[192:195], v[112:115]
	v_mfma_f32_16x16x32_bf16 v[100:103], v[148:151], v[200:203], v[100:103]
	v_mfma_f32_16x16x32_bf16 v[96:99], v[156:159], v[200:203], v[96:99]
	v_mfma_f32_16x16x32_bf16 v[84:87], v[148:151], v[208:211], v[84:87]
	v_mfma_f32_16x16x32_bf16 v[80:83], v[156:159], v[208:211], v[80:83]
	v_mfma_f32_16x16x32_bf16 v[68:71], v[148:151], v[216:219], v[68:71]
	v_mfma_f32_16x16x32_bf16 v[64:67], v[156:159], v[216:219], v[64:67]
	s_barrier
	s_add_i32 s0, s62, s38
	v_lshl_add_u64 v[220:221], v[220:221], 0, s[10:11]
	s_mov_b32 m0, s0
	ds_read_b128 v[178:181], v190 offset:49152
	ds_read_b128 v[192:195], v190 offset:50176
	ds_read_b128 v[196:199], v190 offset:51200
	ds_read_b128 v[200:203], v190 offset:52224
	ds_read_b128 v[204:207], v190 offset:53248
	ds_read_b128 v[208:211], v190 offset:54272
	ds_read_b128 v[212:215], v190 offset:55296
	ds_read_b128 v[216:219], v190 offset:56320
	global_load_lds_dwordx4 v[220:221], off
	s_add_i32 m0, s0, 0x2000
	s_add_u32 s0, s28, 0x50080
	v_lshl_add_u64 v[220:221], v[222:223], 0, s[10:11]
	s_addc_u32 s1, s29, 0
	s_add_i32 s28, s63, s38
	global_load_lds_dwordx4 v[220:221], off
	v_lshl_add_u64 v[220:221], s[0:1], 0, v[164:165]
	s_mov_b32 m0, s28
	s_nop 0
	global_load_lds_dwordx4 v[220:221], off
	v_lshl_add_u64 v[220:221], s[0:1], 0, v[168:169]
	s_add_i32 m0, s28, 0x2000
	s_nop 0
	global_load_lds_dwordx4 v[220:221], off
	v_lshl_add_u64 v[220:221], v[224:225], 0, s[10:11]
	s_mov_b32 m0, s45
	s_nop 0
	global_load_lds_dwordx4 v[220:221], off
	v_lshl_add_u64 v[220:221], v[226:227], 0, s[10:11]
	s_mov_b32 m0, s46
	s_nop 0
	global_load_lds_dwordx4 v[220:221], off
	s_waitcnt vmcnt(8) lgkmcnt(0)
	s_barrier
	v_mfma_f32_16x16x32_bf16 v[60:63], v[128:131], v[178:181], v[60:63]
	v_mfma_f32_16x16x32_bf16 v[56:59], v[136:139], v[178:181], v[56:59]
	v_mfma_f32_16x16x32_bf16 v[44:47], v[128:131], v[196:199], v[44:47]
	v_mfma_f32_16x16x32_bf16 v[40:43], v[136:139], v[196:199], v[40:43]
	v_mfma_f32_16x16x32_bf16 v[28:31], v[128:131], v[204:207], v[28:31]
	v_mfma_f32_16x16x32_bf16 v[24:27], v[136:139], v[204:207], v[24:27]
	v_mfma_f32_16x16x32_bf16 v[12:15], v[128:131], v[212:215], v[12:15]
	v_mfma_f32_16x16x32_bf16 v[8:11], v[136:139], v[212:215], v[8:11]
	v_mfma_f32_16x16x32_bf16 v[60:63], v[132:135], v[192:195], v[60:63]
	v_mfma_f32_16x16x32_bf16 v[56:59], v[140:143], v[192:195], v[56:59]
	v_mfma_f32_16x16x32_bf16 v[44:47], v[132:135], v[200:203], v[44:47]
	v_mfma_f32_16x16x32_bf16 v[40:43], v[140:143], v[200:203], v[40:43]
	v_mfma_f32_16x16x32_bf16 v[28:31], v[132:135], v[208:211], v[28:31]
	v_mfma_f32_16x16x32_bf16 v[24:27], v[140:143], v[208:211], v[24:27]
	v_mfma_f32_16x16x32_bf16 v[12:15], v[132:135], v[216:219], v[12:15]
	v_mfma_f32_16x16x32_bf16 v[8:11], v[140:143], v[216:219], v[8:11]
	v_mfma_f32_16x16x32_bf16 v[52:55], v[144:147], v[178:181], v[52:55]
	v_mfma_f32_16x16x32_bf16 v[48:51], v[152:155], v[178:181], v[48:51]
	v_mfma_f32_16x16x32_bf16 v[36:39], v[144:147], v[196:199], v[36:39]
	v_mfma_f32_16x16x32_bf16 v[32:35], v[152:155], v[196:199], v[32:35]
	v_mfma_f32_16x16x32_bf16 v[20:23], v[144:147], v[204:207], v[20:23]
	v_mfma_f32_16x16x32_bf16 v[16:19], v[152:155], v[204:207], v[16:19]
	v_mfma_f32_16x16x32_bf16 v[4:7], v[144:147], v[212:215], v[4:7]
	v_mfma_f32_16x16x32_bf16 v[0:3], v[152:155], v[212:215], v[0:3]
	v_mfma_f32_16x16x32_bf16 v[52:55], v[148:151], v[192:195], v[52:55]
	v_mfma_f32_16x16x32_bf16 v[48:51], v[156:159], v[192:195], v[48:51]
	v_mfma_f32_16x16x32_bf16 v[36:39], v[148:151], v[200:203], v[36:39]
	v_mfma_f32_16x16x32_bf16 v[32:35], v[156:159], v[200:203], v[32:35]
	v_mfma_f32_16x16x32_bf16 v[20:23], v[148:151], v[208:211], v[20:23]
	v_mfma_f32_16x16x32_bf16 v[16:19], v[156:159], v[208:211], v[16:19]
	v_mfma_f32_16x16x32_bf16 v[4:7], v[148:151], v[216:219], v[4:7]
	v_mfma_f32_16x16x32_bf16 v[0:3], v[156:159], v[216:219], v[0:3]
	s_barrier
	s_add_i32 s61, s61, 2
	s_add_u32 s59, s59, 0x100
	s_addc_u32 s60, s60, 0
	s_cmp_gt_u32 s61, 17
	s_mov_b64 s[0:1], s[16:17]
	s_cbranch_scc0 .LBB0_551
	s_branch .Lpeel_exit_2
.LBB0_551:
	ds_read_b128 v[128:131], v188
	ds_read_b128 v[132:135], v188 offset:1024
	ds_read_b128 v[136:139], v188 offset:2048
	ds_read_b128 v[140:143], v188 offset:3072
	ds_read_b128 v[144:147], v189
	ds_read_b128 v[148:151], v189 offset:1024
	ds_read_b128 v[152:155], v189 offset:2048
	ds_read_b128 v[156:159], v189 offset:3072
	s_add_u32 s16, s0, 0x100
	s_addc_u32 s17, s1, 0
	s_cmp_eq_u32 s61, 16
	s_cselect_b32 s35, s7, s17
	s_cselect_b32 s34, s6, s16
	s_cselect_b32 s29, s15, s60
	s_cselect_b32 s28, s14, s59
	v_lshl_add_u64 v[220:221], s[0:1], 0, v[170:171]
	s_add_i32 m0, s39, 0xc000
	ds_read_b128 v[178:181], v190
	ds_read_b128 v[192:195], v190 offset:1024
	ds_read_b128 v[196:199], v190 offset:2048
	ds_read_b128 v[200:203], v190 offset:3072
	ds_read_b128 v[204:207], v190 offset:4096
	ds_read_b128 v[208:211], v190 offset:5120
	ds_read_b128 v[212:215], v190 offset:6144
	ds_read_b128 v[216:219], v190 offset:7168
	global_load_lds_dwordx4 v[220:221], off
	v_lshl_add_u64 v[220:221], s[0:1], 0, v[172:173]
	s_add_i32 m0, s39, 0xe000
	s_nop 0
	global_load_lds_dwordx4 v[220:221], off
	s_waitcnt vmcnt(8) lgkmcnt(0)
	s_barrier
	v_mfma_f32_16x16x32_bf16 v[124:127], v[128:131], v[178:181], v[124:127]
	v_mfma_f32_16x16x32_bf16 v[120:123], v[136:139], v[178:181], v[120:123]
	v_mfma_f32_16x16x32_bf16 v[108:111], v[128:131], v[196:199], v[108:111]
	v_mfma_f32_16x16x32_bf16 v[104:107], v[136:139], v[196:199], v[104:107]
	v_mfma_f32_16x16x32_bf16 v[92:95], v[128:131], v[204:207], v[92:95]
	v_mfma_f32_16x16x32_bf16 v[88:91], v[136:139], v[204:207], v[88:91]
	v_mfma_f32_16x16x32_bf16 v[76:79], v[128:131], v[212:215], v[76:79]
	v_mfma_f32_16x16x32_bf16 v[72:75], v[136:139], v[212:215], v[72:75]
	v_mfma_f32_16x16x32_bf16 v[124:127], v[132:135], v[192:195], v[124:127]
	v_mfma_f32_16x16x32_bf16 v[120:123], v[140:143], v[192:195], v[120:123]
	v_mfma_f32_16x16x32_bf16 v[108:111], v[132:135], v[200:203], v[108:111]
	v_mfma_f32_16x16x32_bf16 v[104:107], v[140:143], v[200:203], v[104:107]
	v_mfma_f32_16x16x32_bf16 v[92:95], v[132:135], v[208:211], v[92:95]
	v_mfma_f32_16x16x32_bf16 v[88:91], v[140:143], v[208:211], v[88:91]
	v_mfma_f32_16x16x32_bf16 v[76:79], v[132:135], v[216:219], v[76:79]
	v_mfma_f32_16x16x32_bf16 v[72:75], v[140:143], v[216:219], v[72:75]
	v_mfma_f32_16x16x32_bf16 v[116:119], v[144:147], v[178:181], v[116:119]
	v_mfma_f32_16x16x32_bf16 v[112:115], v[152:155], v[178:181], v[112:115]
	v_mfma_f32_16x16x32_bf16 v[100:103], v[144:147], v[196:199], v[100:103]
	v_mfma_f32_16x16x32_bf16 v[96:99], v[152:155], v[196:199], v[96:99]
	v_mfma_f32_16x16x32_bf16 v[84:87], v[144:147], v[204:207], v[84:87]
	v_mfma_f32_16x16x32_bf16 v[80:83], v[152:155], v[204:207], v[80:83]
	v_mfma_f32_16x16x32_bf16 v[68:71], v[144:147], v[212:215], v[68:71]
	v_mfma_f32_16x16x32_bf16 v[64:67], v[152:155], v[212:215], v[64:67]
	v_mfma_f32_16x16x32_bf16 v[116:119], v[148:151], v[192:195], v[116:119]
	v_mfma_f32_16x16x32_bf16 v[112:115], v[156:159], v[192:195], v[112:115]
	v_mfma_f32_16x16x32_bf16 v[100:103], v[148:151], v[200:203], v[100:103]
	v_mfma_f32_16x16x32_bf16 v[96:99], v[156:159], v[200:203], v[96:99]
	v_mfma_f32_16x16x32_bf16 v[84:87], v[148:151], v[208:211], v[84:87]
	v_mfma_f32_16x16x32_bf16 v[80:83], v[156:159], v[208:211], v[80:83]
	v_mfma_f32_16x16x32_bf16 v[68:71], v[148:151], v[216:219], v[68:71]
	v_mfma_f32_16x16x32_bf16 v[64:67], v[156:159], v[216:219], v[64:67]
	s_barrier
	s_add_i32 s0, s50, s38
	v_lshl_add_u64 v[220:221], s[28:29], 0, v[164:165]
	s_mov_b32 m0, s0
	ds_read_b128 v[178:181], v190 offset:16384
	ds_read_b128 v[192:195], v190 offset:17408
	ds_read_b128 v[196:199], v190 offset:18432
	ds_read_b128 v[200:203], v190 offset:19456
	ds_read_b128 v[204:207], v190 offset:20480
	ds_read_b128 v[208:211], v190 offset:21504
	ds_read_b128 v[212:215], v190 offset:22528
	ds_read_b128 v[216:219], v190 offset:23552
	global_load_lds_dwordx4 v[220:221], off
	s_add_i32 m0, s0, 0x2000
	s_add_u32 s0, s28, 0x50000
	v_lshl_add_u64 v[222:223], s[28:29], 0, v[168:169]
	s_addc_u32 s1, s29, 0
	s_add_i32 s62, s51, s38
	global_load_lds_dwordx4 v[222:223], off
	v_lshl_add_u64 v[224:225], s[0:1], 0, v[164:165]
	s_mov_b32 m0, s62
	v_lshl_add_u64 v[226:227], s[34:35], 0, v[166:167]
	global_load_lds_dwordx4 v[224:225], off
	v_lshl_add_u64 v[224:225], s[0:1], 0, v[168:169]
	s_add_i32 m0, s62, 0x2000
	s_nop 0
	global_load_lds_dwordx4 v[224:225], off
	v_lshl_add_u64 v[224:225], s[34:35], 0, v[162:163]
	s_mov_b32 m0, s39
	s_nop 0
	global_load_lds_dwordx4 v[224:225], off
	s_mov_b32 m0, s40
	s_nop 0
	global_load_lds_dwordx4 v[226:227], off
	s_waitcnt vmcnt(8) lgkmcnt(0)
	s_barrier
	v_mfma_f32_16x16x32_bf16 v[60:63], v[128:131], v[178:181], v[60:63]
	v_mfma_f32_16x16x32_bf16 v[56:59], v[136:139], v[178:181], v[56:59]
	v_mfma_f32_16x16x32_bf16 v[44:47], v[128:131], v[196:199], v[44:47]
	v_mfma_f32_16x16x32_bf16 v[40:43], v[136:139], v[196:199], v[40:43]
	v_mfma_f32_16x16x32_bf16 v[28:31], v[128:131], v[204:207], v[28:31]
	v_mfma_f32_16x16x32_bf16 v[24:27], v[136:139], v[204:207], v[24:27]
	v_mfma_f32_16x16x32_bf16 v[12:15], v[128:131], v[212:215], v[12:15]
	v_mfma_f32_16x16x32_bf16 v[8:11], v[136:139], v[212:215], v[8:11]
	v_mfma_f32_16x16x32_bf16 v[60:63], v[132:135], v[192:195], v[60:63]
	v_mfma_f32_16x16x32_bf16 v[56:59], v[140:143], v[192:195], v[56:59]
	v_mfma_f32_16x16x32_bf16 v[44:47], v[132:135], v[200:203], v[44:47]
	v_mfma_f32_16x16x32_bf16 v[40:43], v[140:143], v[200:203], v[40:43]
	v_mfma_f32_16x16x32_bf16 v[28:31], v[132:135], v[208:211], v[28:31]
	v_mfma_f32_16x16x32_bf16 v[24:27], v[140:143], v[208:211], v[24:27]
	v_mfma_f32_16x16x32_bf16 v[12:15], v[132:135], v[216:219], v[12:15]
	v_mfma_f32_16x16x32_bf16 v[8:11], v[140:143], v[216:219], v[8:11]
	v_mfma_f32_16x16x32_bf16 v[52:55], v[144:147], v[178:181], v[52:55]
	v_mfma_f32_16x16x32_bf16 v[48:51], v[152:155], v[178:181], v[48:51]
	v_mfma_f32_16x16x32_bf16 v[36:39], v[144:147], v[196:199], v[36:39]
	v_mfma_f32_16x16x32_bf16 v[32:35], v[152:155], v[196:199], v[32:35]
	v_mfma_f32_16x16x32_bf16 v[20:23], v[144:147], v[204:207], v[20:23]
	v_mfma_f32_16x16x32_bf16 v[16:19], v[152:155], v[204:207], v[16:19]
	v_mfma_f32_16x16x32_bf16 v[4:7], v[144:147], v[212:215], v[4:7]
	v_mfma_f32_16x16x32_bf16 v[0:3], v[152:155], v[212:215], v[0:3]
	v_mfma_f32_16x16x32_bf16 v[52:55], v[148:151], v[192:195], v[52:55]
	v_mfma_f32_16x16x32_bf16 v[48:51], v[156:159], v[192:195], v[48:51]
	v_mfma_f32_16x16x32_bf16 v[36:39], v[148:151], v[200:203], v[36:39]
	v_mfma_f32_16x16x32_bf16 v[32:35], v[156:159], v[200:203], v[32:35]
	v_mfma_f32_16x16x32_bf16 v[20:23], v[148:151], v[208:211], v[20:23]
	v_mfma_f32_16x16x32_bf16 v[16:19], v[156:159], v[208:211], v[16:19]
	v_mfma_f32_16x16x32_bf16 v[4:7], v[148:151], v[216:219], v[4:7]
	v_mfma_f32_16x16x32_bf16 v[0:3], v[156:159], v[216:219], v[0:3]
	s_barrier
	s_add_i32 s62, 0, 0x18000
	s_add_i32 s63, 0, 0x1c000
	v_add_u32_e32 v140, s62, v183
	v_add_u32_e32 v156, s63, v183
	ds_read_b128 v[128:131], v140
	ds_read_b128 v[132:135], v140 offset:1024
	ds_read_b128 v[136:139], v140 offset:2048
	ds_read_b128 v[140:143], v140 offset:3072
	ds_read_b128 v[144:147], v156
	ds_read_b128 v[148:151], v156 offset:1024
	ds_read_b128 v[152:155], v156 offset:2048
	ds_read_b128 v[156:159], v156 offset:3072
	s_add_u32 s0, s34, 0x50000
	s_addc_u32 s1, s35, 0
	s_mov_b32 m0, s41
	v_lshl_add_u64 v[228:229], s[0:1], 0, v[162:163]
	ds_read_b128 v[178:181], v190 offset:32768
	ds_read_b128 v[192:195], v190 offset:33792
	ds_read_b128 v[196:199], v190 offset:34816
	ds_read_b128 v[200:203], v190 offset:35840
	ds_read_b128 v[204:207], v190 offset:36864
	ds_read_b128 v[208:211], v190 offset:37888
	ds_read_b128 v[212:215], v190 offset:38912
	ds_read_b128 v[216:219], v190 offset:39936
	global_load_lds_dwordx4 v[228:229], off
	v_lshl_add_u64 v[228:229], s[0:1], 0, v[166:167]
	s_mov_b32 m0, s42
	s_nop 0
	global_load_lds_dwordx4 v[228:229], off
	s_waitcnt vmcnt(8) lgkmcnt(0)
	s_barrier
	v_mfma_f32_16x16x32_bf16 v[124:127], v[128:131], v[178:181], v[124:127]
	v_mfma_f32_16x16x32_bf16 v[120:123], v[136:139], v[178:181], v[120:123]
	v_mfma_f32_16x16x32_bf16 v[108:111], v[128:131], v[196:199], v[108:111]
	v_mfma_f32_16x16x32_bf16 v[104:107], v[136:139], v[196:199], v[104:107]
	v_mfma_f32_16x16x32_bf16 v[92:95], v[128:131], v[204:207], v[92:95]
	v_mfma_f32_16x16x32_bf16 v[88:91], v[136:139], v[204:207], v[88:91]
	v_mfma_f32_16x16x32_bf16 v[76:79], v[128:131], v[212:215], v[76:79]
	v_mfma_f32_16x16x32_bf16 v[72:75], v[136:139], v[212:215], v[72:75]
	v_mfma_f32_16x16x32_bf16 v[124:127], v[132:135], v[192:195], v[124:127]
	v_mfma_f32_16x16x32_bf16 v[120:123], v[140:143], v[192:195], v[120:123]
	v_mfma_f32_16x16x32_bf16 v[108:111], v[132:135], v[200:203], v[108:111]
	v_mfma_f32_16x16x32_bf16 v[104:107], v[140:143], v[200:203], v[104:107]
	v_mfma_f32_16x16x32_bf16 v[92:95], v[132:135], v[208:211], v[92:95]
	v_mfma_f32_16x16x32_bf16 v[88:91], v[140:143], v[208:211], v[88:91]
	v_mfma_f32_16x16x32_bf16 v[76:79], v[132:135], v[216:219], v[76:79]
	v_mfma_f32_16x16x32_bf16 v[72:75], v[140:143], v[216:219], v[72:75]
	v_mfma_f32_16x16x32_bf16 v[116:119], v[144:147], v[178:181], v[116:119]
	v_mfma_f32_16x16x32_bf16 v[112:115], v[152:155], v[178:181], v[112:115]
	v_mfma_f32_16x16x32_bf16 v[100:103], v[144:147], v[196:199], v[100:103]
	v_mfma_f32_16x16x32_bf16 v[96:99], v[152:155], v[196:199], v[96:99]
	v_mfma_f32_16x16x32_bf16 v[84:87], v[144:147], v[204:207], v[84:87]
	v_mfma_f32_16x16x32_bf16 v[80:83], v[152:155], v[204:207], v[80:83]
	v_mfma_f32_16x16x32_bf16 v[68:71], v[144:147], v[212:215], v[68:71]
	v_mfma_f32_16x16x32_bf16 v[64:67], v[152:155], v[212:215], v[64:67]
	v_mfma_f32_16x16x32_bf16 v[116:119], v[148:151], v[192:195], v[116:119]
	v_mfma_f32_16x16x32_bf16 v[112:115], v[156:159], v[192:195], v[112:115]
	v_mfma_f32_16x16x32_bf16 v[100:103], v[148:151], v[200:203], v[100:103]
	v_mfma_f32_16x16x32_bf16 v[96:99], v[156:159], v[200:203], v[96:99]
	v_mfma_f32_16x16x32_bf16 v[84:87], v[148:151], v[208:211], v[84:87]
	v_mfma_f32_16x16x32_bf16 v[80:83], v[156:159], v[208:211], v[80:83]
	v_mfma_f32_16x16x32_bf16 v[68:71], v[148:151], v[216:219], v[68:71]
	v_mfma_f32_16x16x32_bf16 v[64:67], v[156:159], v[216:219], v[64:67]
	s_barrier
	s_add_i32 s0, s62, s38
	v_lshl_add_u64 v[220:221], v[220:221], 0, s[10:11]
	s_mov_b32 m0, s0
	ds_read_b128 v[178:181], v190 offset:49152
	ds_read_b128 v[192:195], v190 offset:50176
	ds_read_b128 v[196:199], v190 offset:51200
	ds_read_b128 v[200:203], v190 offset:52224
	ds_read_b128 v[204:207], v190 offset:53248
	ds_read_b128 v[208:211], v190 offset:54272
	ds_read_b128 v[212:215], v190 offset:55296
	ds_read_b128 v[216:219], v190 offset:56320
	global_load_lds_dwordx4 v[220:221], off
	s_add_i32 m0, s0, 0x2000
	s_add_u32 s0, s28, 0x50080
	v_lshl_add_u64 v[220:221], v[222:223], 0, s[10:11]
	s_addc_u32 s1, s29, 0
	s_add_i32 s28, s63, s38
	global_load_lds_dwordx4 v[220:221], off
	v_lshl_add_u64 v[220:221], s[0:1], 0, v[164:165]
	s_mov_b32 m0, s28
	s_nop 0
	global_load_lds_dwordx4 v[220:221], off
	v_lshl_add_u64 v[220:221], s[0:1], 0, v[168:169]
	s_add_i32 m0, s28, 0x2000
	s_nop 0
	global_load_lds_dwordx4 v[220:221], off
	v_lshl_add_u64 v[220:221], v[224:225], 0, s[10:11]
	s_mov_b32 m0, s45
	s_nop 0
	global_load_lds_dwordx4 v[220:221], off
	v_lshl_add_u64 v[220:221], v[226:227], 0, s[10:11]
	s_mov_b32 m0, s46
	s_nop 0
	global_load_lds_dwordx4 v[220:221], off
	s_waitcnt vmcnt(8) lgkmcnt(0)
	s_barrier
	v_mfma_f32_16x16x32_bf16 v[60:63], v[128:131], v[178:181], v[60:63]
	v_mfma_f32_16x16x32_bf16 v[56:59], v[136:139], v[178:181], v[56:59]
	v_mfma_f32_16x16x32_bf16 v[44:47], v[128:131], v[196:199], v[44:47]
	v_mfma_f32_16x16x32_bf16 v[40:43], v[136:139], v[196:199], v[40:43]
	v_mfma_f32_16x16x32_bf16 v[28:31], v[128:131], v[204:207], v[28:31]
	v_mfma_f32_16x16x32_bf16 v[24:27], v[136:139], v[204:207], v[24:27]
	v_mfma_f32_16x16x32_bf16 v[12:15], v[128:131], v[212:215], v[12:15]
	v_mfma_f32_16x16x32_bf16 v[8:11], v[136:139], v[212:215], v[8:11]
	v_mfma_f32_16x16x32_bf16 v[60:63], v[132:135], v[192:195], v[60:63]
	v_mfma_f32_16x16x32_bf16 v[56:59], v[140:143], v[192:195], v[56:59]
	v_mfma_f32_16x16x32_bf16 v[44:47], v[132:135], v[200:203], v[44:47]
	v_mfma_f32_16x16x32_bf16 v[40:43], v[140:143], v[200:203], v[40:43]
	v_mfma_f32_16x16x32_bf16 v[28:31], v[132:135], v[208:211], v[28:31]
	v_mfma_f32_16x16x32_bf16 v[24:27], v[140:143], v[208:211], v[24:27]
	v_mfma_f32_16x16x32_bf16 v[12:15], v[132:135], v[216:219], v[12:15]
	v_mfma_f32_16x16x32_bf16 v[8:11], v[140:143], v[216:219], v[8:11]
	v_mfma_f32_16x16x32_bf16 v[52:55], v[144:147], v[178:181], v[52:55]
	v_mfma_f32_16x16x32_bf16 v[48:51], v[152:155], v[178:181], v[48:51]
	v_mfma_f32_16x16x32_bf16 v[36:39], v[144:147], v[196:199], v[36:39]
	v_mfma_f32_16x16x32_bf16 v[32:35], v[152:155], v[196:199], v[32:35]
	v_mfma_f32_16x16x32_bf16 v[20:23], v[144:147], v[204:207], v[20:23]
	v_mfma_f32_16x16x32_bf16 v[16:19], v[152:155], v[204:207], v[16:19]
	v_mfma_f32_16x16x32_bf16 v[4:7], v[144:147], v[212:215], v[4:7]
	v_mfma_f32_16x16x32_bf16 v[0:3], v[152:155], v[212:215], v[0:3]
	v_mfma_f32_16x16x32_bf16 v[52:55], v[148:151], v[192:195], v[52:55]
	v_mfma_f32_16x16x32_bf16 v[48:51], v[156:159], v[192:195], v[48:51]
	v_mfma_f32_16x16x32_bf16 v[36:39], v[148:151], v[200:203], v[36:39]
	v_mfma_f32_16x16x32_bf16 v[32:35], v[156:159], v[200:203], v[32:35]
	v_mfma_f32_16x16x32_bf16 v[20:23], v[148:151], v[208:211], v[20:23]
	v_mfma_f32_16x16x32_bf16 v[16:19], v[156:159], v[208:211], v[16:19]
	v_mfma_f32_16x16x32_bf16 v[4:7], v[148:151], v[216:219], v[4:7]
	v_mfma_f32_16x16x32_bf16 v[0:3], v[156:159], v[216:219], v[0:3]
	s_barrier
	s_add_i32 s61, s61, 2
	s_add_u32 s59, s59, 0x100
	s_addc_u32 s60, s60, 0
	s_cmp_gt_u32 s61, 17
	s_mov_b64 s[0:1], s[16:17]
	s_cbranch_scc0 .LBB0_551

.LBB0_635:
	s_ashr_i32 s13, s12, 31
	s_lshl_b64 s[14:15], s[12:13], 19
	s_add_u32 s14, s64, s14
	s_addc_u32 s15, s65, s15
	s_and_b64 s[16:17], s[2:3], exec
	s_cselect_b32 s13, s15, s1
	s_cselect_b32 s48, s14, s0
	s_ashr_i32 s11, s10, 31
	s_lshl_b64 s[16:17], s[10:11], 19
	s_add_u32 s16, s36, s16
	s_addc_u32 s17, s37, s17
	s_and_b64 s[34:35], s[2:3], exec
	s_cselect_b32 s11, s17, s31
	s_cselect_b32 s49, s16, s30
	s_add_u32 s0, s0, 0x40080
	s_addc_u32 s1, s1, 0
	s_add_u32 s50, s30, 0x100
	s_addc_u32 s51, s31, 0
	s_mov_b32 s52, -2
	v_lshl_add_u32 v248, s28, 8, v156
	v_ashrrev_i32_e32 v249, 31, v248
	v_lshl_add_u64 v[248:249], v[248:249], 2, s[26:27]
	global_load_dword v240, v[248:249], off
	global_load_dword v241, v[248:249], off offset:64
	global_load_dword v242, v[248:249], off offset:128
	global_load_dword v243, v[248:249], off offset:192
	global_load_dword v244, v[248:249], off offset:512
	global_load_dword v245, v[248:249], off offset:576
	global_load_dword v246, v[248:249], off offset:640
	global_load_dword v247, v[248:249], off offset:704
	ds_read_b128 v[144:147], v159
	ds_read_b128 v[148:151], v159 offset:1024
	ds_read_b128 v[152:155], v159 offset:2048
	ds_read_b128 v[166:169], v159 offset:3072
	ds_read_b128 v[170:173], v162
	ds_read_b128 v[174:177], v162 offset:1024
	ds_read_b128 v[178:181], v162 offset:2048
	ds_read_b128 v[182:185], v162 offset:3072
	s_add_u32 s30, s0, 0xfffc0080
	s_addc_u32 s31, s1, -1
	s_cmp_eq_u32 s52, 12
	s_cselect_b32 s35, s13, s31
	s_cselect_b32 s34, s48, s30
	s_cselect_b32 s31, s11, s51
	s_cselect_b32 s30, s49, s50
	v_lshl_add_u64 v[218:219], s[0:1], 0, v[136:137]
	s_add_i32 m0, s29, 0xc000
	ds_read_b128 v[186:189], v163
	ds_read_b128 v[190:193], v163 offset:1024
	ds_read_b128 v[194:197], v163 offset:2048
	ds_read_b128 v[198:201], v163 offset:3072
	ds_read_b128 v[202:205], v163 offset:4096
	ds_read_b128 v[206:209], v163 offset:5120
	ds_read_b128 v[210:213], v163 offset:6144
	ds_read_b128 v[214:217], v163 offset:7168
	global_load_lds_dwordx4 v[218:219], off
	v_lshl_add_u64 v[218:219], s[0:1], 0, v[138:139]
	s_add_i32 m0, s29, 0xe000
	s_nop 0
	global_load_lds_dwordx4 v[218:219], off
	s_waitcnt vmcnt(8) lgkmcnt(0)
	s_barrier
	v_mfma_f32_16x16x32_bf16 v[124:127], v[144:147], v[186:189], 0
	v_mfma_f32_16x16x32_bf16 v[120:123], v[152:155], v[186:189], 0
	v_mfma_f32_16x16x32_bf16 v[116:119], v[144:147], v[194:197], 0
	v_mfma_f32_16x16x32_bf16 v[104:107], v[152:155], v[194:197], 0
	v_mfma_f32_16x16x32_bf16 v[92:95], v[144:147], v[202:205], 0
	v_mfma_f32_16x16x32_bf16 v[88:91], v[152:155], v[202:205], 0
	v_mfma_f32_16x16x32_bf16 v[76:79], v[144:147], v[210:213], 0
	v_mfma_f32_16x16x32_bf16 v[72:75], v[152:155], v[210:213], 0
	v_mfma_f32_16x16x32_bf16 v[124:127], v[148:151], v[190:193], v[124:127]
	v_mfma_f32_16x16x32_bf16 v[120:123], v[166:169], v[190:193], v[120:123]
	v_mfma_f32_16x16x32_bf16 v[116:119], v[148:151], v[198:201], v[116:119]
	v_mfma_f32_16x16x32_bf16 v[104:107], v[166:169], v[198:201], v[104:107]
	v_mfma_f32_16x16x32_bf16 v[92:95], v[148:151], v[206:209], v[92:95]
	v_mfma_f32_16x16x32_bf16 v[88:91], v[166:169], v[206:209], v[88:91]
	v_mfma_f32_16x16x32_bf16 v[76:79], v[148:151], v[214:217], v[76:79]
	v_mfma_f32_16x16x32_bf16 v[72:75], v[166:169], v[214:217], v[72:75]
	v_mfma_f32_16x16x32_bf16 v[112:115], v[170:173], v[186:189], 0
	v_mfma_f32_16x16x32_bf16 v[108:111], v[178:181], v[186:189], 0
	v_mfma_f32_16x16x32_bf16 v[100:103], v[170:173], v[194:197], 0
	v_mfma_f32_16x16x32_bf16 v[96:99], v[178:181], v[194:197], 0
	v_mfma_f32_16x16x32_bf16 v[84:87], v[170:173], v[202:205], 0
	v_mfma_f32_16x16x32_bf16 v[80:83], v[178:181], v[202:205], 0
	v_mfma_f32_16x16x32_bf16 v[68:71], v[170:173], v[210:213], 0
	v_mfma_f32_16x16x32_bf16 v[64:67], v[178:181], v[210:213], 0
	v_mfma_f32_16x16x32_bf16 v[112:115], v[174:177], v[190:193], v[112:115]
	v_mfma_f32_16x16x32_bf16 v[108:111], v[182:185], v[190:193], v[108:111]
	v_mfma_f32_16x16x32_bf16 v[100:103], v[174:177], v[198:201], v[100:103]
	v_mfma_f32_16x16x32_bf16 v[96:99], v[182:185], v[198:201], v[96:99]
	v_mfma_f32_16x16x32_bf16 v[84:87], v[174:177], v[206:209], v[84:87]
	v_mfma_f32_16x16x32_bf16 v[80:83], v[182:185], v[206:209], v[80:83]
	v_mfma_f32_16x16x32_bf16 v[68:71], v[174:177], v[214:217], v[68:71]
	v_mfma_f32_16x16x32_bf16 v[64:67], v[182:185], v[214:217], v[64:67]
	s_barrier
	s_add_i32 s53, s46, s38
	v_lshl_add_u64 v[218:219], s[30:31], 0, v[132:133]
	s_mov_b32 m0, s53
	ds_read_b128 v[186:189], v163 offset:16384
	ds_read_b128 v[190:193], v163 offset:17408
	ds_read_b128 v[194:197], v163 offset:18432
	ds_read_b128 v[198:201], v163 offset:19456
	ds_read_b128 v[202:205], v163 offset:20480
	ds_read_b128 v[206:209], v163 offset:21504
	ds_read_b128 v[210:213], v163 offset:22528
	ds_read_b128 v[214:217], v163 offset:23552
	global_load_lds_dwordx4 v[218:219], off
	s_add_i32 m0, s53, 0x2000
	s_add_u32 s54, s30, 0x40000
	v_lshl_add_u64 v[220:221], s[30:31], 0, v[128:129]
	s_addc_u32 s55, s31, 0
	s_add_i32 s53, s47, s38
	global_load_lds_dwordx4 v[220:221], off
	v_lshl_add_u64 v[222:223], s[54:55], 0, v[132:133]
	s_mov_b32 m0, s53
	v_lshl_add_u64 v[224:225], s[34:35], 0, v[130:131]
	global_load_lds_dwordx4 v[222:223], off
	v_lshl_add_u64 v[222:223], s[54:55], 0, v[128:129]
	s_add_i32 m0, s53, 0x2000
	s_nop 0
	global_load_lds_dwordx4 v[222:223], off
	v_lshl_add_u64 v[222:223], s[34:35], 0, v[134:135]
	s_mov_b32 m0, s29
	s_nop 0
	global_load_lds_dwordx4 v[222:223], off
	s_mov_b32 m0, s40
	s_nop 0
	global_load_lds_dwordx4 v[224:225], off
	s_waitcnt vmcnt(8) lgkmcnt(0)
	s_barrier
	v_mfma_f32_16x16x32_bf16 v[60:63], v[144:147], v[186:189], 0
	v_mfma_f32_16x16x32_bf16 v[56:59], v[152:155], v[186:189], 0
	v_mfma_f32_16x16x32_bf16 v[44:47], v[144:147], v[194:197], 0
	v_mfma_f32_16x16x32_bf16 v[40:43], v[152:155], v[194:197], 0
	v_mfma_f32_16x16x32_bf16 v[28:31], v[144:147], v[202:205], 0
	v_mfma_f32_16x16x32_bf16 v[24:27], v[152:155], v[202:205], 0
	v_mfma_f32_16x16x32_bf16 v[12:15], v[144:147], v[210:213], 0
	v_mfma_f32_16x16x32_bf16 v[8:11], v[152:155], v[210:213], 0
	v_mfma_f32_16x16x32_bf16 v[60:63], v[148:151], v[190:193], v[60:63]
	v_mfma_f32_16x16x32_bf16 v[56:59], v[166:169], v[190:193], v[56:59]
	v_mfma_f32_16x16x32_bf16 v[44:47], v[148:151], v[198:201], v[44:47]
	v_mfma_f32_16x16x32_bf16 v[40:43], v[166:169], v[198:201], v[40:43]
	v_mfma_f32_16x16x32_bf16 v[28:31], v[148:151], v[206:209], v[28:31]
	v_mfma_f32_16x16x32_bf16 v[24:27], v[166:169], v[206:209], v[24:27]
	v_mfma_f32_16x16x32_bf16 v[12:15], v[148:151], v[214:217], v[12:15]
	v_mfma_f32_16x16x32_bf16 v[8:11], v[166:169], v[214:217], v[8:11]
	v_mfma_f32_16x16x32_bf16 v[52:55], v[170:173], v[186:189], 0
	v_mfma_f32_16x16x32_bf16 v[48:51], v[178:181], v[186:189], 0
	v_mfma_f32_16x16x32_bf16 v[36:39], v[170:173], v[194:197], 0
	v_mfma_f32_16x16x32_bf16 v[32:35], v[178:181], v[194:197], 0
	v_mfma_f32_16x16x32_bf16 v[20:23], v[170:173], v[202:205], 0
	v_mfma_f32_16x16x32_bf16 v[16:19], v[178:181], v[202:205], 0
	v_mfma_f32_16x16x32_bf16 v[4:7], v[170:173], v[210:213], 0
	v_mfma_f32_16x16x32_bf16 v[0:3], v[178:181], v[210:213], 0
	v_mfma_f32_16x16x32_bf16 v[52:55], v[174:177], v[190:193], v[52:55]
	v_mfma_f32_16x16x32_bf16 v[48:51], v[182:185], v[190:193], v[48:51]
	v_mfma_f32_16x16x32_bf16 v[36:39], v[174:177], v[198:201], v[36:39]
	v_mfma_f32_16x16x32_bf16 v[32:35], v[182:185], v[198:201], v[32:35]
	v_mfma_f32_16x16x32_bf16 v[20:23], v[174:177], v[206:209], v[20:23]
	v_mfma_f32_16x16x32_bf16 v[16:19], v[182:185], v[206:209], v[16:19]
	v_mfma_f32_16x16x32_bf16 v[4:7], v[174:177], v[214:217], v[4:7]
	v_mfma_f32_16x16x32_bf16 v[0:3], v[182:185], v[214:217], v[0:3]
	s_barrier
	s_add_i32 s53, 0, 0x18000
	v_add_u32_e32 v165, s53, v157
	s_add_i32 s54, 0, 0x1c000
	ds_read_b128 v[144:147], v165
	ds_read_b128 v[148:151], v165 offset:1024
	ds_read_b128 v[152:155], v165 offset:2048
	ds_read_b128 v[166:169], v165 offset:3072
	v_add_u32_e32 v165, s54, v157
	ds_read_b128 v[170:173], v165
	ds_read_b128 v[174:177], v165 offset:1024
	ds_read_b128 v[178:181], v165 offset:2048
	ds_read_b128 v[182:185], v165 offset:3072
	s_add_u32 s34, s34, 0x40000
	s_addc_u32 s35, s35, 0
	s_mov_b32 m0, s41
	v_lshl_add_u64 v[226:227], s[34:35], 0, v[134:135]
	ds_read_b128 v[186:189], v163 offset:32768
	ds_read_b128 v[190:193], v163 offset:33792
	ds_read_b128 v[194:197], v163 offset:34816
	ds_read_b128 v[198:201], v163 offset:35840
	ds_read_b128 v[202:205], v163 offset:36864
	ds_read_b128 v[206:209], v163 offset:37888
	ds_read_b128 v[210:213], v163 offset:38912
	ds_read_b128 v[214:217], v163 offset:39936
	global_load_lds_dwordx4 v[226:227], off
	v_lshl_add_u64 v[226:227], s[34:35], 0, v[130:131]
	s_mov_b32 m0, s42
	s_nop 0
	global_load_lds_dwordx4 v[226:227], off
	s_waitcnt vmcnt(8) lgkmcnt(0)
	s_barrier
	v_mfma_f32_16x16x32_bf16 v[124:127], v[144:147], v[186:189], v[124:127]
	v_mfma_f32_16x16x32_bf16 v[120:123], v[152:155], v[186:189], v[120:123]
	v_mfma_f32_16x16x32_bf16 v[116:119], v[144:147], v[194:197], v[116:119]
	v_mfma_f32_16x16x32_bf16 v[104:107], v[152:155], v[194:197], v[104:107]
	v_mfma_f32_16x16x32_bf16 v[92:95], v[144:147], v[202:205], v[92:95]
	v_mfma_f32_16x16x32_bf16 v[88:91], v[152:155], v[202:205], v[88:91]
	v_mfma_f32_16x16x32_bf16 v[76:79], v[144:147], v[210:213], v[76:79]
	v_mfma_f32_16x16x32_bf16 v[72:75], v[152:155], v[210:213], v[72:75]
	v_mfma_f32_16x16x32_bf16 v[124:127], v[148:151], v[190:193], v[124:127]
	v_mfma_f32_16x16x32_bf16 v[120:123], v[166:169], v[190:193], v[120:123]
	v_mfma_f32_16x16x32_bf16 v[116:119], v[148:151], v[198:201], v[116:119]
	v_mfma_f32_16x16x32_bf16 v[104:107], v[166:169], v[198:201], v[104:107]
	v_mfma_f32_16x16x32_bf16 v[92:95], v[148:151], v[206:209], v[92:95]
	v_mfma_f32_16x16x32_bf16 v[88:91], v[166:169], v[206:209], v[88:91]
	v_mfma_f32_16x16x32_bf16 v[76:79], v[148:151], v[214:217], v[76:79]
	v_mfma_f32_16x16x32_bf16 v[72:75], v[166:169], v[214:217], v[72:75]
	v_mfma_f32_16x16x32_bf16 v[112:115], v[170:173], v[186:189], v[112:115]
	v_mfma_f32_16x16x32_bf16 v[108:111], v[178:181], v[186:189], v[108:111]
	v_mfma_f32_16x16x32_bf16 v[100:103], v[170:173], v[194:197], v[100:103]
	v_mfma_f32_16x16x32_bf16 v[96:99], v[178:181], v[194:197], v[96:99]
	v_mfma_f32_16x16x32_bf16 v[84:87], v[170:173], v[202:205], v[84:87]
	v_mfma_f32_16x16x32_bf16 v[80:83], v[178:181], v[202:205], v[80:83]
	v_mfma_f32_16x16x32_bf16 v[68:71], v[170:173], v[210:213], v[68:71]
	v_mfma_f32_16x16x32_bf16 v[64:67], v[178:181], v[210:213], v[64:67]
	v_mfma_f32_16x16x32_bf16 v[112:115], v[174:177], v[190:193], v[112:115]
	v_mfma_f32_16x16x32_bf16 v[108:111], v[182:185], v[190:193], v[108:111]
	v_mfma_f32_16x16x32_bf16 v[100:103], v[174:177], v[198:201], v[100:103]
	v_mfma_f32_16x16x32_bf16 v[96:99], v[182:185], v[198:201], v[96:99]
	v_mfma_f32_16x16x32_bf16 v[84:87], v[174:177], v[206:209], v[84:87]
	v_mfma_f32_16x16x32_bf16 v[80:83], v[182:185], v[206:209], v[80:83]
	v_mfma_f32_16x16x32_bf16 v[68:71], v[174:177], v[214:217], v[68:71]
	v_mfma_f32_16x16x32_bf16 v[64:67], v[182:185], v[214:217], v[64:67]
	s_barrier
	s_add_i32 s34, s53, s38
	v_lshl_add_u64 v[218:219], v[218:219], 0, s[6:7]
	s_mov_b32 m0, s34
	ds_read_b128 v[186:189], v163 offset:49152
	ds_read_b128 v[190:193], v163 offset:50176
	ds_read_b128 v[194:197], v163 offset:51200
	ds_read_b128 v[198:201], v163 offset:52224
	ds_read_b128 v[202:205], v163 offset:53248
	ds_read_b128 v[206:209], v163 offset:54272
	ds_read_b128 v[210:213], v163 offset:55296
	ds_read_b128 v[214:217], v163 offset:56320
	global_load_lds_dwordx4 v[218:219], off
	s_add_i32 m0, s34, 0x2000
	s_add_u32 s30, s30, 0x40080
	v_lshl_add_u64 v[218:219], v[220:221], 0, s[6:7]
	s_addc_u32 s31, s31, 0
	s_add_i32 s34, s54, s38
	global_load_lds_dwordx4 v[218:219], off
	v_lshl_add_u64 v[218:219], s[30:31], 0, v[132:133]
	s_mov_b32 m0, s34
	s_nop 0
	global_load_lds_dwordx4 v[218:219], off
	v_lshl_add_u64 v[218:219], s[30:31], 0, v[128:129]
	s_add_i32 m0, s34, 0x2000
	s_nop 0
	global_load_lds_dwordx4 v[218:219], off
	v_lshl_add_u64 v[218:219], v[222:223], 0, s[6:7]
	s_mov_b32 m0, s44
	s_nop 0
	global_load_lds_dwordx4 v[218:219], off
	v_lshl_add_u64 v[218:219], v[224:225], 0, s[6:7]
	s_mov_b32 m0, s45
	s_nop 0
	global_load_lds_dwordx4 v[218:219], off
	s_waitcnt vmcnt(8) lgkmcnt(0)
	s_barrier
	v_mfma_f32_16x16x32_bf16 v[60:63], v[144:147], v[186:189], v[60:63]
	v_mfma_f32_16x16x32_bf16 v[56:59], v[152:155], v[186:189], v[56:59]
	v_mfma_f32_16x16x32_bf16 v[44:47], v[144:147], v[194:197], v[44:47]
	v_mfma_f32_16x16x32_bf16 v[40:43], v[152:155], v[194:197], v[40:43]
	v_mfma_f32_16x16x32_bf16 v[28:31], v[144:147], v[202:205], v[28:31]
	v_mfma_f32_16x16x32_bf16 v[24:27], v[152:155], v[202:205], v[24:27]
	v_mfma_f32_16x16x32_bf16 v[12:15], v[144:147], v[210:213], v[12:15]
	v_mfma_f32_16x16x32_bf16 v[8:11], v[152:155], v[210:213], v[8:11]
	v_mfma_f32_16x16x32_bf16 v[60:63], v[148:151], v[190:193], v[60:63]
	v_mfma_f32_16x16x32_bf16 v[56:59], v[166:169], v[190:193], v[56:59]
	v_mfma_f32_16x16x32_bf16 v[44:47], v[148:151], v[198:201], v[44:47]
	v_mfma_f32_16x16x32_bf16 v[40:43], v[166:169], v[198:201], v[40:43]
	v_mfma_f32_16x16x32_bf16 v[28:31], v[148:151], v[206:209], v[28:31]
	v_mfma_f32_16x16x32_bf16 v[24:27], v[166:169], v[206:209], v[24:27]
	v_mfma_f32_16x16x32_bf16 v[12:15], v[148:151], v[214:217], v[12:15]
	v_mfma_f32_16x16x32_bf16 v[8:11], v[166:169], v[214:217], v[8:11]
	v_mfma_f32_16x16x32_bf16 v[52:55], v[170:173], v[186:189], v[52:55]
	v_mfma_f32_16x16x32_bf16 v[48:51], v[178:181], v[186:189], v[48:51]
	v_mfma_f32_16x16x32_bf16 v[36:39], v[170:173], v[194:197], v[36:39]
	v_mfma_f32_16x16x32_bf16 v[32:35], v[178:181], v[194:197], v[32:35]
	v_mfma_f32_16x16x32_bf16 v[20:23], v[170:173], v[202:205], v[20:23]
	v_mfma_f32_16x16x32_bf16 v[16:19], v[178:181], v[202:205], v[16:19]
	v_mfma_f32_16x16x32_bf16 v[4:7], v[170:173], v[210:213], v[4:7]
	v_mfma_f32_16x16x32_bf16 v[0:3], v[178:181], v[210:213], v[0:3]
	v_mfma_f32_16x16x32_bf16 v[52:55], v[174:177], v[190:193], v[52:55]
	v_mfma_f32_16x16x32_bf16 v[48:51], v[182:185], v[190:193], v[48:51]
	v_mfma_f32_16x16x32_bf16 v[36:39], v[174:177], v[198:201], v[36:39]
	v_mfma_f32_16x16x32_bf16 v[32:35], v[182:185], v[198:201], v[32:35]
	v_mfma_f32_16x16x32_bf16 v[20:23], v[174:177], v[206:209], v[20:23]
	v_mfma_f32_16x16x32_bf16 v[16:19], v[182:185], v[206:209], v[16:19]
	v_mfma_f32_16x16x32_bf16 v[4:7], v[174:177], v[214:217], v[4:7]
	v_mfma_f32_16x16x32_bf16 v[0:3], v[182:185], v[214:217], v[0:3]
	s_barrier
	s_add_i32 s52, s52, 2
	s_add_u32 s0, s0, 0x100
	s_addc_u32 s1, s1, 0
	s_add_u32 s50, s50, 0x100
	s_addc_u32 s51, s51, 0
	s_cmp_gt_u32 s52, 13
	s_cbranch_scc0 .LBB0_636
	s_branch .Lpeel_exit_3
.LBB0_636:
	ds_read_b128 v[144:147], v159
	ds_read_b128 v[148:151], v159 offset:1024
	ds_read_b128 v[152:155], v159 offset:2048
	ds_read_b128 v[166:169], v159 offset:3072
	ds_read_b128 v[170:173], v162
	ds_read_b128 v[174:177], v162 offset:1024
	ds_read_b128 v[178:181], v162 offset:2048
	ds_read_b128 v[182:185], v162 offset:3072
	s_add_u32 s30, s0, 0xfffc0080
	s_addc_u32 s31, s1, -1
	s_cmp_eq_u32 s52, 12
	s_cselect_b32 s35, s13, s31
	s_cselect_b32 s34, s48, s30
	s_cselect_b32 s31, s11, s51
	s_cselect_b32 s30, s49, s50
	v_lshl_add_u64 v[218:219], s[0:1], 0, v[136:137]
	s_add_i32 m0, s29, 0xc000
	ds_read_b128 v[186:189], v163
	ds_read_b128 v[190:193], v163 offset:1024
	ds_read_b128 v[194:197], v163 offset:2048
	ds_read_b128 v[198:201], v163 offset:3072
	ds_read_b128 v[202:205], v163 offset:4096
	ds_read_b128 v[206:209], v163 offset:5120
	ds_read_b128 v[210:213], v163 offset:6144
	ds_read_b128 v[214:217], v163 offset:7168
	global_load_lds_dwordx4 v[218:219], off
	v_lshl_add_u64 v[218:219], s[0:1], 0, v[138:139]
	s_add_i32 m0, s29, 0xe000
	s_nop 0
	global_load_lds_dwordx4 v[218:219], off
	s_waitcnt vmcnt(8) lgkmcnt(0)
	s_barrier
	v_mfma_f32_16x16x32_bf16 v[124:127], v[144:147], v[186:189], v[124:127]
	v_mfma_f32_16x16x32_bf16 v[120:123], v[152:155], v[186:189], v[120:123]
	v_mfma_f32_16x16x32_bf16 v[116:119], v[144:147], v[194:197], v[116:119]
	v_mfma_f32_16x16x32_bf16 v[104:107], v[152:155], v[194:197], v[104:107]
	v_mfma_f32_16x16x32_bf16 v[92:95], v[144:147], v[202:205], v[92:95]
	v_mfma_f32_16x16x32_bf16 v[88:91], v[152:155], v[202:205], v[88:91]
	v_mfma_f32_16x16x32_bf16 v[76:79], v[144:147], v[210:213], v[76:79]
	v_mfma_f32_16x16x32_bf16 v[72:75], v[152:155], v[210:213], v[72:75]
	v_mfma_f32_16x16x32_bf16 v[124:127], v[148:151], v[190:193], v[124:127]
	v_mfma_f32_16x16x32_bf16 v[120:123], v[166:169], v[190:193], v[120:123]
	v_mfma_f32_16x16x32_bf16 v[116:119], v[148:151], v[198:201], v[116:119]
	v_mfma_f32_16x16x32_bf16 v[104:107], v[166:169], v[198:201], v[104:107]
	v_mfma_f32_16x16x32_bf16 v[92:95], v[148:151], v[206:209], v[92:95]
	v_mfma_f32_16x16x32_bf16 v[88:91], v[166:169], v[206:209], v[88:91]
	v_mfma_f32_16x16x32_bf16 v[76:79], v[148:151], v[214:217], v[76:79]
	v_mfma_f32_16x16x32_bf16 v[72:75], v[166:169], v[214:217], v[72:75]
	v_mfma_f32_16x16x32_bf16 v[112:115], v[170:173], v[186:189], v[112:115]
	v_mfma_f32_16x16x32_bf16 v[108:111], v[178:181], v[186:189], v[108:111]
	v_mfma_f32_16x16x32_bf16 v[100:103], v[170:173], v[194:197], v[100:103]
	v_mfma_f32_16x16x32_bf16 v[96:99], v[178:181], v[194:197], v[96:99]
	v_mfma_f32_16x16x32_bf16 v[84:87], v[170:173], v[202:205], v[84:87]
	v_mfma_f32_16x16x32_bf16 v[80:83], v[178:181], v[202:205], v[80:83]
	v_mfma_f32_16x16x32_bf16 v[68:71], v[170:173], v[210:213], v[68:71]
	v_mfma_f32_16x16x32_bf16 v[64:67], v[178:181], v[210:213], v[64:67]
	v_mfma_f32_16x16x32_bf16 v[112:115], v[174:177], v[190:193], v[112:115]
	v_mfma_f32_16x16x32_bf16 v[108:111], v[182:185], v[190:193], v[108:111]
	v_mfma_f32_16x16x32_bf16 v[100:103], v[174:177], v[198:201], v[100:103]
	v_mfma_f32_16x16x32_bf16 v[96:99], v[182:185], v[198:201], v[96:99]
	v_mfma_f32_16x16x32_bf16 v[84:87], v[174:177], v[206:209], v[84:87]
	v_mfma_f32_16x16x32_bf16 v[80:83], v[182:185], v[206:209], v[80:83]
	v_mfma_f32_16x16x32_bf16 v[68:71], v[174:177], v[214:217], v[68:71]
	v_mfma_f32_16x16x32_bf16 v[64:67], v[182:185], v[214:217], v[64:67]
	s_barrier
	s_add_i32 s53, s46, s38
	v_lshl_add_u64 v[218:219], s[30:31], 0, v[132:133]
	s_mov_b32 m0, s53
	ds_read_b128 v[186:189], v163 offset:16384
	ds_read_b128 v[190:193], v163 offset:17408
	ds_read_b128 v[194:197], v163 offset:18432
	ds_read_b128 v[198:201], v163 offset:19456
	ds_read_b128 v[202:205], v163 offset:20480
	ds_read_b128 v[206:209], v163 offset:21504
	ds_read_b128 v[210:213], v163 offset:22528
	ds_read_b128 v[214:217], v163 offset:23552
	global_load_lds_dwordx4 v[218:219], off
	s_add_i32 m0, s53, 0x2000
	s_add_u32 s54, s30, 0x40000
	v_lshl_add_u64 v[220:221], s[30:31], 0, v[128:129]
	s_addc_u32 s55, s31, 0
	s_add_i32 s53, s47, s38
	global_load_lds_dwordx4 v[220:221], off
	v_lshl_add_u64 v[222:223], s[54:55], 0, v[132:133]
	s_mov_b32 m0, s53
	v_lshl_add_u64 v[224:225], s[34:35], 0, v[130:131]
	global_load_lds_dwordx4 v[222:223], off
	v_lshl_add_u64 v[222:223], s[54:55], 0, v[128:129]
	s_add_i32 m0, s53, 0x2000
	s_nop 0
	global_load_lds_dwordx4 v[222:223], off
	v_lshl_add_u64 v[222:223], s[34:35], 0, v[134:135]
	s_mov_b32 m0, s29
	s_nop 0
	global_load_lds_dwordx4 v[222:223], off
	s_mov_b32 m0, s40
	s_nop 0
	global_load_lds_dwordx4 v[224:225], off
	s_waitcnt vmcnt(8) lgkmcnt(0)
	s_barrier
	v_mfma_f32_16x16x32_bf16 v[60:63], v[144:147], v[186:189], v[60:63]
	v_mfma_f32_16x16x32_bf16 v[56:59], v[152:155], v[186:189], v[56:59]
	v_mfma_f32_16x16x32_bf16 v[44:47], v[144:147], v[194:197], v[44:47]
	v_mfma_f32_16x16x32_bf16 v[40:43], v[152:155], v[194:197], v[40:43]
	v_mfma_f32_16x16x32_bf16 v[28:31], v[144:147], v[202:205], v[28:31]
	v_mfma_f32_16x16x32_bf16 v[24:27], v[152:155], v[202:205], v[24:27]
	v_mfma_f32_16x16x32_bf16 v[12:15], v[144:147], v[210:213], v[12:15]
	v_mfma_f32_16x16x32_bf16 v[8:11], v[152:155], v[210:213], v[8:11]
	v_mfma_f32_16x16x32_bf16 v[60:63], v[148:151], v[190:193], v[60:63]
	v_mfma_f32_16x16x32_bf16 v[56:59], v[166:169], v[190:193], v[56:59]
	v_mfma_f32_16x16x32_bf16 v[44:47], v[148:151], v[198:201], v[44:47]
	v_mfma_f32_16x16x32_bf16 v[40:43], v[166:169], v[198:201], v[40:43]
	v_mfma_f32_16x16x32_bf16 v[28:31], v[148:151], v[206:209], v[28:31]
	v_mfma_f32_16x16x32_bf16 v[24:27], v[166:169], v[206:209], v[24:27]
	v_mfma_f32_16x16x32_bf16 v[12:15], v[148:151], v[214:217], v[12:15]
	v_mfma_f32_16x16x32_bf16 v[8:11], v[166:169], v[214:217], v[8:11]
	v_mfma_f32_16x16x32_bf16 v[52:55], v[170:173], v[186:189], v[52:55]
	v_mfma_f32_16x16x32_bf16 v[48:51], v[178:181], v[186:189], v[48:51]
	v_mfma_f32_16x16x32_bf16 v[36:39], v[170:173], v[194:197], v[36:39]
	v_mfma_f32_16x16x32_bf16 v[32:35], v[178:181], v[194:197], v[32:35]
	v_mfma_f32_16x16x32_bf16 v[20:23], v[170:173], v[202:205], v[20:23]
	v_mfma_f32_16x16x32_bf16 v[16:19], v[178:181], v[202:205], v[16:19]
	v_mfma_f32_16x16x32_bf16 v[4:7], v[170:173], v[210:213], v[4:7]
	v_mfma_f32_16x16x32_bf16 v[0:3], v[178:181], v[210:213], v[0:3]
	v_mfma_f32_16x16x32_bf16 v[52:55], v[174:177], v[190:193], v[52:55]
	v_mfma_f32_16x16x32_bf16 v[48:51], v[182:185], v[190:193], v[48:51]
	v_mfma_f32_16x16x32_bf16 v[36:39], v[174:177], v[198:201], v[36:39]
	v_mfma_f32_16x16x32_bf16 v[32:35], v[182:185], v[198:201], v[32:35]
	v_mfma_f32_16x16x32_bf16 v[20:23], v[174:177], v[206:209], v[20:23]
	v_mfma_f32_16x16x32_bf16 v[16:19], v[182:185], v[206:209], v[16:19]
	v_mfma_f32_16x16x32_bf16 v[4:7], v[174:177], v[214:217], v[4:7]
	v_mfma_f32_16x16x32_bf16 v[0:3], v[182:185], v[214:217], v[0:3]
	s_barrier
	s_add_i32 s53, 0, 0x18000
	v_add_u32_e32 v165, s53, v157
	s_add_i32 s54, 0, 0x1c000
	ds_read_b128 v[144:147], v165
	ds_read_b128 v[148:151], v165 offset:1024
	ds_read_b128 v[152:155], v165 offset:2048
	ds_read_b128 v[166:169], v165 offset:3072
	v_add_u32_e32 v165, s54, v157
	ds_read_b128 v[170:173], v165
	ds_read_b128 v[174:177], v165 offset:1024
	ds_read_b128 v[178:181], v165 offset:2048
	ds_read_b128 v[182:185], v165 offset:3072
	s_add_u32 s34, s34, 0x40000
	s_addc_u32 s35, s35, 0
	s_mov_b32 m0, s41
	v_lshl_add_u64 v[226:227], s[34:35], 0, v[134:135]
	ds_read_b128 v[186:189], v163 offset:32768
	ds_read_b128 v[190:193], v163 offset:33792
	ds_read_b128 v[194:197], v163 offset:34816
	ds_read_b128 v[198:201], v163 offset:35840
	ds_read_b128 v[202:205], v163 offset:36864
	ds_read_b128 v[206:209], v163 offset:37888
	ds_read_b128 v[210:213], v163 offset:38912
	ds_read_b128 v[214:217], v163 offset:39936
	global_load_lds_dwordx4 v[226:227], off
	v_lshl_add_u64 v[226:227], s[34:35], 0, v[130:131]
	s_mov_b32 m0, s42
	s_nop 0
	global_load_lds_dwordx4 v[226:227], off
	s_waitcnt vmcnt(8) lgkmcnt(0)
	s_barrier
	v_mfma_f32_16x16x32_bf16 v[124:127], v[144:147], v[186:189], v[124:127]
	v_mfma_f32_16x16x32_bf16 v[120:123], v[152:155], v[186:189], v[120:123]
	v_mfma_f32_16x16x32_bf16 v[116:119], v[144:147], v[194:197], v[116:119]
	v_mfma_f32_16x16x32_bf16 v[104:107], v[152:155], v[194:197], v[104:107]
	v_mfma_f32_16x16x32_bf16 v[92:95], v[144:147], v[202:205], v[92:95]
	v_mfma_f32_16x16x32_bf16 v[88:91], v[152:155], v[202:205], v[88:91]
	v_mfma_f32_16x16x32_bf16 v[76:79], v[144:147], v[210:213], v[76:79]
	v_mfma_f32_16x16x32_bf16 v[72:75], v[152:155], v[210:213], v[72:75]
	v_mfma_f32_16x16x32_bf16 v[124:127], v[148:151], v[190:193], v[124:127]
	v_mfma_f32_16x16x32_bf16 v[120:123], v[166:169], v[190:193], v[120:123]
	v_mfma_f32_16x16x32_bf16 v[116:119], v[148:151], v[198:201], v[116:119]
	v_mfma_f32_16x16x32_bf16 v[104:107], v[166:169], v[198:201], v[104:107]
	v_mfma_f32_16x16x32_bf16 v[92:95], v[148:151], v[206:209], v[92:95]
	v_mfma_f32_16x16x32_bf16 v[88:91], v[166:169], v[206:209], v[88:91]
	v_mfma_f32_16x16x32_bf16 v[76:79], v[148:151], v[214:217], v[76:79]
	v_mfma_f32_16x16x32_bf16 v[72:75], v[166:169], v[214:217], v[72:75]
	v_mfma_f32_16x16x32_bf16 v[112:115], v[170:173], v[186:189], v[112:115]
	v_mfma_f32_16x16x32_bf16 v[108:111], v[178:181], v[186:189], v[108:111]
	v_mfma_f32_16x16x32_bf16 v[100:103], v[170:173], v[194:197], v[100:103]
	v_mfma_f32_16x16x32_bf16 v[96:99], v[178:181], v[194:197], v[96:99]
	v_mfma_f32_16x16x32_bf16 v[84:87], v[170:173], v[202:205], v[84:87]
	v_mfma_f32_16x16x32_bf16 v[80:83], v[178:181], v[202:205], v[80:83]
	v_mfma_f32_16x16x32_bf16 v[68:71], v[170:173], v[210:213], v[68:71]
	v_mfma_f32_16x16x32_bf16 v[64:67], v[178:181], v[210:213], v[64:67]
	v_mfma_f32_16x16x32_bf16 v[112:115], v[174:177], v[190:193], v[112:115]
	v_mfma_f32_16x16x32_bf16 v[108:111], v[182:185], v[190:193], v[108:111]
	v_mfma_f32_16x16x32_bf16 v[100:103], v[174:177], v[198:201], v[100:103]
	v_mfma_f32_16x16x32_bf16 v[96:99], v[182:185], v[198:201], v[96:99]
	v_mfma_f32_16x16x32_bf16 v[84:87], v[174:177], v[206:209], v[84:87]
	v_mfma_f32_16x16x32_bf16 v[80:83], v[182:185], v[206:209], v[80:83]
	v_mfma_f32_16x16x32_bf16 v[68:71], v[174:177], v[214:217], v[68:71]
	v_mfma_f32_16x16x32_bf16 v[64:67], v[182:185], v[214:217], v[64:67]
	s_barrier
	s_add_i32 s34, s53, s38
	v_lshl_add_u64 v[218:219], v[218:219], 0, s[6:7]
	s_mov_b32 m0, s34
	ds_read_b128 v[186:189], v163 offset:49152
	ds_read_b128 v[190:193], v163 offset:50176
	ds_read_b128 v[194:197], v163 offset:51200
	ds_read_b128 v[198:201], v163 offset:52224
	ds_read_b128 v[202:205], v163 offset:53248
	ds_read_b128 v[206:209], v163 offset:54272
	ds_read_b128 v[210:213], v163 offset:55296
	ds_read_b128 v[214:217], v163 offset:56320
	global_load_lds_dwordx4 v[218:219], off
	s_add_i32 m0, s34, 0x2000
	s_add_u32 s30, s30, 0x40080
	v_lshl_add_u64 v[218:219], v[220:221], 0, s[6:7]
	s_addc_u32 s31, s31, 0
	s_add_i32 s34, s54, s38
	global_load_lds_dwordx4 v[218:219], off
	v_lshl_add_u64 v[218:219], s[30:31], 0, v[132:133]
	s_mov_b32 m0, s34
	s_nop 0
	global_load_lds_dwordx4 v[218:219], off
	v_lshl_add_u64 v[218:219], s[30:31], 0, v[128:129]
	s_add_i32 m0, s34, 0x2000
	s_nop 0
	global_load_lds_dwordx4 v[218:219], off
	v_lshl_add_u64 v[218:219], v[222:223], 0, s[6:7]
	s_mov_b32 m0, s44
	s_nop 0
	global_load_lds_dwordx4 v[218:219], off
	v_lshl_add_u64 v[218:219], v[224:225], 0, s[6:7]
	s_mov_b32 m0, s45
	s_nop 0
	global_load_lds_dwordx4 v[218:219], off
	s_waitcnt vmcnt(8) lgkmcnt(0)
	s_barrier
	v_mfma_f32_16x16x32_bf16 v[60:63], v[144:147], v[186:189], v[60:63]
	v_mfma_f32_16x16x32_bf16 v[56:59], v[152:155], v[186:189], v[56:59]
	v_mfma_f32_16x16x32_bf16 v[44:47], v[144:147], v[194:197], v[44:47]
	v_mfma_f32_16x16x32_bf16 v[40:43], v[152:155], v[194:197], v[40:43]
	v_mfma_f32_16x16x32_bf16 v[28:31], v[144:147], v[202:205], v[28:31]
	v_mfma_f32_16x16x32_bf16 v[24:27], v[152:155], v[202:205], v[24:27]
	v_mfma_f32_16x16x32_bf16 v[12:15], v[144:147], v[210:213], v[12:15]
	v_mfma_f32_16x16x32_bf16 v[8:11], v[152:155], v[210:213], v[8:11]
	v_mfma_f32_16x16x32_bf16 v[60:63], v[148:151], v[190:193], v[60:63]
	v_mfma_f32_16x16x32_bf16 v[56:59], v[166:169], v[190:193], v[56:59]
	v_mfma_f32_16x16x32_bf16 v[44:47], v[148:151], v[198:201], v[44:47]
	v_mfma_f32_16x16x32_bf16 v[40:43], v[166:169], v[198:201], v[40:43]
	v_mfma_f32_16x16x32_bf16 v[28:31], v[148:151], v[206:209], v[28:31]
	v_mfma_f32_16x16x32_bf16 v[24:27], v[166:169], v[206:209], v[24:27]
	v_mfma_f32_16x16x32_bf16 v[12:15], v[148:151], v[214:217], v[12:15]
	v_mfma_f32_16x16x32_bf16 v[8:11], v[166:169], v[214:217], v[8:11]
	v_mfma_f32_16x16x32_bf16 v[52:55], v[170:173], v[186:189], v[52:55]
	v_mfma_f32_16x16x32_bf16 v[48:51], v[178:181], v[186:189], v[48:51]
	v_mfma_f32_16x16x32_bf16 v[36:39], v[170:173], v[194:197], v[36:39]
	v_mfma_f32_16x16x32_bf16 v[32:35], v[178:181], v[194:197], v[32:35]
	v_mfma_f32_16x16x32_bf16 v[20:23], v[170:173], v[202:205], v[20:23]
	v_mfma_f32_16x16x32_bf16 v[16:19], v[178:181], v[202:205], v[16:19]
	v_mfma_f32_16x16x32_bf16 v[4:7], v[170:173], v[210:213], v[4:7]
	v_mfma_f32_16x16x32_bf16 v[0:3], v[178:181], v[210:213], v[0:3]
	v_mfma_f32_16x16x32_bf16 v[52:55], v[174:177], v[190:193], v[52:55]
	v_mfma_f32_16x16x32_bf16 v[48:51], v[182:185], v[190:193], v[48:51]
	v_mfma_f32_16x16x32_bf16 v[36:39], v[174:177], v[198:201], v[36:39]
	v_mfma_f32_16x16x32_bf16 v[32:35], v[182:185], v[198:201], v[32:35]
	v_mfma_f32_16x16x32_bf16 v[20:23], v[174:177], v[206:209], v[20:23]
	v_mfma_f32_16x16x32_bf16 v[16:19], v[182:185], v[206:209], v[16:19]
	v_mfma_f32_16x16x32_bf16 v[4:7], v[174:177], v[214:217], v[4:7]
	v_mfma_f32_16x16x32_bf16 v[0:3], v[182:185], v[214:217], v[0:3]
	s_barrier
	s_add_i32 s52, s52, 2
	s_add_u32 s0, s0, 0x100
	s_addc_u32 s1, s1, 0
	s_add_u32 s50, s50, 0x100
	s_addc_u32 s51, s51, 0
	s_cmp_gt_u32 s52, 13
	s_cbranch_scc0 .LBB0_636

.LBB0_710:
	s_ashr_i32 s17, s16, 31
	s_lshl_b64 s[26:27], s[16:17], 21
	s_add_u32 s26, s92, s26
	s_addc_u32 s27, s93, s27
	s_and_b64 s[28:29], s[6:7], exec
	s_cselect_b32 s17, s27, s1
	s_cselect_b32 s33, s26, s0
	s_ashr_i32 s15, s14, 31
	s_lshl_b64 s[28:29], s[14:15], 21
	s_add_u32 s28, s56, s28
	s_addc_u32 s29, s57, s29
	s_and_b64 s[38:39], s[6:7], exec
	s_cselect_b32 s15, s29, s37
	s_cselect_b32 s55, s28, s36
	s_add_u32 s0, s0, 0x100080
	s_addc_u32 s1, s1, 0
	s_add_u32 s58, s36, 0x100
	s_addc_u32 s59, s37, 0
	s_mov_b32 s60, -2
	s_waitcnt lgkmcnt(0)
	ds_read_b128 v[128:131], v188
	ds_read_b128 v[132:135], v188 offset:1024
	ds_read_b128 v[136:139], v188 offset:2048
	ds_read_b128 v[140:143], v188 offset:3072
	ds_read_b128 v[144:147], v189
	ds_read_b128 v[148:151], v189 offset:1024
	ds_read_b128 v[152:155], v189 offset:2048
	ds_read_b128 v[156:159], v189 offset:3072
	s_add_u32 s36, s0, 0xfff00080
	s_addc_u32 s37, s1, -1
	s_cmp_eq_u32 s60, 60
	s_cselect_b32 s39, s17, s37
	s_cselect_b32 s38, s33, s36
	s_cselect_b32 s37, s15, s59
	s_cselect_b32 s36, s55, s58
	v_lshl_add_u64 v[220:221], s[0:1], 0, v[170:171]
	s_add_i32 m0, s31, 0xc000
	ds_read_b128 v[178:181], v190
	ds_read_b128 v[192:195], v190 offset:1024
	ds_read_b128 v[196:199], v190 offset:2048
	ds_read_b128 v[200:203], v190 offset:3072
	ds_read_b128 v[204:207], v190 offset:4096
	ds_read_b128 v[208:211], v190 offset:5120
	ds_read_b128 v[212:215], v190 offset:6144
	ds_read_b128 v[216:219], v190 offset:7168
	global_load_lds_dwordx4 v[220:221], off
	v_lshl_add_u64 v[220:221], s[0:1], 0, v[172:173]
	s_add_i32 m0, s31, 0xe000
	s_nop 0
	global_load_lds_dwordx4 v[220:221], off
	s_waitcnt vmcnt(8) lgkmcnt(0)
	s_barrier
	v_mfma_f32_16x16x32_bf16 v[124:127], v[128:131], v[178:181], 0
	v_mfma_f32_16x16x32_bf16 v[120:123], v[136:139], v[178:181], 0
	v_mfma_f32_16x16x32_bf16 v[108:111], v[128:131], v[196:199], 0
	v_mfma_f32_16x16x32_bf16 v[104:107], v[136:139], v[196:199], 0
	v_mfma_f32_16x16x32_bf16 v[92:95], v[128:131], v[204:207], 0
	v_mfma_f32_16x16x32_bf16 v[88:91], v[136:139], v[204:207], 0
	v_mfma_f32_16x16x32_bf16 v[76:79], v[128:131], v[212:215], 0
	v_mfma_f32_16x16x32_bf16 v[72:75], v[136:139], v[212:215], 0
	v_mfma_f32_16x16x32_bf16 v[124:127], v[132:135], v[192:195], v[124:127]
	v_mfma_f32_16x16x32_bf16 v[120:123], v[140:143], v[192:195], v[120:123]
	v_mfma_f32_16x16x32_bf16 v[108:111], v[132:135], v[200:203], v[108:111]
	v_mfma_f32_16x16x32_bf16 v[104:107], v[140:143], v[200:203], v[104:107]
	v_mfma_f32_16x16x32_bf16 v[92:95], v[132:135], v[208:211], v[92:95]
	v_mfma_f32_16x16x32_bf16 v[88:91], v[140:143], v[208:211], v[88:91]
	v_mfma_f32_16x16x32_bf16 v[76:79], v[132:135], v[216:219], v[76:79]
	v_mfma_f32_16x16x32_bf16 v[72:75], v[140:143], v[216:219], v[72:75]
	v_mfma_f32_16x16x32_bf16 v[116:119], v[144:147], v[178:181], 0
	v_mfma_f32_16x16x32_bf16 v[112:115], v[152:155], v[178:181], 0
	v_mfma_f32_16x16x32_bf16 v[100:103], v[144:147], v[196:199], 0
	v_mfma_f32_16x16x32_bf16 v[96:99], v[152:155], v[196:199], 0
	v_mfma_f32_16x16x32_bf16 v[84:87], v[144:147], v[204:207], 0
	v_mfma_f32_16x16x32_bf16 v[80:83], v[152:155], v[204:207], 0
	v_mfma_f32_16x16x32_bf16 v[68:71], v[144:147], v[212:215], 0
	v_mfma_f32_16x16x32_bf16 v[64:67], v[152:155], v[212:215], 0
	v_mfma_f32_16x16x32_bf16 v[116:119], v[148:151], v[192:195], v[116:119]
	v_mfma_f32_16x16x32_bf16 v[112:115], v[156:159], v[192:195], v[112:115]
	v_mfma_f32_16x16x32_bf16 v[100:103], v[148:151], v[200:203], v[100:103]
	v_mfma_f32_16x16x32_bf16 v[96:99], v[156:159], v[200:203], v[96:99]
	v_mfma_f32_16x16x32_bf16 v[84:87], v[148:151], v[208:211], v[84:87]
	v_mfma_f32_16x16x32_bf16 v[80:83], v[156:159], v[208:211], v[80:83]
	v_mfma_f32_16x16x32_bf16 v[68:71], v[148:151], v[216:219], v[68:71]
	v_mfma_f32_16x16x32_bf16 v[64:67], v[156:159], v[216:219], v[64:67]
	s_barrier
	s_add_i32 s61, s49, s40
	v_lshl_add_u64 v[220:221], s[36:37], 0, v[164:165]
	s_mov_b32 m0, s61
	ds_read_b128 v[178:181], v190 offset:16384
	ds_read_b128 v[192:195], v190 offset:17408
	ds_read_b128 v[196:199], v190 offset:18432
	ds_read_b128 v[200:203], v190 offset:19456
	ds_read_b128 v[204:207], v190 offset:20480
	ds_read_b128 v[208:211], v190 offset:21504
	ds_read_b128 v[212:215], v190 offset:22528
	ds_read_b128 v[216:219], v190 offset:23552
	global_load_lds_dwordx4 v[220:221], off
	s_add_i32 m0, s61, 0x2000
	s_add_u32 s62, s36, 0x100000
	v_lshl_add_u64 v[222:223], s[36:37], 0, v[168:169]
	s_addc_u32 s63, s37, 0
	s_add_i32 s61, s50, s40
	global_load_lds_dwordx4 v[222:223], off
	v_lshl_add_u64 v[224:225], s[62:63], 0, v[164:165]
	s_mov_b32 m0, s61
	v_lshl_add_u64 v[226:227], s[38:39], 0, v[166:167]
	global_load_lds_dwordx4 v[224:225], off
	v_lshl_add_u64 v[224:225], s[62:63], 0, v[168:169]
	s_add_i32 m0, s61, 0x2000
	s_nop 0
	global_load_lds_dwordx4 v[224:225], off
	v_lshl_add_u64 v[224:225], s[38:39], 0, v[162:163]
	s_mov_b32 m0, s31
	s_nop 0
	global_load_lds_dwordx4 v[224:225], off
	s_mov_b32 m0, s35
	s_nop 0
	global_load_lds_dwordx4 v[226:227], off
	s_waitcnt vmcnt(8) lgkmcnt(0)
	s_barrier
	v_mfma_f32_16x16x32_bf16 v[60:63], v[128:131], v[178:181], 0
	v_mfma_f32_16x16x32_bf16 v[56:59], v[136:139], v[178:181], 0
	v_mfma_f32_16x16x32_bf16 v[44:47], v[128:131], v[196:199], 0
	v_mfma_f32_16x16x32_bf16 v[40:43], v[136:139], v[196:199], 0
	v_mfma_f32_16x16x32_bf16 v[28:31], v[128:131], v[204:207], 0
	v_mfma_f32_16x16x32_bf16 v[24:27], v[136:139], v[204:207], 0
	v_mfma_f32_16x16x32_bf16 v[12:15], v[128:131], v[212:215], 0
	v_mfma_f32_16x16x32_bf16 v[8:11], v[136:139], v[212:215], 0
	v_mfma_f32_16x16x32_bf16 v[60:63], v[132:135], v[192:195], v[60:63]
	v_mfma_f32_16x16x32_bf16 v[56:59], v[140:143], v[192:195], v[56:59]
	v_mfma_f32_16x16x32_bf16 v[44:47], v[132:135], v[200:203], v[44:47]
	v_mfma_f32_16x16x32_bf16 v[40:43], v[140:143], v[200:203], v[40:43]
	v_mfma_f32_16x16x32_bf16 v[28:31], v[132:135], v[208:211], v[28:31]
	v_mfma_f32_16x16x32_bf16 v[24:27], v[140:143], v[208:211], v[24:27]
	v_mfma_f32_16x16x32_bf16 v[12:15], v[132:135], v[216:219], v[12:15]
	v_mfma_f32_16x16x32_bf16 v[8:11], v[140:143], v[216:219], v[8:11]
	v_mfma_f32_16x16x32_bf16 v[52:55], v[144:147], v[178:181], 0
	v_mfma_f32_16x16x32_bf16 v[48:51], v[152:155], v[178:181], 0
	v_mfma_f32_16x16x32_bf16 v[36:39], v[144:147], v[196:199], 0
	v_mfma_f32_16x16x32_bf16 v[32:35], v[152:155], v[196:199], 0
	v_mfma_f32_16x16x32_bf16 v[20:23], v[144:147], v[204:207], 0
	v_mfma_f32_16x16x32_bf16 v[16:19], v[152:155], v[204:207], 0
	v_mfma_f32_16x16x32_bf16 v[4:7], v[144:147], v[212:215], 0
	v_mfma_f32_16x16x32_bf16 v[0:3], v[152:155], v[212:215], 0
	v_mfma_f32_16x16x32_bf16 v[52:55], v[148:151], v[192:195], v[52:55]
	v_mfma_f32_16x16x32_bf16 v[48:51], v[156:159], v[192:195], v[48:51]
	v_mfma_f32_16x16x32_bf16 v[36:39], v[148:151], v[200:203], v[36:39]
	v_mfma_f32_16x16x32_bf16 v[32:35], v[156:159], v[200:203], v[32:35]
	v_mfma_f32_16x16x32_bf16 v[20:23], v[148:151], v[208:211], v[20:23]
	v_mfma_f32_16x16x32_bf16 v[16:19], v[156:159], v[208:211], v[16:19]
	v_mfma_f32_16x16x32_bf16 v[4:7], v[148:151], v[216:219], v[4:7]
	v_mfma_f32_16x16x32_bf16 v[0:3], v[156:159], v[216:219], v[0:3]
	s_barrier
	s_add_i32 s61, 0, 0x18000
	s_add_i32 s62, 0, 0x1c000
	v_add_u32_e32 v140, s61, v183
	v_add_u32_e32 v156, s62, v183
	ds_read_b128 v[128:131], v140
	ds_read_b128 v[132:135], v140 offset:1024
	ds_read_b128 v[136:139], v140 offset:2048
	ds_read_b128 v[140:143], v140 offset:3072
	ds_read_b128 v[144:147], v156
	ds_read_b128 v[148:151], v156 offset:1024
	ds_read_b128 v[152:155], v156 offset:2048
	ds_read_b128 v[156:159], v156 offset:3072
	s_add_u32 s38, s38, 0x100000
	s_addc_u32 s39, s39, 0
	s_mov_b32 m0, s41
	v_lshl_add_u64 v[228:229], s[38:39], 0, v[162:163]
	ds_read_b128 v[178:181], v190 offset:32768
	ds_read_b128 v[192:195], v190 offset:33792
	ds_read_b128 v[196:199], v190 offset:34816
	ds_read_b128 v[200:203], v190 offset:35840
	ds_read_b128 v[204:207], v190 offset:36864
	ds_read_b128 v[208:211], v190 offset:37888
	ds_read_b128 v[212:215], v190 offset:38912
	ds_read_b128 v[216:219], v190 offset:39936
	global_load_lds_dwordx4 v[228:229], off
	v_lshl_add_u64 v[228:229], s[38:39], 0, v[166:167]
	s_mov_b32 m0, s42
	s_nop 0
	global_load_lds_dwordx4 v[228:229], off
	s_waitcnt vmcnt(8) lgkmcnt(0)
	s_barrier
	v_mfma_f32_16x16x32_bf16 v[124:127], v[128:131], v[178:181], v[124:127]
	v_mfma_f32_16x16x32_bf16 v[120:123], v[136:139], v[178:181], v[120:123]
	v_mfma_f32_16x16x32_bf16 v[108:111], v[128:131], v[196:199], v[108:111]
	v_mfma_f32_16x16x32_bf16 v[104:107], v[136:139], v[196:199], v[104:107]
	v_mfma_f32_16x16x32_bf16 v[92:95], v[128:131], v[204:207], v[92:95]
	v_mfma_f32_16x16x32_bf16 v[88:91], v[136:139], v[204:207], v[88:91]
	v_mfma_f32_16x16x32_bf16 v[76:79], v[128:131], v[212:215], v[76:79]
	v_mfma_f32_16x16x32_bf16 v[72:75], v[136:139], v[212:215], v[72:75]
	v_mfma_f32_16x16x32_bf16 v[124:127], v[132:135], v[192:195], v[124:127]
	v_mfma_f32_16x16x32_bf16 v[120:123], v[140:143], v[192:195], v[120:123]
	v_mfma_f32_16x16x32_bf16 v[108:111], v[132:135], v[200:203], v[108:111]
	v_mfma_f32_16x16x32_bf16 v[104:107], v[140:143], v[200:203], v[104:107]
	v_mfma_f32_16x16x32_bf16 v[92:95], v[132:135], v[208:211], v[92:95]
	v_mfma_f32_16x16x32_bf16 v[88:91], v[140:143], v[208:211], v[88:91]
	v_mfma_f32_16x16x32_bf16 v[76:79], v[132:135], v[216:219], v[76:79]
	v_mfma_f32_16x16x32_bf16 v[72:75], v[140:143], v[216:219], v[72:75]
	v_mfma_f32_16x16x32_bf16 v[116:119], v[144:147], v[178:181], v[116:119]
	v_mfma_f32_16x16x32_bf16 v[112:115], v[152:155], v[178:181], v[112:115]
	v_mfma_f32_16x16x32_bf16 v[100:103], v[144:147], v[196:199], v[100:103]
	v_mfma_f32_16x16x32_bf16 v[96:99], v[152:155], v[196:199], v[96:99]
	v_mfma_f32_16x16x32_bf16 v[84:87], v[144:147], v[204:207], v[84:87]
	v_mfma_f32_16x16x32_bf16 v[80:83], v[152:155], v[204:207], v[80:83]
	v_mfma_f32_16x16x32_bf16 v[68:71], v[144:147], v[212:215], v[68:71]
	v_mfma_f32_16x16x32_bf16 v[64:67], v[152:155], v[212:215], v[64:67]
	v_mfma_f32_16x16x32_bf16 v[116:119], v[148:151], v[192:195], v[116:119]
	v_mfma_f32_16x16x32_bf16 v[112:115], v[156:159], v[192:195], v[112:115]
	v_mfma_f32_16x16x32_bf16 v[100:103], v[148:151], v[200:203], v[100:103]
	v_mfma_f32_16x16x32_bf16 v[96:99], v[156:159], v[200:203], v[96:99]
	v_mfma_f32_16x16x32_bf16 v[84:87], v[148:151], v[208:211], v[84:87]
	v_mfma_f32_16x16x32_bf16 v[80:83], v[156:159], v[208:211], v[80:83]
	v_mfma_f32_16x16x32_bf16 v[68:71], v[148:151], v[216:219], v[68:71]
	v_mfma_f32_16x16x32_bf16 v[64:67], v[156:159], v[216:219], v[64:67]
	s_barrier
	s_add_i32 s38, s61, s40
	v_lshl_add_u64 v[220:221], v[220:221], 0, s[8:9]
	s_mov_b32 m0, s38
	ds_read_b128 v[178:181], v190 offset:49152
	ds_read_b128 v[192:195], v190 offset:50176
	ds_read_b128 v[196:199], v190 offset:51200
	ds_read_b128 v[200:203], v190 offset:52224
	ds_read_b128 v[204:207], v190 offset:53248
	ds_read_b128 v[208:211], v190 offset:54272
	ds_read_b128 v[212:215], v190 offset:55296
	ds_read_b128 v[216:219], v190 offset:56320
	global_load_lds_dwordx4 v[220:221], off
	s_add_i32 m0, s38, 0x2000
	s_add_u32 s36, s36, 0x100080
	v_lshl_add_u64 v[220:221], v[222:223], 0, s[8:9]
	s_addc_u32 s37, s37, 0
	s_add_i32 s38, s62, s40
	global_load_lds_dwordx4 v[220:221], off
	v_lshl_add_u64 v[220:221], s[36:37], 0, v[164:165]
	s_mov_b32 m0, s38
	s_nop 0
	global_load_lds_dwordx4 v[220:221], off
	v_lshl_add_u64 v[220:221], s[36:37], 0, v[168:169]
	s_add_i32 m0, s38, 0x2000
	s_nop 0
	global_load_lds_dwordx4 v[220:221], off
	v_lshl_add_u64 v[220:221], v[224:225], 0, s[8:9]
	s_mov_b32 m0, s45
	s_nop 0
	global_load_lds_dwordx4 v[220:221], off
	v_lshl_add_u64 v[220:221], v[226:227], 0, s[8:9]
	s_mov_b32 m0, s46
	s_nop 0
	global_load_lds_dwordx4 v[220:221], off
	s_waitcnt vmcnt(8) lgkmcnt(0)
	s_barrier
	v_mfma_f32_16x16x32_bf16 v[60:63], v[128:131], v[178:181], v[60:63]
	v_mfma_f32_16x16x32_bf16 v[56:59], v[136:139], v[178:181], v[56:59]
	v_mfma_f32_16x16x32_bf16 v[44:47], v[128:131], v[196:199], v[44:47]
	v_mfma_f32_16x16x32_bf16 v[40:43], v[136:139], v[196:199], v[40:43]
	v_mfma_f32_16x16x32_bf16 v[28:31], v[128:131], v[204:207], v[28:31]
	v_mfma_f32_16x16x32_bf16 v[24:27], v[136:139], v[204:207], v[24:27]
	v_mfma_f32_16x16x32_bf16 v[12:15], v[128:131], v[212:215], v[12:15]
	v_mfma_f32_16x16x32_bf16 v[8:11], v[136:139], v[212:215], v[8:11]
	v_mfma_f32_16x16x32_bf16 v[60:63], v[132:135], v[192:195], v[60:63]
	v_mfma_f32_16x16x32_bf16 v[56:59], v[140:143], v[192:195], v[56:59]
	v_mfma_f32_16x16x32_bf16 v[44:47], v[132:135], v[200:203], v[44:47]
	v_mfma_f32_16x16x32_bf16 v[40:43], v[140:143], v[200:203], v[40:43]
	v_mfma_f32_16x16x32_bf16 v[28:31], v[132:135], v[208:211], v[28:31]
	v_mfma_f32_16x16x32_bf16 v[24:27], v[140:143], v[208:211], v[24:27]
	v_mfma_f32_16x16x32_bf16 v[12:15], v[132:135], v[216:219], v[12:15]
	v_mfma_f32_16x16x32_bf16 v[8:11], v[140:143], v[216:219], v[8:11]
	v_mfma_f32_16x16x32_bf16 v[52:55], v[144:147], v[178:181], v[52:55]
	v_mfma_f32_16x16x32_bf16 v[48:51], v[152:155], v[178:181], v[48:51]
	v_mfma_f32_16x16x32_bf16 v[36:39], v[144:147], v[196:199], v[36:39]
	v_mfma_f32_16x16x32_bf16 v[32:35], v[152:155], v[196:199], v[32:35]
	v_mfma_f32_16x16x32_bf16 v[20:23], v[144:147], v[204:207], v[20:23]
	v_mfma_f32_16x16x32_bf16 v[16:19], v[152:155], v[204:207], v[16:19]
	v_mfma_f32_16x16x32_bf16 v[4:7], v[144:147], v[212:215], v[4:7]
	v_mfma_f32_16x16x32_bf16 v[0:3], v[152:155], v[212:215], v[0:3]
	v_mfma_f32_16x16x32_bf16 v[52:55], v[148:151], v[192:195], v[52:55]
	v_mfma_f32_16x16x32_bf16 v[48:51], v[156:159], v[192:195], v[48:51]
	v_mfma_f32_16x16x32_bf16 v[36:39], v[148:151], v[200:203], v[36:39]
	v_mfma_f32_16x16x32_bf16 v[32:35], v[156:159], v[200:203], v[32:35]
	v_mfma_f32_16x16x32_bf16 v[20:23], v[148:151], v[208:211], v[20:23]
	v_mfma_f32_16x16x32_bf16 v[16:19], v[156:159], v[208:211], v[16:19]
	v_mfma_f32_16x16x32_bf16 v[4:7], v[148:151], v[216:219], v[4:7]
	v_mfma_f32_16x16x32_bf16 v[0:3], v[156:159], v[216:219], v[0:3]
	s_barrier
	s_add_i32 s60, s60, 2
	s_add_u32 s0, s0, 0x100
	s_addc_u32 s1, s1, 0
	s_add_u32 s58, s58, 0x100
	s_addc_u32 s59, s59, 0
	s_cmp_gt_u32 s60, 61
	s_cbranch_scc0 .LBB0_711
	s_branch .Lpeel_exit_4
.LBB0_711:
	ds_read_b128 v[128:131], v188
	ds_read_b128 v[132:135], v188 offset:1024
	ds_read_b128 v[136:139], v188 offset:2048
	ds_read_b128 v[140:143], v188 offset:3072
	ds_read_b128 v[144:147], v189
	ds_read_b128 v[148:151], v189 offset:1024
	ds_read_b128 v[152:155], v189 offset:2048
	ds_read_b128 v[156:159], v189 offset:3072
	s_add_u32 s36, s0, 0xfff00080
	s_addc_u32 s37, s1, -1
	s_cmp_eq_u32 s60, 60
	s_cselect_b32 s39, s17, s37
	s_cselect_b32 s38, s33, s36
	s_cselect_b32 s37, s15, s59
	s_cselect_b32 s36, s55, s58
	v_lshl_add_u64 v[220:221], s[0:1], 0, v[170:171]
	s_add_i32 m0, s31, 0xc000
	ds_read_b128 v[178:181], v190
	ds_read_b128 v[192:195], v190 offset:1024
	ds_read_b128 v[196:199], v190 offset:2048
	ds_read_b128 v[200:203], v190 offset:3072
	ds_read_b128 v[204:207], v190 offset:4096
	ds_read_b128 v[208:211], v190 offset:5120
	ds_read_b128 v[212:215], v190 offset:6144
	ds_read_b128 v[216:219], v190 offset:7168
	global_load_lds_dwordx4 v[220:221], off
	v_lshl_add_u64 v[220:221], s[0:1], 0, v[172:173]
	s_add_i32 m0, s31, 0xe000
	s_nop 0
	global_load_lds_dwordx4 v[220:221], off
	s_waitcnt vmcnt(8) lgkmcnt(0)
	s_barrier
	v_mfma_f32_16x16x32_bf16 v[124:127], v[128:131], v[178:181], v[124:127]
	v_mfma_f32_16x16x32_bf16 v[120:123], v[136:139], v[178:181], v[120:123]
	v_mfma_f32_16x16x32_bf16 v[108:111], v[128:131], v[196:199], v[108:111]
	v_mfma_f32_16x16x32_bf16 v[104:107], v[136:139], v[196:199], v[104:107]
	v_mfma_f32_16x16x32_bf16 v[92:95], v[128:131], v[204:207], v[92:95]
	v_mfma_f32_16x16x32_bf16 v[88:91], v[136:139], v[204:207], v[88:91]
	v_mfma_f32_16x16x32_bf16 v[76:79], v[128:131], v[212:215], v[76:79]
	v_mfma_f32_16x16x32_bf16 v[72:75], v[136:139], v[212:215], v[72:75]
	v_mfma_f32_16x16x32_bf16 v[124:127], v[132:135], v[192:195], v[124:127]
	v_mfma_f32_16x16x32_bf16 v[120:123], v[140:143], v[192:195], v[120:123]
	v_mfma_f32_16x16x32_bf16 v[108:111], v[132:135], v[200:203], v[108:111]
	v_mfma_f32_16x16x32_bf16 v[104:107], v[140:143], v[200:203], v[104:107]
	v_mfma_f32_16x16x32_bf16 v[92:95], v[132:135], v[208:211], v[92:95]
	v_mfma_f32_16x16x32_bf16 v[88:91], v[140:143], v[208:211], v[88:91]
	v_mfma_f32_16x16x32_bf16 v[76:79], v[132:135], v[216:219], v[76:79]
	v_mfma_f32_16x16x32_bf16 v[72:75], v[140:143], v[216:219], v[72:75]
	v_mfma_f32_16x16x32_bf16 v[116:119], v[144:147], v[178:181], v[116:119]
	v_mfma_f32_16x16x32_bf16 v[112:115], v[152:155], v[178:181], v[112:115]
	v_mfma_f32_16x16x32_bf16 v[100:103], v[144:147], v[196:199], v[100:103]
	v_mfma_f32_16x16x32_bf16 v[96:99], v[152:155], v[196:199], v[96:99]
	v_mfma_f32_16x16x32_bf16 v[84:87], v[144:147], v[204:207], v[84:87]
	v_mfma_f32_16x16x32_bf16 v[80:83], v[152:155], v[204:207], v[80:83]
	v_mfma_f32_16x16x32_bf16 v[68:71], v[144:147], v[212:215], v[68:71]
	v_mfma_f32_16x16x32_bf16 v[64:67], v[152:155], v[212:215], v[64:67]
	v_mfma_f32_16x16x32_bf16 v[116:119], v[148:151], v[192:195], v[116:119]
	v_mfma_f32_16x16x32_bf16 v[112:115], v[156:159], v[192:195], v[112:115]
	v_mfma_f32_16x16x32_bf16 v[100:103], v[148:151], v[200:203], v[100:103]
	v_mfma_f32_16x16x32_bf16 v[96:99], v[156:159], v[200:203], v[96:99]
	v_mfma_f32_16x16x32_bf16 v[84:87], v[148:151], v[208:211], v[84:87]
	v_mfma_f32_16x16x32_bf16 v[80:83], v[156:159], v[208:211], v[80:83]
	v_mfma_f32_16x16x32_bf16 v[68:71], v[148:151], v[216:219], v[68:71]
	v_mfma_f32_16x16x32_bf16 v[64:67], v[156:159], v[216:219], v[64:67]
	s_barrier
	s_add_i32 s61, s49, s40
	v_lshl_add_u64 v[220:221], s[36:37], 0, v[164:165]
	s_mov_b32 m0, s61
	ds_read_b128 v[178:181], v190 offset:16384
	ds_read_b128 v[192:195], v190 offset:17408
	ds_read_b128 v[196:199], v190 offset:18432
	ds_read_b128 v[200:203], v190 offset:19456
	ds_read_b128 v[204:207], v190 offset:20480
	ds_read_b128 v[208:211], v190 offset:21504
	ds_read_b128 v[212:215], v190 offset:22528
	ds_read_b128 v[216:219], v190 offset:23552
	global_load_lds_dwordx4 v[220:221], off
	s_add_i32 m0, s61, 0x2000
	s_add_u32 s62, s36, 0x100000
	v_lshl_add_u64 v[222:223], s[36:37], 0, v[168:169]
	s_addc_u32 s63, s37, 0
	s_add_i32 s61, s50, s40
	global_load_lds_dwordx4 v[222:223], off
	v_lshl_add_u64 v[224:225], s[62:63], 0, v[164:165]
	s_mov_b32 m0, s61
	v_lshl_add_u64 v[226:227], s[38:39], 0, v[166:167]
	global_load_lds_dwordx4 v[224:225], off
	v_lshl_add_u64 v[224:225], s[62:63], 0, v[168:169]
	s_add_i32 m0, s61, 0x2000
	s_nop 0
	global_load_lds_dwordx4 v[224:225], off
	v_lshl_add_u64 v[224:225], s[38:39], 0, v[162:163]
	s_mov_b32 m0, s31
	s_nop 0
	global_load_lds_dwordx4 v[224:225], off
	s_mov_b32 m0, s35
	s_nop 0
	global_load_lds_dwordx4 v[226:227], off
	s_waitcnt vmcnt(8) lgkmcnt(0)
	s_barrier
	v_mfma_f32_16x16x32_bf16 v[60:63], v[128:131], v[178:181], v[60:63]
	v_mfma_f32_16x16x32_bf16 v[56:59], v[136:139], v[178:181], v[56:59]
	v_mfma_f32_16x16x32_bf16 v[44:47], v[128:131], v[196:199], v[44:47]
	v_mfma_f32_16x16x32_bf16 v[40:43], v[136:139], v[196:199], v[40:43]
	v_mfma_f32_16x16x32_bf16 v[28:31], v[128:131], v[204:207], v[28:31]
	v_mfma_f32_16x16x32_bf16 v[24:27], v[136:139], v[204:207], v[24:27]
	v_mfma_f32_16x16x32_bf16 v[12:15], v[128:131], v[212:215], v[12:15]
	v_mfma_f32_16x16x32_bf16 v[8:11], v[136:139], v[212:215], v[8:11]
	v_mfma_f32_16x16x32_bf16 v[60:63], v[132:135], v[192:195], v[60:63]
	v_mfma_f32_16x16x32_bf16 v[56:59], v[140:143], v[192:195], v[56:59]
	v_mfma_f32_16x16x32_bf16 v[44:47], v[132:135], v[200:203], v[44:47]
	v_mfma_f32_16x16x32_bf16 v[40:43], v[140:143], v[200:203], v[40:43]
	v_mfma_f32_16x16x32_bf16 v[28:31], v[132:135], v[208:211], v[28:31]
	v_mfma_f32_16x16x32_bf16 v[24:27], v[140:143], v[208:211], v[24:27]
	v_mfma_f32_16x16x32_bf16 v[12:15], v[132:135], v[216:219], v[12:15]
	v_mfma_f32_16x16x32_bf16 v[8:11], v[140:143], v[216:219], v[8:11]
	v_mfma_f32_16x16x32_bf16 v[52:55], v[144:147], v[178:181], v[52:55]
	v_mfma_f32_16x16x32_bf16 v[48:51], v[152:155], v[178:181], v[48:51]
	v_mfma_f32_16x16x32_bf16 v[36:39], v[144:147], v[196:199], v[36:39]
	v_mfma_f32_16x16x32_bf16 v[32:35], v[152:155], v[196:199], v[32:35]
	v_mfma_f32_16x16x32_bf16 v[20:23], v[144:147], v[204:207], v[20:23]
	v_mfma_f32_16x16x32_bf16 v[16:19], v[152:155], v[204:207], v[16:19]
	v_mfma_f32_16x16x32_bf16 v[4:7], v[144:147], v[212:215], v[4:7]
	v_mfma_f32_16x16x32_bf16 v[0:3], v[152:155], v[212:215], v[0:3]
	v_mfma_f32_16x16x32_bf16 v[52:55], v[148:151], v[192:195], v[52:55]
	v_mfma_f32_16x16x32_bf16 v[48:51], v[156:159], v[192:195], v[48:51]
	v_mfma_f32_16x16x32_bf16 v[36:39], v[148:151], v[200:203], v[36:39]
	v_mfma_f32_16x16x32_bf16 v[32:35], v[156:159], v[200:203], v[32:35]
	v_mfma_f32_16x16x32_bf16 v[20:23], v[148:151], v[208:211], v[20:23]
	v_mfma_f32_16x16x32_bf16 v[16:19], v[156:159], v[208:211], v[16:19]
	v_mfma_f32_16x16x32_bf16 v[4:7], v[148:151], v[216:219], v[4:7]
	v_mfma_f32_16x16x32_bf16 v[0:3], v[156:159], v[216:219], v[0:3]
	s_barrier
	s_add_i32 s61, 0, 0x18000
	s_add_i32 s62, 0, 0x1c000
	v_add_u32_e32 v140, s61, v183
	v_add_u32_e32 v156, s62, v183
	ds_read_b128 v[128:131], v140
	ds_read_b128 v[132:135], v140 offset:1024
	ds_read_b128 v[136:139], v140 offset:2048
	ds_read_b128 v[140:143], v140 offset:3072
	ds_read_b128 v[144:147], v156
	ds_read_b128 v[148:151], v156 offset:1024
	ds_read_b128 v[152:155], v156 offset:2048
	ds_read_b128 v[156:159], v156 offset:3072
	s_add_u32 s38, s38, 0x100000
	s_addc_u32 s39, s39, 0
	s_mov_b32 m0, s41
	v_lshl_add_u64 v[228:229], s[38:39], 0, v[162:163]
	ds_read_b128 v[178:181], v190 offset:32768
	ds_read_b128 v[192:195], v190 offset:33792
	ds_read_b128 v[196:199], v190 offset:34816
	ds_read_b128 v[200:203], v190 offset:35840
	ds_read_b128 v[204:207], v190 offset:36864
	ds_read_b128 v[208:211], v190 offset:37888
	ds_read_b128 v[212:215], v190 offset:38912
	ds_read_b128 v[216:219], v190 offset:39936
	global_load_lds_dwordx4 v[228:229], off
	v_lshl_add_u64 v[228:229], s[38:39], 0, v[166:167]
	s_mov_b32 m0, s42
	s_nop 0
	global_load_lds_dwordx4 v[228:229], off
	s_waitcnt vmcnt(8) lgkmcnt(0)
	s_barrier
	v_mfma_f32_16x16x32_bf16 v[124:127], v[128:131], v[178:181], v[124:127]
	v_mfma_f32_16x16x32_bf16 v[120:123], v[136:139], v[178:181], v[120:123]
	v_mfma_f32_16x16x32_bf16 v[108:111], v[128:131], v[196:199], v[108:111]
	v_mfma_f32_16x16x32_bf16 v[104:107], v[136:139], v[196:199], v[104:107]
	v_mfma_f32_16x16x32_bf16 v[92:95], v[128:131], v[204:207], v[92:95]
	v_mfma_f32_16x16x32_bf16 v[88:91], v[136:139], v[204:207], v[88:91]
	v_mfma_f32_16x16x32_bf16 v[76:79], v[128:131], v[212:215], v[76:79]
	v_mfma_f32_16x16x32_bf16 v[72:75], v[136:139], v[212:215], v[72:75]
	v_mfma_f32_16x16x32_bf16 v[124:127], v[132:135], v[192:195], v[124:127]
	v_mfma_f32_16x16x32_bf16 v[120:123], v[140:143], v[192:195], v[120:123]
	v_mfma_f32_16x16x32_bf16 v[108:111], v[132:135], v[200:203], v[108:111]
	v_mfma_f32_16x16x32_bf16 v[104:107], v[140:143], v[200:203], v[104:107]
	v_mfma_f32_16x16x32_bf16 v[92:95], v[132:135], v[208:211], v[92:95]
	v_mfma_f32_16x16x32_bf16 v[88:91], v[140:143], v[208:211], v[88:91]
	v_mfma_f32_16x16x32_bf16 v[76:79], v[132:135], v[216:219], v[76:79]
	v_mfma_f32_16x16x32_bf16 v[72:75], v[140:143], v[216:219], v[72:75]
	v_mfma_f32_16x16x32_bf16 v[116:119], v[144:147], v[178:181], v[116:119]
	v_mfma_f32_16x16x32_bf16 v[112:115], v[152:155], v[178:181], v[112:115]
	v_mfma_f32_16x16x32_bf16 v[100:103], v[144:147], v[196:199], v[100:103]
	v_mfma_f32_16x16x32_bf16 v[96:99], v[152:155], v[196:199], v[96:99]
	v_mfma_f32_16x16x32_bf16 v[84:87], v[144:147], v[204:207], v[84:87]
	v_mfma_f32_16x16x32_bf16 v[80:83], v[152:155], v[204:207], v[80:83]
	v_mfma_f32_16x16x32_bf16 v[68:71], v[144:147], v[212:215], v[68:71]
	v_mfma_f32_16x16x32_bf16 v[64:67], v[152:155], v[212:215], v[64:67]
	v_mfma_f32_16x16x32_bf16 v[116:119], v[148:151], v[192:195], v[116:119]
	v_mfma_f32_16x16x32_bf16 v[112:115], v[156:159], v[192:195], v[112:115]
	v_mfma_f32_16x16x32_bf16 v[100:103], v[148:151], v[200:203], v[100:103]
	v_mfma_f32_16x16x32_bf16 v[96:99], v[156:159], v[200:203], v[96:99]
	v_mfma_f32_16x16x32_bf16 v[84:87], v[148:151], v[208:211], v[84:87]
	v_mfma_f32_16x16x32_bf16 v[80:83], v[156:159], v[208:211], v[80:83]
	v_mfma_f32_16x16x32_bf16 v[68:71], v[148:151], v[216:219], v[68:71]
	v_mfma_f32_16x16x32_bf16 v[64:67], v[156:159], v[216:219], v[64:67]
	s_barrier
	s_add_i32 s38, s61, s40
	v_lshl_add_u64 v[220:221], v[220:221], 0, s[8:9]
	s_mov_b32 m0, s38
	ds_read_b128 v[178:181], v190 offset:49152
	ds_read_b128 v[192:195], v190 offset:50176
	ds_read_b128 v[196:199], v190 offset:51200
	ds_read_b128 v[200:203], v190 offset:52224
	ds_read_b128 v[204:207], v190 offset:53248
	ds_read_b128 v[208:211], v190 offset:54272
	ds_read_b128 v[212:215], v190 offset:55296
	ds_read_b128 v[216:219], v190 offset:56320
	global_load_lds_dwordx4 v[220:221], off
	s_add_i32 m0, s38, 0x2000
	s_add_u32 s36, s36, 0x100080
	v_lshl_add_u64 v[220:221], v[222:223], 0, s[8:9]
	s_addc_u32 s37, s37, 0
	s_add_i32 s38, s62, s40
	global_load_lds_dwordx4 v[220:221], off
	v_lshl_add_u64 v[220:221], s[36:37], 0, v[164:165]
	s_mov_b32 m0, s38
	s_nop 0
	global_load_lds_dwordx4 v[220:221], off
	v_lshl_add_u64 v[220:221], s[36:37], 0, v[168:169]
	s_add_i32 m0, s38, 0x2000
	s_nop 0
	global_load_lds_dwordx4 v[220:221], off
	v_lshl_add_u64 v[220:221], v[224:225], 0, s[8:9]
	s_mov_b32 m0, s45
	s_nop 0
	global_load_lds_dwordx4 v[220:221], off
	v_lshl_add_u64 v[220:221], v[226:227], 0, s[8:9]
	s_mov_b32 m0, s46
	s_nop 0
	global_load_lds_dwordx4 v[220:221], off
	s_waitcnt vmcnt(8) lgkmcnt(0)
	s_barrier
	v_mfma_f32_16x16x32_bf16 v[60:63], v[128:131], v[178:181], v[60:63]
	v_mfma_f32_16x16x32_bf16 v[56:59], v[136:139], v[178:181], v[56:59]
	v_mfma_f32_16x16x32_bf16 v[44:47], v[128:131], v[196:199], v[44:47]
	v_mfma_f32_16x16x32_bf16 v[40:43], v[136:139], v[196:199], v[40:43]
	v_mfma_f32_16x16x32_bf16 v[28:31], v[128:131], v[204:207], v[28:31]
	v_mfma_f32_16x16x32_bf16 v[24:27], v[136:139], v[204:207], v[24:27]
	v_mfma_f32_16x16x32_bf16 v[12:15], v[128:131], v[212:215], v[12:15]
	v_mfma_f32_16x16x32_bf16 v[8:11], v[136:139], v[212:215], v[8:11]
	v_mfma_f32_16x16x32_bf16 v[60:63], v[132:135], v[192:195], v[60:63]
	v_mfma_f32_16x16x32_bf16 v[56:59], v[140:143], v[192:195], v[56:59]
	v_mfma_f32_16x16x32_bf16 v[44:47], v[132:135], v[200:203], v[44:47]
	v_mfma_f32_16x16x32_bf16 v[40:43], v[140:143], v[200:203], v[40:43]
	v_mfma_f32_16x16x32_bf16 v[28:31], v[132:135], v[208:211], v[28:31]
	v_mfma_f32_16x16x32_bf16 v[24:27], v[140:143], v[208:211], v[24:27]
	v_mfma_f32_16x16x32_bf16 v[12:15], v[132:135], v[216:219], v[12:15]
	v_mfma_f32_16x16x32_bf16 v[8:11], v[140:143], v[216:219], v[8:11]
	v_mfma_f32_16x16x32_bf16 v[52:55], v[144:147], v[178:181], v[52:55]
	v_mfma_f32_16x16x32_bf16 v[48:51], v[152:155], v[178:181], v[48:51]
	v_mfma_f32_16x16x32_bf16 v[36:39], v[144:147], v[196:199], v[36:39]
	v_mfma_f32_16x16x32_bf16 v[32:35], v[152:155], v[196:199], v[32:35]
	v_mfma_f32_16x16x32_bf16 v[20:23], v[144:147], v[204:207], v[20:23]
	v_mfma_f32_16x16x32_bf16 v[16:19], v[152:155], v[204:207], v[16:19]
	v_mfma_f32_16x16x32_bf16 v[4:7], v[144:147], v[212:215], v[4:7]
	v_mfma_f32_16x16x32_bf16 v[0:3], v[152:155], v[212:215], v[0:3]
	v_mfma_f32_16x16x32_bf16 v[52:55], v[148:151], v[192:195], v[52:55]
	v_mfma_f32_16x16x32_bf16 v[48:51], v[156:159], v[192:195], v[48:51]
	v_mfma_f32_16x16x32_bf16 v[36:39], v[148:151], v[200:203], v[36:39]
	v_mfma_f32_16x16x32_bf16 v[32:35], v[156:159], v[200:203], v[32:35]
	v_mfma_f32_16x16x32_bf16 v[20:23], v[148:151], v[208:211], v[20:23]
	v_mfma_f32_16x16x32_bf16 v[16:19], v[156:159], v[208:211], v[16:19]
	v_mfma_f32_16x16x32_bf16 v[4:7], v[148:151], v[216:219], v[4:7]
	v_mfma_f32_16x16x32_bf16 v[0:3], v[156:159], v[216:219], v[0:3]
	s_barrier
	s_add_i32 s60, s60, 2
	s_add_u32 s0, s0, 0x100
	s_addc_u32 s1, s1, 0
	s_add_u32 s58, s58, 0x100
	s_addc_u32 s59, s59, 0
	s_cmp_gt_u32 s60, 61
	s_cbranch_scc0 .LBB0_711

.LBB0_798:
	s_ashr_i32 s29, s28, 31
	s_lshl_b64 s[30:31], s[28:29], 19
	s_add_u32 s30, s96, s30
	s_addc_u32 s31, s97, s31
	s_and_b64 s[34:35], s[4:5], exec
	s_cselect_b32 s3, s31, s1
	s_cselect_b32 s7, s30, s0
	s_ashr_i32 s27, s26, 31
	s_lshl_b64 s[34:35], s[26:27], 19
	s_add_u32 s34, s58, s34
	s_addc_u32 s35, s59, s35
	s_and_b64 s[36:37], s[4:5], exec
	s_cselect_b32 s27, s35, s9
	s_cselect_b32 s29, s34, s8
	s_add_u32 s0, s0, 0x40080
	s_addc_u32 s1, s1, 0
	s_add_u32 s33, s8, 0x100
	s_addc_u32 s38, s9, 0
	s_mov_b32 s39, -2
	ds_read_b128 v[128:131], v177
	ds_read_b128 v[154:157], v177 offset:1024
	ds_read_b128 v[162:165], v177 offset:2048
	ds_read_b128 v[166:169], v177 offset:3072
	ds_read_b128 v[182:185], v178
	ds_read_b128 v[186:189], v178 offset:1024
	ds_read_b128 v[190:193], v178 offset:2048
	ds_read_b128 v[194:197], v178 offset:3072
	s_add_u32 s8, s0, 0xfffc0080
	s_addc_u32 s9, s1, -1
	s_cmp_eq_u32 s39, 12
	s_cselect_b32 s37, s3, s9
	s_cselect_b32 s36, s7, s8
	s_cselect_b32 s9, s27, s38
	s_cselect_b32 s8, s29, s33
	v_lshl_add_u64 v[158:159], s[0:1], 0, v[146:147]
	s_add_i32 m0, s62, 0xc000
	ds_read_b128 v[198:201], v179
	ds_read_b128 v[202:205], v179 offset:1024
	ds_read_b128 v[206:209], v179 offset:2048
	ds_read_b128 v[210:213], v179 offset:3072
	ds_read_b128 v[214:217], v179 offset:4096
	ds_read_b128 v[218:221], v179 offset:5120
	ds_read_b128 v[222:225], v179 offset:6144
	ds_read_b128 v[226:229], v179 offset:7168
	global_load_lds_dwordx4 v[158:159], off
	v_lshl_add_u64 v[158:159], s[0:1], 0, v[148:149]
	s_add_i32 m0, s62, 0xe000
	s_nop 0
	global_load_lds_dwordx4 v[158:159], off
	s_waitcnt vmcnt(8) lgkmcnt(0)
	s_barrier
	v_mfma_f32_16x16x32_bf16 v[124:127], v[128:131], v[198:201], 0
	v_mfma_f32_16x16x32_bf16 v[120:123], v[162:165], v[198:201], 0
	v_mfma_f32_16x16x32_bf16 v[108:111], v[128:131], v[206:209], 0
	v_mfma_f32_16x16x32_bf16 v[104:107], v[162:165], v[206:209], 0
	v_mfma_f32_16x16x32_bf16 v[92:95], v[128:131], v[214:217], 0
	v_mfma_f32_16x16x32_bf16 v[88:91], v[162:165], v[214:217], 0
	v_mfma_f32_16x16x32_bf16 v[76:79], v[128:131], v[222:225], 0
	v_mfma_f32_16x16x32_bf16 v[72:75], v[162:165], v[222:225], 0
	v_mfma_f32_16x16x32_bf16 v[124:127], v[154:157], v[202:205], v[124:127]
	v_mfma_f32_16x16x32_bf16 v[120:123], v[166:169], v[202:205], v[120:123]
	v_mfma_f32_16x16x32_bf16 v[108:111], v[154:157], v[210:213], v[108:111]
	v_mfma_f32_16x16x32_bf16 v[104:107], v[166:169], v[210:213], v[104:107]
	v_mfma_f32_16x16x32_bf16 v[92:95], v[154:157], v[218:221], v[92:95]
	v_mfma_f32_16x16x32_bf16 v[88:91], v[166:169], v[218:221], v[88:91]
	v_mfma_f32_16x16x32_bf16 v[76:79], v[154:157], v[226:229], v[76:79]
	v_mfma_f32_16x16x32_bf16 v[72:75], v[166:169], v[226:229], v[72:75]
	v_mfma_f32_16x16x32_bf16 v[116:119], v[182:185], v[198:201], 0
	v_mfma_f32_16x16x32_bf16 v[112:115], v[190:193], v[198:201], 0
	v_mfma_f32_16x16x32_bf16 v[100:103], v[182:185], v[206:209], 0
	v_mfma_f32_16x16x32_bf16 v[96:99], v[190:193], v[206:209], 0
	v_mfma_f32_16x16x32_bf16 v[84:87], v[182:185], v[214:217], 0
	v_mfma_f32_16x16x32_bf16 v[80:83], v[190:193], v[214:217], 0
	v_mfma_f32_16x16x32_bf16 v[68:71], v[182:185], v[222:225], 0
	v_mfma_f32_16x16x32_bf16 v[64:67], v[190:193], v[222:225], 0
	v_mfma_f32_16x16x32_bf16 v[116:119], v[186:189], v[202:205], v[116:119]
	v_mfma_f32_16x16x32_bf16 v[112:115], v[194:197], v[202:205], v[112:115]
	v_mfma_f32_16x16x32_bf16 v[100:103], v[186:189], v[210:213], v[100:103]
	v_mfma_f32_16x16x32_bf16 v[96:99], v[194:197], v[210:213], v[96:99]
	v_mfma_f32_16x16x32_bf16 v[84:87], v[186:189], v[218:221], v[84:87]
	v_mfma_f32_16x16x32_bf16 v[80:83], v[194:197], v[218:221], v[80:83]
	v_mfma_f32_16x16x32_bf16 v[68:71], v[186:189], v[226:229], v[68:71]
	v_mfma_f32_16x16x32_bf16 v[64:67], v[194:197], v[226:229], v[64:67]
	s_barrier
	s_add_i32 s40, s78, s61
	v_lshl_add_u64 v[158:159], s[8:9], 0, v[134:135]
	s_mov_b32 m0, s40
	ds_read_b128 v[198:201], v179 offset:16384
	ds_read_b128 v[202:205], v179 offset:17408
	ds_read_b128 v[206:209], v179 offset:18432
	ds_read_b128 v[210:213], v179 offset:19456
	ds_read_b128 v[214:217], v179 offset:20480
	ds_read_b128 v[218:221], v179 offset:21504
	ds_read_b128 v[222:225], v179 offset:22528
	ds_read_b128 v[226:229], v179 offset:23552
	global_load_lds_dwordx4 v[158:159], off
	s_add_i32 m0, s40, 0x2000
	s_add_u32 s40, s8, 0x40000
	v_lshl_add_u64 v[230:231], s[8:9], 0, v[138:139]
	s_addc_u32 s41, s9, 0
	s_add_i32 s42, s79, s61
	global_load_lds_dwordx4 v[230:231], off
	v_lshl_add_u64 v[232:233], s[40:41], 0, v[134:135]
	s_mov_b32 m0, s42
	v_lshl_add_u64 v[234:235], s[36:37], 0, v[136:137]
	global_load_lds_dwordx4 v[232:233], off
	v_lshl_add_u64 v[232:233], s[40:41], 0, v[138:139]
	s_add_i32 m0, s42, 0x2000
	s_nop 0
	global_load_lds_dwordx4 v[232:233], off
	v_lshl_add_u64 v[232:233], s[36:37], 0, v[132:133]
	s_mov_b32 m0, s62
	s_nop 0
	global_load_lds_dwordx4 v[232:233], off
	s_mov_b32 m0, s63
	s_nop 0
	global_load_lds_dwordx4 v[234:235], off
	s_waitcnt vmcnt(8) lgkmcnt(0)
	s_barrier
	v_mfma_f32_16x16x32_bf16 v[60:63], v[128:131], v[198:201], 0
	v_mfma_f32_16x16x32_bf16 v[56:59], v[162:165], v[198:201], 0
	v_mfma_f32_16x16x32_bf16 v[44:47], v[128:131], v[206:209], 0
	v_mfma_f32_16x16x32_bf16 v[40:43], v[162:165], v[206:209], 0
	v_mfma_f32_16x16x32_bf16 v[28:31], v[128:131], v[214:217], 0
	v_mfma_f32_16x16x32_bf16 v[24:27], v[162:165], v[214:217], 0
	v_mfma_f32_16x16x32_bf16 v[12:15], v[128:131], v[222:225], 0
	v_mfma_f32_16x16x32_bf16 v[8:11], v[162:165], v[222:225], 0
	v_mfma_f32_16x16x32_bf16 v[60:63], v[154:157], v[202:205], v[60:63]
	v_mfma_f32_16x16x32_bf16 v[56:59], v[166:169], v[202:205], v[56:59]
	v_mfma_f32_16x16x32_bf16 v[44:47], v[154:157], v[210:213], v[44:47]
	v_mfma_f32_16x16x32_bf16 v[40:43], v[166:169], v[210:213], v[40:43]
	v_mfma_f32_16x16x32_bf16 v[28:31], v[154:157], v[218:221], v[28:31]
	v_mfma_f32_16x16x32_bf16 v[24:27], v[166:169], v[218:221], v[24:27]
	v_mfma_f32_16x16x32_bf16 v[12:15], v[154:157], v[226:229], v[12:15]
	v_mfma_f32_16x16x32_bf16 v[8:11], v[166:169], v[226:229], v[8:11]
	v_mfma_f32_16x16x32_bf16 v[52:55], v[182:185], v[198:201], 0
	v_mfma_f32_16x16x32_bf16 v[48:51], v[190:193], v[198:201], 0
	v_mfma_f32_16x16x32_bf16 v[36:39], v[182:185], v[206:209], 0
	v_mfma_f32_16x16x32_bf16 v[32:35], v[190:193], v[206:209], 0
	v_mfma_f32_16x16x32_bf16 v[20:23], v[182:185], v[214:217], 0
	v_mfma_f32_16x16x32_bf16 v[16:19], v[190:193], v[214:217], 0
	v_mfma_f32_16x16x32_bf16 v[4:7], v[182:185], v[222:225], 0
	v_mfma_f32_16x16x32_bf16 v[0:3], v[190:193], v[222:225], 0
	v_mfma_f32_16x16x32_bf16 v[52:55], v[186:189], v[202:205], v[52:55]
	v_mfma_f32_16x16x32_bf16 v[48:51], v[194:197], v[202:205], v[48:51]
	v_mfma_f32_16x16x32_bf16 v[36:39], v[186:189], v[210:213], v[36:39]
	v_mfma_f32_16x16x32_bf16 v[32:35], v[194:197], v[210:213], v[32:35]
	v_mfma_f32_16x16x32_bf16 v[20:23], v[186:189], v[218:221], v[20:23]
	v_mfma_f32_16x16x32_bf16 v[16:19], v[194:197], v[218:221], v[16:19]
	v_mfma_f32_16x16x32_bf16 v[4:7], v[186:189], v[226:229], v[4:7]
	v_mfma_f32_16x16x32_bf16 v[0:3], v[194:197], v[226:229], v[0:3]
	s_barrier
	s_add_i32 s40, 0, 0x18000
	v_add_u32_e32 v140, s40, v171
	s_add_i32 s41, 0, 0x1c000
	ds_read_b128 v[128:131], v140
	ds_read_b128 v[154:157], v140 offset:1024
	ds_read_b128 v[162:165], v140 offset:2048
	ds_read_b128 v[166:169], v140 offset:3072
	v_add_u32_e32 v140, s41, v171
	ds_read_b128 v[182:185], v140
	ds_read_b128 v[186:189], v140 offset:1024
	ds_read_b128 v[190:193], v140 offset:2048
	ds_read_b128 v[194:197], v140 offset:3072
	s_add_u32 s36, s36, 0x40000
	s_addc_u32 s37, s37, 0
	s_mov_b32 m0, s64
	v_lshl_add_u64 v[236:237], s[36:37], 0, v[132:133]
	ds_read_b128 v[198:201], v179 offset:32768
	ds_read_b128 v[202:205], v179 offset:33792
	ds_read_b128 v[206:209], v179 offset:34816
	ds_read_b128 v[210:213], v179 offset:35840
	ds_read_b128 v[214:217], v179 offset:36864
	ds_read_b128 v[218:221], v179 offset:37888
	ds_read_b128 v[222:225], v179 offset:38912
	ds_read_b128 v[226:229], v179 offset:39936
	global_load_lds_dwordx4 v[236:237], off
	v_lshl_add_u64 v[236:237], s[36:37], 0, v[136:137]
	s_mov_b32 m0, s65
	s_nop 0
	global_load_lds_dwordx4 v[236:237], off
	s_waitcnt vmcnt(8) lgkmcnt(0)
	s_barrier
	v_mfma_f32_16x16x32_bf16 v[124:127], v[128:131], v[198:201], v[124:127]
	v_mfma_f32_16x16x32_bf16 v[120:123], v[162:165], v[198:201], v[120:123]
	v_mfma_f32_16x16x32_bf16 v[108:111], v[128:131], v[206:209], v[108:111]
	v_mfma_f32_16x16x32_bf16 v[104:107], v[162:165], v[206:209], v[104:107]
	v_mfma_f32_16x16x32_bf16 v[92:95], v[128:131], v[214:217], v[92:95]
	v_mfma_f32_16x16x32_bf16 v[88:91], v[162:165], v[214:217], v[88:91]
	v_mfma_f32_16x16x32_bf16 v[76:79], v[128:131], v[222:225], v[76:79]
	v_mfma_f32_16x16x32_bf16 v[72:75], v[162:165], v[222:225], v[72:75]
	v_mfma_f32_16x16x32_bf16 v[124:127], v[154:157], v[202:205], v[124:127]
	v_mfma_f32_16x16x32_bf16 v[120:123], v[166:169], v[202:205], v[120:123]
	v_mfma_f32_16x16x32_bf16 v[108:111], v[154:157], v[210:213], v[108:111]
	v_mfma_f32_16x16x32_bf16 v[104:107], v[166:169], v[210:213], v[104:107]
	v_mfma_f32_16x16x32_bf16 v[92:95], v[154:157], v[218:221], v[92:95]
	v_mfma_f32_16x16x32_bf16 v[88:91], v[166:169], v[218:221], v[88:91]
	v_mfma_f32_16x16x32_bf16 v[76:79], v[154:157], v[226:229], v[76:79]
	v_mfma_f32_16x16x32_bf16 v[72:75], v[166:169], v[226:229], v[72:75]
	v_mfma_f32_16x16x32_bf16 v[116:119], v[182:185], v[198:201], v[116:119]
	v_mfma_f32_16x16x32_bf16 v[112:115], v[190:193], v[198:201], v[112:115]
	v_mfma_f32_16x16x32_bf16 v[100:103], v[182:185], v[206:209], v[100:103]
	v_mfma_f32_16x16x32_bf16 v[96:99], v[190:193], v[206:209], v[96:99]
	v_mfma_f32_16x16x32_bf16 v[84:87], v[182:185], v[214:217], v[84:87]
	v_mfma_f32_16x16x32_bf16 v[80:83], v[190:193], v[214:217], v[80:83]
	v_mfma_f32_16x16x32_bf16 v[68:71], v[182:185], v[222:225], v[68:71]
	v_mfma_f32_16x16x32_bf16 v[64:67], v[190:193], v[222:225], v[64:67]
	v_mfma_f32_16x16x32_bf16 v[116:119], v[186:189], v[202:205], v[116:119]
	v_mfma_f32_16x16x32_bf16 v[112:115], v[194:197], v[202:205], v[112:115]
	v_mfma_f32_16x16x32_bf16 v[100:103], v[186:189], v[210:213], v[100:103]
	v_mfma_f32_16x16x32_bf16 v[96:99], v[194:197], v[210:213], v[96:99]
	v_mfma_f32_16x16x32_bf16 v[84:87], v[186:189], v[218:221], v[84:87]
	v_mfma_f32_16x16x32_bf16 v[80:83], v[194:197], v[218:221], v[80:83]
	v_mfma_f32_16x16x32_bf16 v[68:71], v[186:189], v[226:229], v[68:71]
	v_mfma_f32_16x16x32_bf16 v[64:67], v[194:197], v[226:229], v[64:67]
	s_barrier
	s_add_i32 s36, s40, s61
	v_lshl_add_u64 v[158:159], v[158:159], 0, s[14:15]
	s_mov_b32 m0, s36
	ds_read_b128 v[198:201], v179 offset:49152
	ds_read_b128 v[202:205], v179 offset:50176
	ds_read_b128 v[206:209], v179 offset:51200
	ds_read_b128 v[210:213], v179 offset:52224
	ds_read_b128 v[214:217], v179 offset:53248
	ds_read_b128 v[218:221], v179 offset:54272
	ds_read_b128 v[222:225], v179 offset:55296
	ds_read_b128 v[226:229], v179 offset:56320
	global_load_lds_dwordx4 v[158:159], off
	s_add_i32 m0, s36, 0x2000
	s_add_u32 s8, s8, 0x40080
	v_lshl_add_u64 v[158:159], v[230:231], 0, s[14:15]
	s_addc_u32 s9, s9, 0
	s_add_i32 s36, s41, s61
	global_load_lds_dwordx4 v[158:159], off
	v_lshl_add_u64 v[158:159], s[8:9], 0, v[134:135]
	s_mov_b32 m0, s36
	s_nop 0
	global_load_lds_dwordx4 v[158:159], off
	v_lshl_add_u64 v[158:159], s[8:9], 0, v[138:139]
	s_add_i32 m0, s36, 0x2000
	s_nop 0
	global_load_lds_dwordx4 v[158:159], off
	v_lshl_add_u64 v[158:159], v[232:233], 0, s[14:15]
	s_mov_b32 m0, s76
	s_nop 0
	global_load_lds_dwordx4 v[158:159], off
	v_lshl_add_u64 v[158:159], v[234:235], 0, s[14:15]
	s_mov_b32 m0, s77
	s_nop 0
	global_load_lds_dwordx4 v[158:159], off
	s_waitcnt vmcnt(8) lgkmcnt(0)
	s_barrier
	v_mfma_f32_16x16x32_bf16 v[60:63], v[128:131], v[198:201], v[60:63]
	v_mfma_f32_16x16x32_bf16 v[56:59], v[162:165], v[198:201], v[56:59]
	v_mfma_f32_16x16x32_bf16 v[44:47], v[128:131], v[206:209], v[44:47]
	v_mfma_f32_16x16x32_bf16 v[40:43], v[162:165], v[206:209], v[40:43]
	v_mfma_f32_16x16x32_bf16 v[28:31], v[128:131], v[214:217], v[28:31]
	v_mfma_f32_16x16x32_bf16 v[24:27], v[162:165], v[214:217], v[24:27]
	v_mfma_f32_16x16x32_bf16 v[12:15], v[128:131], v[222:225], v[12:15]
	v_mfma_f32_16x16x32_bf16 v[8:11], v[162:165], v[222:225], v[8:11]
	v_mfma_f32_16x16x32_bf16 v[60:63], v[154:157], v[202:205], v[60:63]
	v_mfma_f32_16x16x32_bf16 v[56:59], v[166:169], v[202:205], v[56:59]
	v_mfma_f32_16x16x32_bf16 v[44:47], v[154:157], v[210:213], v[44:47]
	v_mfma_f32_16x16x32_bf16 v[40:43], v[166:169], v[210:213], v[40:43]
	v_mfma_f32_16x16x32_bf16 v[28:31], v[154:157], v[218:221], v[28:31]
	v_mfma_f32_16x16x32_bf16 v[24:27], v[166:169], v[218:221], v[24:27]
	v_mfma_f32_16x16x32_bf16 v[12:15], v[154:157], v[226:229], v[12:15]
	v_mfma_f32_16x16x32_bf16 v[8:11], v[166:169], v[226:229], v[8:11]
	v_mfma_f32_16x16x32_bf16 v[52:55], v[182:185], v[198:201], v[52:55]
	v_mfma_f32_16x16x32_bf16 v[48:51], v[190:193], v[198:201], v[48:51]
	v_mfma_f32_16x16x32_bf16 v[36:39], v[182:185], v[206:209], v[36:39]
	v_mfma_f32_16x16x32_bf16 v[32:35], v[190:193], v[206:209], v[32:35]
	v_mfma_f32_16x16x32_bf16 v[20:23], v[182:185], v[214:217], v[20:23]
	v_mfma_f32_16x16x32_bf16 v[16:19], v[190:193], v[214:217], v[16:19]
	v_mfma_f32_16x16x32_bf16 v[4:7], v[182:185], v[222:225], v[4:7]
	v_mfma_f32_16x16x32_bf16 v[0:3], v[190:193], v[222:225], v[0:3]
	v_mfma_f32_16x16x32_bf16 v[52:55], v[186:189], v[202:205], v[52:55]
	v_mfma_f32_16x16x32_bf16 v[48:51], v[194:197], v[202:205], v[48:51]
	v_mfma_f32_16x16x32_bf16 v[36:39], v[186:189], v[210:213], v[36:39]
	v_mfma_f32_16x16x32_bf16 v[32:35], v[194:197], v[210:213], v[32:35]
	v_mfma_f32_16x16x32_bf16 v[20:23], v[186:189], v[218:221], v[20:23]
	v_mfma_f32_16x16x32_bf16 v[16:19], v[194:197], v[218:221], v[16:19]
	v_mfma_f32_16x16x32_bf16 v[4:7], v[186:189], v[226:229], v[4:7]
	v_mfma_f32_16x16x32_bf16 v[0:3], v[194:197], v[226:229], v[0:3]
	s_barrier
	s_add_i32 s39, s39, 2
	s_add_u32 s0, s0, 0x100
	s_addc_u32 s1, s1, 0
	s_add_u32 s33, s33, 0x100
	s_addc_u32 s38, s38, 0
	s_cmp_gt_u32 s39, 13
	s_cbranch_scc0 .LBB0_799
	s_branch .Lpeel_exit_5
.LBB0_799:
	ds_read_b128 v[128:131], v177
	ds_read_b128 v[154:157], v177 offset:1024
	ds_read_b128 v[162:165], v177 offset:2048
	ds_read_b128 v[166:169], v177 offset:3072
	ds_read_b128 v[182:185], v178
	ds_read_b128 v[186:189], v178 offset:1024
	ds_read_b128 v[190:193], v178 offset:2048
	ds_read_b128 v[194:197], v178 offset:3072
	s_add_u32 s8, s0, 0xfffc0080
	s_addc_u32 s9, s1, -1
	s_cmp_eq_u32 s39, 12
	s_cselect_b32 s37, s3, s9
	s_cselect_b32 s36, s7, s8
	s_cselect_b32 s9, s27, s38
	s_cselect_b32 s8, s29, s33
	v_lshl_add_u64 v[158:159], s[0:1], 0, v[146:147]
	s_add_i32 m0, s62, 0xc000
	ds_read_b128 v[198:201], v179
	ds_read_b128 v[202:205], v179 offset:1024
	ds_read_b128 v[206:209], v179 offset:2048
	ds_read_b128 v[210:213], v179 offset:3072
	ds_read_b128 v[214:217], v179 offset:4096
	ds_read_b128 v[218:221], v179 offset:5120
	ds_read_b128 v[222:225], v179 offset:6144
	ds_read_b128 v[226:229], v179 offset:7168
	global_load_lds_dwordx4 v[158:159], off
	v_lshl_add_u64 v[158:159], s[0:1], 0, v[148:149]
	s_add_i32 m0, s62, 0xe000
	s_nop 0
	global_load_lds_dwordx4 v[158:159], off
	s_waitcnt vmcnt(8) lgkmcnt(0)
	s_barrier
	v_mfma_f32_16x16x32_bf16 v[124:127], v[128:131], v[198:201], v[124:127]
	v_mfma_f32_16x16x32_bf16 v[120:123], v[162:165], v[198:201], v[120:123]
	v_mfma_f32_16x16x32_bf16 v[108:111], v[128:131], v[206:209], v[108:111]
	v_mfma_f32_16x16x32_bf16 v[104:107], v[162:165], v[206:209], v[104:107]
	v_mfma_f32_16x16x32_bf16 v[92:95], v[128:131], v[214:217], v[92:95]
	v_mfma_f32_16x16x32_bf16 v[88:91], v[162:165], v[214:217], v[88:91]
	v_mfma_f32_16x16x32_bf16 v[76:79], v[128:131], v[222:225], v[76:79]
	v_mfma_f32_16x16x32_bf16 v[72:75], v[162:165], v[222:225], v[72:75]
	v_mfma_f32_16x16x32_bf16 v[124:127], v[154:157], v[202:205], v[124:127]
	v_mfma_f32_16x16x32_bf16 v[120:123], v[166:169], v[202:205], v[120:123]
	v_mfma_f32_16x16x32_bf16 v[108:111], v[154:157], v[210:213], v[108:111]
	v_mfma_f32_16x16x32_bf16 v[104:107], v[166:169], v[210:213], v[104:107]
	v_mfma_f32_16x16x32_bf16 v[92:95], v[154:157], v[218:221], v[92:95]
	v_mfma_f32_16x16x32_bf16 v[88:91], v[166:169], v[218:221], v[88:91]
	v_mfma_f32_16x16x32_bf16 v[76:79], v[154:157], v[226:229], v[76:79]
	v_mfma_f32_16x16x32_bf16 v[72:75], v[166:169], v[226:229], v[72:75]
	v_mfma_f32_16x16x32_bf16 v[116:119], v[182:185], v[198:201], v[116:119]
	v_mfma_f32_16x16x32_bf16 v[112:115], v[190:193], v[198:201], v[112:115]
	v_mfma_f32_16x16x32_bf16 v[100:103], v[182:185], v[206:209], v[100:103]
	v_mfma_f32_16x16x32_bf16 v[96:99], v[190:193], v[206:209], v[96:99]
	v_mfma_f32_16x16x32_bf16 v[84:87], v[182:185], v[214:217], v[84:87]
	v_mfma_f32_16x16x32_bf16 v[80:83], v[190:193], v[214:217], v[80:83]
	v_mfma_f32_16x16x32_bf16 v[68:71], v[182:185], v[222:225], v[68:71]
	v_mfma_f32_16x16x32_bf16 v[64:67], v[190:193], v[222:225], v[64:67]
	v_mfma_f32_16x16x32_bf16 v[116:119], v[186:189], v[202:205], v[116:119]
	v_mfma_f32_16x16x32_bf16 v[112:115], v[194:197], v[202:205], v[112:115]
	v_mfma_f32_16x16x32_bf16 v[100:103], v[186:189], v[210:213], v[100:103]
	v_mfma_f32_16x16x32_bf16 v[96:99], v[194:197], v[210:213], v[96:99]
	v_mfma_f32_16x16x32_bf16 v[84:87], v[186:189], v[218:221], v[84:87]
	v_mfma_f32_16x16x32_bf16 v[80:83], v[194:197], v[218:221], v[80:83]
	v_mfma_f32_16x16x32_bf16 v[68:71], v[186:189], v[226:229], v[68:71]
	v_mfma_f32_16x16x32_bf16 v[64:67], v[194:197], v[226:229], v[64:67]
	s_barrier
	s_add_i32 s40, s78, s61
	v_lshl_add_u64 v[158:159], s[8:9], 0, v[134:135]
	s_mov_b32 m0, s40
	ds_read_b128 v[198:201], v179 offset:16384
	ds_read_b128 v[202:205], v179 offset:17408
	ds_read_b128 v[206:209], v179 offset:18432
	ds_read_b128 v[210:213], v179 offset:19456
	ds_read_b128 v[214:217], v179 offset:20480
	ds_read_b128 v[218:221], v179 offset:21504
	ds_read_b128 v[222:225], v179 offset:22528
	ds_read_b128 v[226:229], v179 offset:23552
	global_load_lds_dwordx4 v[158:159], off
	s_add_i32 m0, s40, 0x2000
	s_add_u32 s40, s8, 0x40000
	v_lshl_add_u64 v[230:231], s[8:9], 0, v[138:139]
	s_addc_u32 s41, s9, 0
	s_add_i32 s42, s79, s61
	global_load_lds_dwordx4 v[230:231], off
	v_lshl_add_u64 v[232:233], s[40:41], 0, v[134:135]
	s_mov_b32 m0, s42
	v_lshl_add_u64 v[234:235], s[36:37], 0, v[136:137]
	global_load_lds_dwordx4 v[232:233], off
	v_lshl_add_u64 v[232:233], s[40:41], 0, v[138:139]
	s_add_i32 m0, s42, 0x2000
	s_nop 0
	global_load_lds_dwordx4 v[232:233], off
	v_lshl_add_u64 v[232:233], s[36:37], 0, v[132:133]
	s_mov_b32 m0, s62
	s_nop 0
	global_load_lds_dwordx4 v[232:233], off
	s_mov_b32 m0, s63
	s_nop 0
	global_load_lds_dwordx4 v[234:235], off
	s_waitcnt vmcnt(8) lgkmcnt(0)
	s_barrier
	v_mfma_f32_16x16x32_bf16 v[60:63], v[128:131], v[198:201], v[60:63]
	v_mfma_f32_16x16x32_bf16 v[56:59], v[162:165], v[198:201], v[56:59]
	v_mfma_f32_16x16x32_bf16 v[44:47], v[128:131], v[206:209], v[44:47]
	v_mfma_f32_16x16x32_bf16 v[40:43], v[162:165], v[206:209], v[40:43]
	v_mfma_f32_16x16x32_bf16 v[28:31], v[128:131], v[214:217], v[28:31]
	v_mfma_f32_16x16x32_bf16 v[24:27], v[162:165], v[214:217], v[24:27]
	v_mfma_f32_16x16x32_bf16 v[12:15], v[128:131], v[222:225], v[12:15]
	v_mfma_f32_16x16x32_bf16 v[8:11], v[162:165], v[222:225], v[8:11]
	v_mfma_f32_16x16x32_bf16 v[60:63], v[154:157], v[202:205], v[60:63]
	v_mfma_f32_16x16x32_bf16 v[56:59], v[166:169], v[202:205], v[56:59]
	v_mfma_f32_16x16x32_bf16 v[44:47], v[154:157], v[210:213], v[44:47]
	v_mfma_f32_16x16x32_bf16 v[40:43], v[166:169], v[210:213], v[40:43]
	v_mfma_f32_16x16x32_bf16 v[28:31], v[154:157], v[218:221], v[28:31]
	v_mfma_f32_16x16x32_bf16 v[24:27], v[166:169], v[218:221], v[24:27]
	v_mfma_f32_16x16x32_bf16 v[12:15], v[154:157], v[226:229], v[12:15]
	v_mfma_f32_16x16x32_bf16 v[8:11], v[166:169], v[226:229], v[8:11]
	v_mfma_f32_16x16x32_bf16 v[52:55], v[182:185], v[198:201], v[52:55]
	v_mfma_f32_16x16x32_bf16 v[48:51], v[190:193], v[198:201], v[48:51]
	v_mfma_f32_16x16x32_bf16 v[36:39], v[182:185], v[206:209], v[36:39]
	v_mfma_f32_16x16x32_bf16 v[32:35], v[190:193], v[206:209], v[32:35]
	v_mfma_f32_16x16x32_bf16 v[20:23], v[182:185], v[214:217], v[20:23]
	v_mfma_f32_16x16x32_bf16 v[16:19], v[190:193], v[214:217], v[16:19]
	v_mfma_f32_16x16x32_bf16 v[4:7], v[182:185], v[222:225], v[4:7]
	v_mfma_f32_16x16x32_bf16 v[0:3], v[190:193], v[222:225], v[0:3]
	v_mfma_f32_16x16x32_bf16 v[52:55], v[186:189], v[202:205], v[52:55]
	v_mfma_f32_16x16x32_bf16 v[48:51], v[194:197], v[202:205], v[48:51]
	v_mfma_f32_16x16x32_bf16 v[36:39], v[186:189], v[210:213], v[36:39]
	v_mfma_f32_16x16x32_bf16 v[32:35], v[194:197], v[210:213], v[32:35]
	v_mfma_f32_16x16x32_bf16 v[20:23], v[186:189], v[218:221], v[20:23]
	v_mfma_f32_16x16x32_bf16 v[16:19], v[194:197], v[218:221], v[16:19]
	v_mfma_f32_16x16x32_bf16 v[4:7], v[186:189], v[226:229], v[4:7]
	v_mfma_f32_16x16x32_bf16 v[0:3], v[194:197], v[226:229], v[0:3]
	s_barrier
	s_add_i32 s40, 0, 0x18000
	v_add_u32_e32 v140, s40, v171
	s_add_i32 s41, 0, 0x1c000
	ds_read_b128 v[128:131], v140
	ds_read_b128 v[154:157], v140 offset:1024
	ds_read_b128 v[162:165], v140 offset:2048
	ds_read_b128 v[166:169], v140 offset:3072
	v_add_u32_e32 v140, s41, v171
	ds_read_b128 v[182:185], v140
	ds_read_b128 v[186:189], v140 offset:1024
	ds_read_b128 v[190:193], v140 offset:2048
	ds_read_b128 v[194:197], v140 offset:3072
	s_add_u32 s36, s36, 0x40000
	s_addc_u32 s37, s37, 0
	s_mov_b32 m0, s64
	v_lshl_add_u64 v[236:237], s[36:37], 0, v[132:133]
	ds_read_b128 v[198:201], v179 offset:32768
	ds_read_b128 v[202:205], v179 offset:33792
	ds_read_b128 v[206:209], v179 offset:34816
	ds_read_b128 v[210:213], v179 offset:35840
	ds_read_b128 v[214:217], v179 offset:36864
	ds_read_b128 v[218:221], v179 offset:37888
	ds_read_b128 v[222:225], v179 offset:38912
	ds_read_b128 v[226:229], v179 offset:39936
	global_load_lds_dwordx4 v[236:237], off
	v_lshl_add_u64 v[236:237], s[36:37], 0, v[136:137]
	s_mov_b32 m0, s65
	s_nop 0
	global_load_lds_dwordx4 v[236:237], off
	s_waitcnt vmcnt(8) lgkmcnt(0)
	s_barrier
	v_mfma_f32_16x16x32_bf16 v[124:127], v[128:131], v[198:201], v[124:127]
	v_mfma_f32_16x16x32_bf16 v[120:123], v[162:165], v[198:201], v[120:123]
	v_mfma_f32_16x16x32_bf16 v[108:111], v[128:131], v[206:209], v[108:111]
	v_mfma_f32_16x16x32_bf16 v[104:107], v[162:165], v[206:209], v[104:107]
	v_mfma_f32_16x16x32_bf16 v[92:95], v[128:131], v[214:217], v[92:95]
	v_mfma_f32_16x16x32_bf16 v[88:91], v[162:165], v[214:217], v[88:91]
	v_mfma_f32_16x16x32_bf16 v[76:79], v[128:131], v[222:225], v[76:79]
	v_mfma_f32_16x16x32_bf16 v[72:75], v[162:165], v[222:225], v[72:75]
	v_mfma_f32_16x16x32_bf16 v[124:127], v[154:157], v[202:205], v[124:127]
	v_mfma_f32_16x16x32_bf16 v[120:123], v[166:169], v[202:205], v[120:123]
	v_mfma_f32_16x16x32_bf16 v[108:111], v[154:157], v[210:213], v[108:111]
	v_mfma_f32_16x16x32_bf16 v[104:107], v[166:169], v[210:213], v[104:107]
	v_mfma_f32_16x16x32_bf16 v[92:95], v[154:157], v[218:221], v[92:95]
	v_mfma_f32_16x16x32_bf16 v[88:91], v[166:169], v[218:221], v[88:91]
	v_mfma_f32_16x16x32_bf16 v[76:79], v[154:157], v[226:229], v[76:79]
	v_mfma_f32_16x16x32_bf16 v[72:75], v[166:169], v[226:229], v[72:75]
	v_mfma_f32_16x16x32_bf16 v[116:119], v[182:185], v[198:201], v[116:119]
	v_mfma_f32_16x16x32_bf16 v[112:115], v[190:193], v[198:201], v[112:115]
	v_mfma_f32_16x16x32_bf16 v[100:103], v[182:185], v[206:209], v[100:103]
	v_mfma_f32_16x16x32_bf16 v[96:99], v[190:193], v[206:209], v[96:99]
	v_mfma_f32_16x16x32_bf16 v[84:87], v[182:185], v[214:217], v[84:87]
	v_mfma_f32_16x16x32_bf16 v[80:83], v[190:193], v[214:217], v[80:83]
	v_mfma_f32_16x16x32_bf16 v[68:71], v[182:185], v[222:225], v[68:71]
	v_mfma_f32_16x16x32_bf16 v[64:67], v[190:193], v[222:225], v[64:67]
	v_mfma_f32_16x16x32_bf16 v[116:119], v[186:189], v[202:205], v[116:119]
	v_mfma_f32_16x16x32_bf16 v[112:115], v[194:197], v[202:205], v[112:115]
	v_mfma_f32_16x16x32_bf16 v[100:103], v[186:189], v[210:213], v[100:103]
	v_mfma_f32_16x16x32_bf16 v[96:99], v[194:197], v[210:213], v[96:99]
	v_mfma_f32_16x16x32_bf16 v[84:87], v[186:189], v[218:221], v[84:87]
	v_mfma_f32_16x16x32_bf16 v[80:83], v[194:197], v[218:221], v[80:83]
	v_mfma_f32_16x16x32_bf16 v[68:71], v[186:189], v[226:229], v[68:71]
	v_mfma_f32_16x16x32_bf16 v[64:67], v[194:197], v[226:229], v[64:67]
	s_barrier
	s_add_i32 s36, s40, s61
	v_lshl_add_u64 v[158:159], v[158:159], 0, s[14:15]
	s_mov_b32 m0, s36
	ds_read_b128 v[198:201], v179 offset:49152
	ds_read_b128 v[202:205], v179 offset:50176
	ds_read_b128 v[206:209], v179 offset:51200
	ds_read_b128 v[210:213], v179 offset:52224
	ds_read_b128 v[214:217], v179 offset:53248
	ds_read_b128 v[218:221], v179 offset:54272
	ds_read_b128 v[222:225], v179 offset:55296
	ds_read_b128 v[226:229], v179 offset:56320
	global_load_lds_dwordx4 v[158:159], off
	s_add_i32 m0, s36, 0x2000
	s_add_u32 s8, s8, 0x40080
	v_lshl_add_u64 v[158:159], v[230:231], 0, s[14:15]
	s_addc_u32 s9, s9, 0
	s_add_i32 s36, s41, s61
	global_load_lds_dwordx4 v[158:159], off
	v_lshl_add_u64 v[158:159], s[8:9], 0, v[134:135]
	s_mov_b32 m0, s36
	s_nop 0
	global_load_lds_dwordx4 v[158:159], off
	v_lshl_add_u64 v[158:159], s[8:9], 0, v[138:139]
	s_add_i32 m0, s36, 0x2000
	s_nop 0
	global_load_lds_dwordx4 v[158:159], off
	v_lshl_add_u64 v[158:159], v[232:233], 0, s[14:15]
	s_mov_b32 m0, s76
	s_nop 0
	global_load_lds_dwordx4 v[158:159], off
	v_lshl_add_u64 v[158:159], v[234:235], 0, s[14:15]
	s_mov_b32 m0, s77
	s_nop 0
	global_load_lds_dwordx4 v[158:159], off
	s_waitcnt vmcnt(8) lgkmcnt(0)
	s_barrier
	v_mfma_f32_16x16x32_bf16 v[60:63], v[128:131], v[198:201], v[60:63]
	v_mfma_f32_16x16x32_bf16 v[56:59], v[162:165], v[198:201], v[56:59]
	v_mfma_f32_16x16x32_bf16 v[44:47], v[128:131], v[206:209], v[44:47]
	v_mfma_f32_16x16x32_bf16 v[40:43], v[162:165], v[206:209], v[40:43]
	v_mfma_f32_16x16x32_bf16 v[28:31], v[128:131], v[214:217], v[28:31]
	v_mfma_f32_16x16x32_bf16 v[24:27], v[162:165], v[214:217], v[24:27]
	v_mfma_f32_16x16x32_bf16 v[12:15], v[128:131], v[222:225], v[12:15]
	v_mfma_f32_16x16x32_bf16 v[8:11], v[162:165], v[222:225], v[8:11]
	v_mfma_f32_16x16x32_bf16 v[60:63], v[154:157], v[202:205], v[60:63]
	v_mfma_f32_16x16x32_bf16 v[56:59], v[166:169], v[202:205], v[56:59]
	v_mfma_f32_16x16x32_bf16 v[44:47], v[154:157], v[210:213], v[44:47]
	v_mfma_f32_16x16x32_bf16 v[40:43], v[166:169], v[210:213], v[40:43]
	v_mfma_f32_16x16x32_bf16 v[28:31], v[154:157], v[218:221], v[28:31]
	v_mfma_f32_16x16x32_bf16 v[24:27], v[166:169], v[218:221], v[24:27]
	v_mfma_f32_16x16x32_bf16 v[12:15], v[154:157], v[226:229], v[12:15]
	v_mfma_f32_16x16x32_bf16 v[8:11], v[166:169], v[226:229], v[8:11]
	v_mfma_f32_16x16x32_bf16 v[52:55], v[182:185], v[198:201], v[52:55]
	v_mfma_f32_16x16x32_bf16 v[48:51], v[190:193], v[198:201], v[48:51]
	v_mfma_f32_16x16x32_bf16 v[36:39], v[182:185], v[206:209], v[36:39]
	v_mfma_f32_16x16x32_bf16 v[32:35], v[190:193], v[206:209], v[32:35]
	v_mfma_f32_16x16x32_bf16 v[20:23], v[182:185], v[214:217], v[20:23]
	v_mfma_f32_16x16x32_bf16 v[16:19], v[190:193], v[214:217], v[16:19]
	v_mfma_f32_16x16x32_bf16 v[4:7], v[182:185], v[222:225], v[4:7]
	v_mfma_f32_16x16x32_bf16 v[0:3], v[190:193], v[222:225], v[0:3]
	v_mfma_f32_16x16x32_bf16 v[52:55], v[186:189], v[202:205], v[52:55]
	v_mfma_f32_16x16x32_bf16 v[48:51], v[194:197], v[202:205], v[48:51]
	v_mfma_f32_16x16x32_bf16 v[36:39], v[186:189], v[210:213], v[36:39]
	v_mfma_f32_16x16x32_bf16 v[32:35], v[194:197], v[210:213], v[32:35]
	v_mfma_f32_16x16x32_bf16 v[20:23], v[186:189], v[218:221], v[20:23]
	v_mfma_f32_16x16x32_bf16 v[16:19], v[194:197], v[218:221], v[16:19]
	v_mfma_f32_16x16x32_bf16 v[4:7], v[186:189], v[226:229], v[4:7]
	v_mfma_f32_16x16x32_bf16 v[0:3], v[194:197], v[226:229], v[0:3]
	s_barrier
	s_add_i32 s39, s39, 2
	s_add_u32 s0, s0, 0x100
	s_addc_u32 s1, s1, 0
	s_add_u32 s33, s33, 0x100
	s_addc_u32 s38, s38, 0
	s_cmp_gt_u32 s39, 13
	s_cbranch_scc0 .LBB0_799

.LBB0_1402:
	s_ashr_i32 s17, s16, 31
	s_lshl_b64 s[18:19], s[16:17], 19
	s_add_u32 s18, s76, s18
	s_addc_u32 s19, s78, s19
	s_and_b64 s[20:21], s[6:7], exec
	s_cselect_b32 s17, s19, s1
	s_cselect_b32 s33, s18, s0
	s_ashr_i32 s15, s14, 31
	s_lshl_b64 s[20:21], s[14:15], 19
	s_add_u32 s20, s31, s20
	s_addc_u32 s21, s34, s21
	s_and_b64 s[28:29], s[6:7], exec
	s_cselect_b32 s15, s21, s27
	s_cselect_b32 s50, s20, s26
	s_add_u32 s0, s0, 0x40080
	s_addc_u32 s1, s1, 0
	s_add_u32 s51, s26, 0x100
	s_addc_u32 s52, s27, 0
	s_mov_b32 s53, -2
	s_waitcnt lgkmcnt(0)
	ds_read_b128 v[128:131], v193
	ds_read_b128 v[132:135], v193 offset:1024
	ds_read_b128 v[136:139], v193 offset:2048
	ds_read_b128 v[140:143], v193 offset:3072
	ds_read_b128 v[144:147], v194
	ds_read_b128 v[148:151], v194 offset:1024
	ds_read_b128 v[152:155], v194 offset:2048
	ds_read_b128 v[156:159], v194 offset:3072
	s_add_u32 s26, s0, 0xfffc0080
	s_addc_u32 s27, s1, -1
	s_cmp_eq_u32 s53, 12
	s_cselect_b32 s29, s17, s27
	s_cselect_b32 s28, s33, s26
	s_cselect_b32 s27, s15, s52
	s_cselect_b32 s26, s50, s51
	v_lshl_add_u64 v[224:225], s[0:1], 0, v[170:171]
	s_add_i32 m0, s23, 0xc000
	ds_read_b128 v[178:181], v195
	ds_read_b128 v[196:199], v195 offset:1024
	ds_read_b128 v[200:203], v195 offset:2048
	ds_read_b128 v[204:207], v195 offset:3072
	ds_read_b128 v[208:211], v195 offset:4096
	ds_read_b128 v[212:215], v195 offset:5120
	ds_read_b128 v[216:219], v195 offset:6144
	ds_read_b128 v[220:223], v195 offset:7168
	global_load_lds_dwordx4 v[224:225], off
	v_lshl_add_u64 v[224:225], s[0:1], 0, v[172:173]
	s_add_i32 m0, s23, 0xe000
	s_nop 0
	global_load_lds_dwordx4 v[224:225], off
	s_waitcnt vmcnt(8) lgkmcnt(0)
	s_barrier
	v_mfma_f32_16x16x32_bf16 v[124:127], v[128:131], v[178:181], 0
	v_mfma_f32_16x16x32_bf16 v[120:123], v[136:139], v[178:181], 0
	v_mfma_f32_16x16x32_bf16 v[108:111], v[128:131], v[200:203], 0
	v_mfma_f32_16x16x32_bf16 v[104:107], v[136:139], v[200:203], 0
	v_mfma_f32_16x16x32_bf16 v[92:95], v[128:131], v[208:211], 0
	v_mfma_f32_16x16x32_bf16 v[88:91], v[136:139], v[208:211], 0
	v_mfma_f32_16x16x32_bf16 v[76:79], v[128:131], v[216:219], 0
	v_mfma_f32_16x16x32_bf16 v[72:75], v[136:139], v[216:219], 0
	v_mfma_f32_16x16x32_bf16 v[124:127], v[132:135], v[196:199], v[124:127]
	v_mfma_f32_16x16x32_bf16 v[120:123], v[140:143], v[196:199], v[120:123]
	v_mfma_f32_16x16x32_bf16 v[108:111], v[132:135], v[204:207], v[108:111]
	v_mfma_f32_16x16x32_bf16 v[104:107], v[140:143], v[204:207], v[104:107]
	v_mfma_f32_16x16x32_bf16 v[92:95], v[132:135], v[212:215], v[92:95]
	v_mfma_f32_16x16x32_bf16 v[88:91], v[140:143], v[212:215], v[88:91]
	v_mfma_f32_16x16x32_bf16 v[76:79], v[132:135], v[220:223], v[76:79]
	v_mfma_f32_16x16x32_bf16 v[72:75], v[140:143], v[220:223], v[72:75]
	v_mfma_f32_16x16x32_bf16 v[116:119], v[144:147], v[178:181], 0
	v_mfma_f32_16x16x32_bf16 v[112:115], v[152:155], v[178:181], 0
	v_mfma_f32_16x16x32_bf16 v[100:103], v[144:147], v[200:203], 0
	v_mfma_f32_16x16x32_bf16 v[96:99], v[152:155], v[200:203], 0
	v_mfma_f32_16x16x32_bf16 v[84:87], v[144:147], v[208:211], 0
	v_mfma_f32_16x16x32_bf16 v[80:83], v[152:155], v[208:211], 0
	v_mfma_f32_16x16x32_bf16 v[68:71], v[144:147], v[216:219], 0
	v_mfma_f32_16x16x32_bf16 v[64:67], v[152:155], v[216:219], 0
	v_mfma_f32_16x16x32_bf16 v[116:119], v[148:151], v[196:199], v[116:119]
	v_mfma_f32_16x16x32_bf16 v[112:115], v[156:159], v[196:199], v[112:115]
	v_mfma_f32_16x16x32_bf16 v[100:103], v[148:151], v[204:207], v[100:103]
	v_mfma_f32_16x16x32_bf16 v[96:99], v[156:159], v[204:207], v[96:99]
	v_mfma_f32_16x16x32_bf16 v[84:87], v[148:151], v[212:215], v[84:87]
	v_mfma_f32_16x16x32_bf16 v[80:83], v[156:159], v[212:215], v[80:83]
	v_mfma_f32_16x16x32_bf16 v[68:71], v[148:151], v[220:223], v[68:71]
	v_mfma_f32_16x16x32_bf16 v[64:67], v[156:159], v[220:223], v[64:67]
	s_barrier
	s_add_i32 s54, s44, s35
	v_lshl_add_u64 v[224:225], s[26:27], 0, v[164:165]
	s_mov_b32 m0, s54
	ds_read_b128 v[178:181], v195 offset:16384
	ds_read_b128 v[196:199], v195 offset:17408
	ds_read_b128 v[200:203], v195 offset:18432
	ds_read_b128 v[204:207], v195 offset:19456
	ds_read_b128 v[208:211], v195 offset:20480
	ds_read_b128 v[212:215], v195 offset:21504
	ds_read_b128 v[216:219], v195 offset:22528
	ds_read_b128 v[220:223], v195 offset:23552
	global_load_lds_dwordx4 v[224:225], off
	s_add_i32 m0, s54, 0x2000
	s_add_u32 s54, s26, 0x40000
	v_lshl_add_u64 v[226:227], s[26:27], 0, v[168:169]
	s_addc_u32 s55, s27, 0
	s_add_i32 s56, s45, s35
	global_load_lds_dwordx4 v[226:227], off
	v_lshl_add_u64 v[228:229], s[54:55], 0, v[164:165]
	s_mov_b32 m0, s56
	v_lshl_add_u64 v[230:231], s[28:29], 0, v[166:167]
	global_load_lds_dwordx4 v[228:229], off
	v_lshl_add_u64 v[228:229], s[54:55], 0, v[168:169]
	s_add_i32 m0, s56, 0x2000
	s_nop 0
	global_load_lds_dwordx4 v[228:229], off
	v_lshl_add_u64 v[228:229], s[28:29], 0, v[162:163]
	s_mov_b32 m0, s23
	s_nop 0
	global_load_lds_dwordx4 v[228:229], off
	s_mov_b32 m0, s25
	s_nop 0
	global_load_lds_dwordx4 v[230:231], off
	s_waitcnt vmcnt(8) lgkmcnt(0)
	s_barrier
	v_mfma_f32_16x16x32_bf16 v[60:63], v[128:131], v[178:181], 0
	v_mfma_f32_16x16x32_bf16 v[56:59], v[136:139], v[178:181], 0
	v_mfma_f32_16x16x32_bf16 v[44:47], v[128:131], v[200:203], 0
	v_mfma_f32_16x16x32_bf16 v[40:43], v[136:139], v[200:203], 0
	v_mfma_f32_16x16x32_bf16 v[28:31], v[128:131], v[208:211], 0
	v_mfma_f32_16x16x32_bf16 v[24:27], v[136:139], v[208:211], 0
	v_mfma_f32_16x16x32_bf16 v[12:15], v[128:131], v[216:219], 0
	v_mfma_f32_16x16x32_bf16 v[8:11], v[136:139], v[216:219], 0
	v_mfma_f32_16x16x32_bf16 v[60:63], v[132:135], v[196:199], v[60:63]
	v_mfma_f32_16x16x32_bf16 v[56:59], v[140:143], v[196:199], v[56:59]
	v_mfma_f32_16x16x32_bf16 v[44:47], v[132:135], v[204:207], v[44:47]
	v_mfma_f32_16x16x32_bf16 v[40:43], v[140:143], v[204:207], v[40:43]
	v_mfma_f32_16x16x32_bf16 v[28:31], v[132:135], v[212:215], v[28:31]
	v_mfma_f32_16x16x32_bf16 v[24:27], v[140:143], v[212:215], v[24:27]
	v_mfma_f32_16x16x32_bf16 v[12:15], v[132:135], v[220:223], v[12:15]
	v_mfma_f32_16x16x32_bf16 v[8:11], v[140:143], v[220:223], v[8:11]
	v_mfma_f32_16x16x32_bf16 v[52:55], v[144:147], v[178:181], 0
	v_mfma_f32_16x16x32_bf16 v[48:51], v[152:155], v[178:181], 0
	v_mfma_f32_16x16x32_bf16 v[36:39], v[144:147], v[200:203], 0
	v_mfma_f32_16x16x32_bf16 v[32:35], v[152:155], v[200:203], 0
	v_mfma_f32_16x16x32_bf16 v[20:23], v[144:147], v[208:211], 0
	v_mfma_f32_16x16x32_bf16 v[16:19], v[152:155], v[208:211], 0
	v_mfma_f32_16x16x32_bf16 v[4:7], v[144:147], v[216:219], 0
	v_mfma_f32_16x16x32_bf16 v[0:3], v[152:155], v[216:219], 0
	v_mfma_f32_16x16x32_bf16 v[52:55], v[148:151], v[196:199], v[52:55]
	v_mfma_f32_16x16x32_bf16 v[48:51], v[156:159], v[196:199], v[48:51]
	v_mfma_f32_16x16x32_bf16 v[36:39], v[148:151], v[204:207], v[36:39]
	v_mfma_f32_16x16x32_bf16 v[32:35], v[156:159], v[204:207], v[32:35]
	v_mfma_f32_16x16x32_bf16 v[20:23], v[148:151], v[212:215], v[20:23]
	v_mfma_f32_16x16x32_bf16 v[16:19], v[156:159], v[212:215], v[16:19]
	v_mfma_f32_16x16x32_bf16 v[4:7], v[148:151], v[220:223], v[4:7]
	v_mfma_f32_16x16x32_bf16 v[0:3], v[156:159], v[220:223], v[0:3]
	s_barrier
	s_add_i32 s54, 0, 0x18000
	s_add_i32 s55, 0, 0x1c000
	v_add_u32_e32 v140, s54, v188
	v_add_u32_e32 v156, s55, v188
	ds_read_b128 v[128:131], v140
	ds_read_b128 v[132:135], v140 offset:1024
	ds_read_b128 v[136:139], v140 offset:2048
	ds_read_b128 v[140:143], v140 offset:3072
	ds_read_b128 v[144:147], v156
	ds_read_b128 v[148:151], v156 offset:1024
	ds_read_b128 v[152:155], v156 offset:2048
	ds_read_b128 v[156:159], v156 offset:3072
	s_add_u32 s28, s28, 0x40000
	s_addc_u32 s29, s29, 0
	s_mov_b32 m0, s36
	v_lshl_add_u64 v[232:233], s[28:29], 0, v[162:163]
	ds_read_b128 v[178:181], v195 offset:32768
	ds_read_b128 v[196:199], v195 offset:33792
	ds_read_b128 v[200:203], v195 offset:34816
	ds_read_b128 v[204:207], v195 offset:35840
	ds_read_b128 v[208:211], v195 offset:36864
	ds_read_b128 v[212:215], v195 offset:37888
	ds_read_b128 v[216:219], v195 offset:38912
	ds_read_b128 v[220:223], v195 offset:39936
	global_load_lds_dwordx4 v[232:233], off
	v_lshl_add_u64 v[232:233], s[28:29], 0, v[166:167]
	s_mov_b32 m0, s37
	s_nop 0
	global_load_lds_dwordx4 v[232:233], off
	s_waitcnt vmcnt(8) lgkmcnt(0)
	s_barrier
	v_mfma_f32_16x16x32_bf16 v[124:127], v[128:131], v[178:181], v[124:127]
	v_mfma_f32_16x16x32_bf16 v[120:123], v[136:139], v[178:181], v[120:123]
	v_mfma_f32_16x16x32_bf16 v[108:111], v[128:131], v[200:203], v[108:111]
	v_mfma_f32_16x16x32_bf16 v[104:107], v[136:139], v[200:203], v[104:107]
	v_mfma_f32_16x16x32_bf16 v[92:95], v[128:131], v[208:211], v[92:95]
	v_mfma_f32_16x16x32_bf16 v[88:91], v[136:139], v[208:211], v[88:91]
	v_mfma_f32_16x16x32_bf16 v[76:79], v[128:131], v[216:219], v[76:79]
	v_mfma_f32_16x16x32_bf16 v[72:75], v[136:139], v[216:219], v[72:75]
	v_mfma_f32_16x16x32_bf16 v[124:127], v[132:135], v[196:199], v[124:127]
	v_mfma_f32_16x16x32_bf16 v[120:123], v[140:143], v[196:199], v[120:123]
	v_mfma_f32_16x16x32_bf16 v[108:111], v[132:135], v[204:207], v[108:111]
	v_mfma_f32_16x16x32_bf16 v[104:107], v[140:143], v[204:207], v[104:107]
	v_mfma_f32_16x16x32_bf16 v[92:95], v[132:135], v[212:215], v[92:95]
	v_mfma_f32_16x16x32_bf16 v[88:91], v[140:143], v[212:215], v[88:91]
	v_mfma_f32_16x16x32_bf16 v[76:79], v[132:135], v[220:223], v[76:79]
	v_mfma_f32_16x16x32_bf16 v[72:75], v[140:143], v[220:223], v[72:75]
	v_mfma_f32_16x16x32_bf16 v[116:119], v[144:147], v[178:181], v[116:119]
	v_mfma_f32_16x16x32_bf16 v[112:115], v[152:155], v[178:181], v[112:115]
	v_mfma_f32_16x16x32_bf16 v[100:103], v[144:147], v[200:203], v[100:103]
	v_mfma_f32_16x16x32_bf16 v[96:99], v[152:155], v[200:203], v[96:99]
	v_mfma_f32_16x16x32_bf16 v[84:87], v[144:147], v[208:211], v[84:87]
	v_mfma_f32_16x16x32_bf16 v[80:83], v[152:155], v[208:211], v[80:83]
	v_mfma_f32_16x16x32_bf16 v[68:71], v[144:147], v[216:219], v[68:71]
	v_mfma_f32_16x16x32_bf16 v[64:67], v[152:155], v[216:219], v[64:67]
	v_mfma_f32_16x16x32_bf16 v[116:119], v[148:151], v[196:199], v[116:119]
	v_mfma_f32_16x16x32_bf16 v[112:115], v[156:159], v[196:199], v[112:115]
	v_mfma_f32_16x16x32_bf16 v[100:103], v[148:151], v[204:207], v[100:103]
	v_mfma_f32_16x16x32_bf16 v[96:99], v[156:159], v[204:207], v[96:99]
	v_mfma_f32_16x16x32_bf16 v[84:87], v[148:151], v[212:215], v[84:87]
	v_mfma_f32_16x16x32_bf16 v[80:83], v[156:159], v[212:215], v[80:83]
	v_mfma_f32_16x16x32_bf16 v[68:71], v[148:151], v[220:223], v[68:71]
	v_mfma_f32_16x16x32_bf16 v[64:67], v[156:159], v[220:223], v[64:67]
	s_barrier
	s_add_i32 s28, s54, s35
	v_lshl_add_u64 v[224:225], v[224:225], 0, s[10:11]
	s_mov_b32 m0, s28
	ds_read_b128 v[178:181], v195 offset:49152
	ds_read_b128 v[196:199], v195 offset:50176
	ds_read_b128 v[200:203], v195 offset:51200
	ds_read_b128 v[204:207], v195 offset:52224
	ds_read_b128 v[208:211], v195 offset:53248
	ds_read_b128 v[212:215], v195 offset:54272
	ds_read_b128 v[216:219], v195 offset:55296
	ds_read_b128 v[220:223], v195 offset:56320
	global_load_lds_dwordx4 v[224:225], off
	s_add_i32 m0, s28, 0x2000
	s_add_u32 s26, s26, 0x40080
	v_lshl_add_u64 v[224:225], v[226:227], 0, s[10:11]
	s_addc_u32 s27, s27, 0
	s_add_i32 s28, s55, s35
	global_load_lds_dwordx4 v[224:225], off
	v_lshl_add_u64 v[224:225], s[26:27], 0, v[164:165]
	s_mov_b32 m0, s28
	s_nop 0
	global_load_lds_dwordx4 v[224:225], off
	v_lshl_add_u64 v[224:225], s[26:27], 0, v[168:169]
	s_add_i32 m0, s28, 0x2000
	s_nop 0
	global_load_lds_dwordx4 v[224:225], off
	v_lshl_add_u64 v[224:225], v[228:229], 0, s[10:11]
	s_mov_b32 m0, s40
	s_nop 0
	global_load_lds_dwordx4 v[224:225], off
	v_lshl_add_u64 v[224:225], v[230:231], 0, s[10:11]
	s_mov_b32 m0, s41
	s_nop 0
	global_load_lds_dwordx4 v[224:225], off
	s_waitcnt vmcnt(8) lgkmcnt(0)
	s_barrier
	v_mfma_f32_16x16x32_bf16 v[60:63], v[128:131], v[178:181], v[60:63]
	v_mfma_f32_16x16x32_bf16 v[56:59], v[136:139], v[178:181], v[56:59]
	v_mfma_f32_16x16x32_bf16 v[44:47], v[128:131], v[200:203], v[44:47]
	v_mfma_f32_16x16x32_bf16 v[40:43], v[136:139], v[200:203], v[40:43]
	v_mfma_f32_16x16x32_bf16 v[28:31], v[128:131], v[208:211], v[28:31]
	v_mfma_f32_16x16x32_bf16 v[24:27], v[136:139], v[208:211], v[24:27]
	v_mfma_f32_16x16x32_bf16 v[12:15], v[128:131], v[216:219], v[12:15]
	v_mfma_f32_16x16x32_bf16 v[8:11], v[136:139], v[216:219], v[8:11]
	v_mfma_f32_16x16x32_bf16 v[60:63], v[132:135], v[196:199], v[60:63]
	v_mfma_f32_16x16x32_bf16 v[56:59], v[140:143], v[196:199], v[56:59]
	v_mfma_f32_16x16x32_bf16 v[44:47], v[132:135], v[204:207], v[44:47]
	v_mfma_f32_16x16x32_bf16 v[40:43], v[140:143], v[204:207], v[40:43]
	v_mfma_f32_16x16x32_bf16 v[28:31], v[132:135], v[212:215], v[28:31]
	v_mfma_f32_16x16x32_bf16 v[24:27], v[140:143], v[212:215], v[24:27]
	v_mfma_f32_16x16x32_bf16 v[12:15], v[132:135], v[220:223], v[12:15]
	v_mfma_f32_16x16x32_bf16 v[8:11], v[140:143], v[220:223], v[8:11]
	v_mfma_f32_16x16x32_bf16 v[52:55], v[144:147], v[178:181], v[52:55]
	v_mfma_f32_16x16x32_bf16 v[48:51], v[152:155], v[178:181], v[48:51]
	v_mfma_f32_16x16x32_bf16 v[36:39], v[144:147], v[200:203], v[36:39]
	v_mfma_f32_16x16x32_bf16 v[32:35], v[152:155], v[200:203], v[32:35]
	v_mfma_f32_16x16x32_bf16 v[20:23], v[144:147], v[208:211], v[20:23]
	v_mfma_f32_16x16x32_bf16 v[16:19], v[152:155], v[208:211], v[16:19]
	v_mfma_f32_16x16x32_bf16 v[4:7], v[144:147], v[216:219], v[4:7]
	v_mfma_f32_16x16x32_bf16 v[0:3], v[152:155], v[216:219], v[0:3]
	v_mfma_f32_16x16x32_bf16 v[52:55], v[148:151], v[196:199], v[52:55]
	v_mfma_f32_16x16x32_bf16 v[48:51], v[156:159], v[196:199], v[48:51]
	v_mfma_f32_16x16x32_bf16 v[36:39], v[148:151], v[204:207], v[36:39]
	v_mfma_f32_16x16x32_bf16 v[32:35], v[156:159], v[204:207], v[32:35]
	v_mfma_f32_16x16x32_bf16 v[20:23], v[148:151], v[212:215], v[20:23]
	v_mfma_f32_16x16x32_bf16 v[16:19], v[156:159], v[212:215], v[16:19]
	v_mfma_f32_16x16x32_bf16 v[4:7], v[148:151], v[220:223], v[4:7]
	v_mfma_f32_16x16x32_bf16 v[0:3], v[156:159], v[220:223], v[0:3]
	s_barrier
	s_add_i32 s53, s53, 2
	s_add_u32 s0, s0, 0x100
	s_addc_u32 s1, s1, 0
	s_add_u32 s51, s51, 0x100
	s_addc_u32 s52, s52, 0
	s_cmp_gt_u32 s53, 13
	s_cbranch_scc0 .LBB0_1403
	s_branch .Lpeel_exit_6
.LBB0_1403:
	ds_read_b128 v[128:131], v193
	ds_read_b128 v[132:135], v193 offset:1024
	ds_read_b128 v[136:139], v193 offset:2048
	ds_read_b128 v[140:143], v193 offset:3072
	ds_read_b128 v[144:147], v194
	ds_read_b128 v[148:151], v194 offset:1024
	ds_read_b128 v[152:155], v194 offset:2048
	ds_read_b128 v[156:159], v194 offset:3072
	s_add_u32 s26, s0, 0xfffc0080
	s_addc_u32 s27, s1, -1
	s_cmp_eq_u32 s53, 12
	s_cselect_b32 s29, s17, s27
	s_cselect_b32 s28, s33, s26
	s_cselect_b32 s27, s15, s52
	s_cselect_b32 s26, s50, s51
	v_lshl_add_u64 v[224:225], s[0:1], 0, v[170:171]
	s_add_i32 m0, s23, 0xc000
	ds_read_b128 v[178:181], v195
	ds_read_b128 v[196:199], v195 offset:1024
	ds_read_b128 v[200:203], v195 offset:2048
	ds_read_b128 v[204:207], v195 offset:3072
	ds_read_b128 v[208:211], v195 offset:4096
	ds_read_b128 v[212:215], v195 offset:5120
	ds_read_b128 v[216:219], v195 offset:6144
	ds_read_b128 v[220:223], v195 offset:7168
	global_load_lds_dwordx4 v[224:225], off
	v_lshl_add_u64 v[224:225], s[0:1], 0, v[172:173]
	s_add_i32 m0, s23, 0xe000
	s_nop 0
	global_load_lds_dwordx4 v[224:225], off
	s_waitcnt vmcnt(8) lgkmcnt(0)
	s_barrier
	v_mfma_f32_16x16x32_bf16 v[124:127], v[128:131], v[178:181], v[124:127]
	v_mfma_f32_16x16x32_bf16 v[120:123], v[136:139], v[178:181], v[120:123]
	v_mfma_f32_16x16x32_bf16 v[108:111], v[128:131], v[200:203], v[108:111]
	v_mfma_f32_16x16x32_bf16 v[104:107], v[136:139], v[200:203], v[104:107]
	v_mfma_f32_16x16x32_bf16 v[92:95], v[128:131], v[208:211], v[92:95]
	v_mfma_f32_16x16x32_bf16 v[88:91], v[136:139], v[208:211], v[88:91]
	v_mfma_f32_16x16x32_bf16 v[76:79], v[128:131], v[216:219], v[76:79]
	v_mfma_f32_16x16x32_bf16 v[72:75], v[136:139], v[216:219], v[72:75]
	v_mfma_f32_16x16x32_bf16 v[124:127], v[132:135], v[196:199], v[124:127]
	v_mfma_f32_16x16x32_bf16 v[120:123], v[140:143], v[196:199], v[120:123]
	v_mfma_f32_16x16x32_bf16 v[108:111], v[132:135], v[204:207], v[108:111]
	v_mfma_f32_16x16x32_bf16 v[104:107], v[140:143], v[204:207], v[104:107]
	v_mfma_f32_16x16x32_bf16 v[92:95], v[132:135], v[212:215], v[92:95]
	v_mfma_f32_16x16x32_bf16 v[88:91], v[140:143], v[212:215], v[88:91]
	v_mfma_f32_16x16x32_bf16 v[76:79], v[132:135], v[220:223], v[76:79]
	v_mfma_f32_16x16x32_bf16 v[72:75], v[140:143], v[220:223], v[72:75]
	v_mfma_f32_16x16x32_bf16 v[116:119], v[144:147], v[178:181], v[116:119]
	v_mfma_f32_16x16x32_bf16 v[112:115], v[152:155], v[178:181], v[112:115]
	v_mfma_f32_16x16x32_bf16 v[100:103], v[144:147], v[200:203], v[100:103]
	v_mfma_f32_16x16x32_bf16 v[96:99], v[152:155], v[200:203], v[96:99]
	v_mfma_f32_16x16x32_bf16 v[84:87], v[144:147], v[208:211], v[84:87]
	v_mfma_f32_16x16x32_bf16 v[80:83], v[152:155], v[208:211], v[80:83]
	v_mfma_f32_16x16x32_bf16 v[68:71], v[144:147], v[216:219], v[68:71]
	v_mfma_f32_16x16x32_bf16 v[64:67], v[152:155], v[216:219], v[64:67]
	v_mfma_f32_16x16x32_bf16 v[116:119], v[148:151], v[196:199], v[116:119]
	v_mfma_f32_16x16x32_bf16 v[112:115], v[156:159], v[196:199], v[112:115]
	v_mfma_f32_16x16x32_bf16 v[100:103], v[148:151], v[204:207], v[100:103]
	v_mfma_f32_16x16x32_bf16 v[96:99], v[156:159], v[204:207], v[96:99]
	v_mfma_f32_16x16x32_bf16 v[84:87], v[148:151], v[212:215], v[84:87]
	v_mfma_f32_16x16x32_bf16 v[80:83], v[156:159], v[212:215], v[80:83]
	v_mfma_f32_16x16x32_bf16 v[68:71], v[148:151], v[220:223], v[68:71]
	v_mfma_f32_16x16x32_bf16 v[64:67], v[156:159], v[220:223], v[64:67]
	s_barrier
	s_add_i32 s54, s44, s35
	v_lshl_add_u64 v[224:225], s[26:27], 0, v[164:165]
	s_mov_b32 m0, s54
	ds_read_b128 v[178:181], v195 offset:16384
	ds_read_b128 v[196:199], v195 offset:17408
	ds_read_b128 v[200:203], v195 offset:18432
	ds_read_b128 v[204:207], v195 offset:19456
	ds_read_b128 v[208:211], v195 offset:20480
	ds_read_b128 v[212:215], v195 offset:21504
	ds_read_b128 v[216:219], v195 offset:22528
	ds_read_b128 v[220:223], v195 offset:23552
	global_load_lds_dwordx4 v[224:225], off
	s_add_i32 m0, s54, 0x2000
	s_add_u32 s54, s26, 0x40000
	v_lshl_add_u64 v[226:227], s[26:27], 0, v[168:169]
	s_addc_u32 s55, s27, 0
	s_add_i32 s56, s45, s35
	global_load_lds_dwordx4 v[226:227], off
	v_lshl_add_u64 v[228:229], s[54:55], 0, v[164:165]
	s_mov_b32 m0, s56
	v_lshl_add_u64 v[230:231], s[28:29], 0, v[166:167]
	global_load_lds_dwordx4 v[228:229], off
	v_lshl_add_u64 v[228:229], s[54:55], 0, v[168:169]
	s_add_i32 m0, s56, 0x2000
	s_nop 0
	global_load_lds_dwordx4 v[228:229], off
	v_lshl_add_u64 v[228:229], s[28:29], 0, v[162:163]
	s_mov_b32 m0, s23
	s_nop 0
	global_load_lds_dwordx4 v[228:229], off
	s_mov_b32 m0, s25
	s_nop 0
	global_load_lds_dwordx4 v[230:231], off
	s_waitcnt vmcnt(8) lgkmcnt(0)
	s_barrier
	v_mfma_f32_16x16x32_bf16 v[60:63], v[128:131], v[178:181], v[60:63]
	v_mfma_f32_16x16x32_bf16 v[56:59], v[136:139], v[178:181], v[56:59]
	v_mfma_f32_16x16x32_bf16 v[44:47], v[128:131], v[200:203], v[44:47]
	v_mfma_f32_16x16x32_bf16 v[40:43], v[136:139], v[200:203], v[40:43]
	v_mfma_f32_16x16x32_bf16 v[28:31], v[128:131], v[208:211], v[28:31]
	v_mfma_f32_16x16x32_bf16 v[24:27], v[136:139], v[208:211], v[24:27]
	v_mfma_f32_16x16x32_bf16 v[12:15], v[128:131], v[216:219], v[12:15]
	v_mfma_f32_16x16x32_bf16 v[8:11], v[136:139], v[216:219], v[8:11]
	v_mfma_f32_16x16x32_bf16 v[60:63], v[132:135], v[196:199], v[60:63]
	v_mfma_f32_16x16x32_bf16 v[56:59], v[140:143], v[196:199], v[56:59]
	v_mfma_f32_16x16x32_bf16 v[44:47], v[132:135], v[204:207], v[44:47]
	v_mfma_f32_16x16x32_bf16 v[40:43], v[140:143], v[204:207], v[40:43]
	v_mfma_f32_16x16x32_bf16 v[28:31], v[132:135], v[212:215], v[28:31]
	v_mfma_f32_16x16x32_bf16 v[24:27], v[140:143], v[212:215], v[24:27]
	v_mfma_f32_16x16x32_bf16 v[12:15], v[132:135], v[220:223], v[12:15]
	v_mfma_f32_16x16x32_bf16 v[8:11], v[140:143], v[220:223], v[8:11]
	v_mfma_f32_16x16x32_bf16 v[52:55], v[144:147], v[178:181], v[52:55]
	v_mfma_f32_16x16x32_bf16 v[48:51], v[152:155], v[178:181], v[48:51]
	v_mfma_f32_16x16x32_bf16 v[36:39], v[144:147], v[200:203], v[36:39]
	v_mfma_f32_16x16x32_bf16 v[32:35], v[152:155], v[200:203], v[32:35]
	v_mfma_f32_16x16x32_bf16 v[20:23], v[144:147], v[208:211], v[20:23]
	v_mfma_f32_16x16x32_bf16 v[16:19], v[152:155], v[208:211], v[16:19]
	v_mfma_f32_16x16x32_bf16 v[4:7], v[144:147], v[216:219], v[4:7]
	v_mfma_f32_16x16x32_bf16 v[0:3], v[152:155], v[216:219], v[0:3]
	v_mfma_f32_16x16x32_bf16 v[52:55], v[148:151], v[196:199], v[52:55]
	v_mfma_f32_16x16x32_bf16 v[48:51], v[156:159], v[196:199], v[48:51]
	v_mfma_f32_16x16x32_bf16 v[36:39], v[148:151], v[204:207], v[36:39]
	v_mfma_f32_16x16x32_bf16 v[32:35], v[156:159], v[204:207], v[32:35]
	v_mfma_f32_16x16x32_bf16 v[20:23], v[148:151], v[212:215], v[20:23]
	v_mfma_f32_16x16x32_bf16 v[16:19], v[156:159], v[212:215], v[16:19]
	v_mfma_f32_16x16x32_bf16 v[4:7], v[148:151], v[220:223], v[4:7]
	v_mfma_f32_16x16x32_bf16 v[0:3], v[156:159], v[220:223], v[0:3]
	s_barrier
	s_add_i32 s54, 0, 0x18000
	s_add_i32 s55, 0, 0x1c000
	v_add_u32_e32 v140, s54, v188
	v_add_u32_e32 v156, s55, v188
	ds_read_b128 v[128:131], v140
	ds_read_b128 v[132:135], v140 offset:1024
	ds_read_b128 v[136:139], v140 offset:2048
	ds_read_b128 v[140:143], v140 offset:3072
	ds_read_b128 v[144:147], v156
	ds_read_b128 v[148:151], v156 offset:1024
	ds_read_b128 v[152:155], v156 offset:2048
	ds_read_b128 v[156:159], v156 offset:3072
	s_add_u32 s28, s28, 0x40000
	s_addc_u32 s29, s29, 0
	s_mov_b32 m0, s36
	v_lshl_add_u64 v[232:233], s[28:29], 0, v[162:163]
	ds_read_b128 v[178:181], v195 offset:32768
	ds_read_b128 v[196:199], v195 offset:33792
	ds_read_b128 v[200:203], v195 offset:34816
	ds_read_b128 v[204:207], v195 offset:35840
	ds_read_b128 v[208:211], v195 offset:36864
	ds_read_b128 v[212:215], v195 offset:37888
	ds_read_b128 v[216:219], v195 offset:38912
	ds_read_b128 v[220:223], v195 offset:39936
	global_load_lds_dwordx4 v[232:233], off
	v_lshl_add_u64 v[232:233], s[28:29], 0, v[166:167]
	s_mov_b32 m0, s37
	s_nop 0
	global_load_lds_dwordx4 v[232:233], off
	s_waitcnt vmcnt(8) lgkmcnt(0)
	s_barrier
	v_mfma_f32_16x16x32_bf16 v[124:127], v[128:131], v[178:181], v[124:127]
	v_mfma_f32_16x16x32_bf16 v[120:123], v[136:139], v[178:181], v[120:123]
	v_mfma_f32_16x16x32_bf16 v[108:111], v[128:131], v[200:203], v[108:111]
	v_mfma_f32_16x16x32_bf16 v[104:107], v[136:139], v[200:203], v[104:107]
	v_mfma_f32_16x16x32_bf16 v[92:95], v[128:131], v[208:211], v[92:95]
	v_mfma_f32_16x16x32_bf16 v[88:91], v[136:139], v[208:211], v[88:91]
	v_mfma_f32_16x16x32_bf16 v[76:79], v[128:131], v[216:219], v[76:79]
	v_mfma_f32_16x16x32_bf16 v[72:75], v[136:139], v[216:219], v[72:75]
	v_mfma_f32_16x16x32_bf16 v[124:127], v[132:135], v[196:199], v[124:127]
	v_mfma_f32_16x16x32_bf16 v[120:123], v[140:143], v[196:199], v[120:123]
	v_mfma_f32_16x16x32_bf16 v[108:111], v[132:135], v[204:207], v[108:111]
	v_mfma_f32_16x16x32_bf16 v[104:107], v[140:143], v[204:207], v[104:107]
	v_mfma_f32_16x16x32_bf16 v[92:95], v[132:135], v[212:215], v[92:95]
	v_mfma_f32_16x16x32_bf16 v[88:91], v[140:143], v[212:215], v[88:91]
	v_mfma_f32_16x16x32_bf16 v[76:79], v[132:135], v[220:223], v[76:79]
	v_mfma_f32_16x16x32_bf16 v[72:75], v[140:143], v[220:223], v[72:75]
	v_mfma_f32_16x16x32_bf16 v[116:119], v[144:147], v[178:181], v[116:119]
	v_mfma_f32_16x16x32_bf16 v[112:115], v[152:155], v[178:181], v[112:115]
	v_mfma_f32_16x16x32_bf16 v[100:103], v[144:147], v[200:203], v[100:103]
	v_mfma_f32_16x16x32_bf16 v[96:99], v[152:155], v[200:203], v[96:99]
	v_mfma_f32_16x16x32_bf16 v[84:87], v[144:147], v[208:211], v[84:87]
	v_mfma_f32_16x16x32_bf16 v[80:83], v[152:155], v[208:211], v[80:83]
	v_mfma_f32_16x16x32_bf16 v[68:71], v[144:147], v[216:219], v[68:71]
	v_mfma_f32_16x16x32_bf16 v[64:67], v[152:155], v[216:219], v[64:67]
	v_mfma_f32_16x16x32_bf16 v[116:119], v[148:151], v[196:199], v[116:119]
	v_mfma_f32_16x16x32_bf16 v[112:115], v[156:159], v[196:199], v[112:115]
	v_mfma_f32_16x16x32_bf16 v[100:103], v[148:151], v[204:207], v[100:103]
	v_mfma_f32_16x16x32_bf16 v[96:99], v[156:159], v[204:207], v[96:99]
	v_mfma_f32_16x16x32_bf16 v[84:87], v[148:151], v[212:215], v[84:87]
	v_mfma_f32_16x16x32_bf16 v[80:83], v[156:159], v[212:215], v[80:83]
	v_mfma_f32_16x16x32_bf16 v[68:71], v[148:151], v[220:223], v[68:71]
	v_mfma_f32_16x16x32_bf16 v[64:67], v[156:159], v[220:223], v[64:67]
	s_barrier
	s_add_i32 s28, s54, s35
	v_lshl_add_u64 v[224:225], v[224:225], 0, s[10:11]
	s_mov_b32 m0, s28
	ds_read_b128 v[178:181], v195 offset:49152
	ds_read_b128 v[196:199], v195 offset:50176
	ds_read_b128 v[200:203], v195 offset:51200
	ds_read_b128 v[204:207], v195 offset:52224
	ds_read_b128 v[208:211], v195 offset:53248
	ds_read_b128 v[212:215], v195 offset:54272
	ds_read_b128 v[216:219], v195 offset:55296
	ds_read_b128 v[220:223], v195 offset:56320
	global_load_lds_dwordx4 v[224:225], off
	s_add_i32 m0, s28, 0x2000
	s_add_u32 s26, s26, 0x40080
	v_lshl_add_u64 v[224:225], v[226:227], 0, s[10:11]
	s_addc_u32 s27, s27, 0
	s_add_i32 s28, s55, s35
	global_load_lds_dwordx4 v[224:225], off
	v_lshl_add_u64 v[224:225], s[26:27], 0, v[164:165]
	s_mov_b32 m0, s28
	s_nop 0
	global_load_lds_dwordx4 v[224:225], off
	v_lshl_add_u64 v[224:225], s[26:27], 0, v[168:169]
	s_add_i32 m0, s28, 0x2000
	s_nop 0
	global_load_lds_dwordx4 v[224:225], off
	v_lshl_add_u64 v[224:225], v[228:229], 0, s[10:11]
	s_mov_b32 m0, s40
	s_nop 0
	global_load_lds_dwordx4 v[224:225], off
	v_lshl_add_u64 v[224:225], v[230:231], 0, s[10:11]
	s_mov_b32 m0, s41
	s_nop 0
	global_load_lds_dwordx4 v[224:225], off
	s_waitcnt vmcnt(8) lgkmcnt(0)
	s_barrier
	v_mfma_f32_16x16x32_bf16 v[60:63], v[128:131], v[178:181], v[60:63]
	v_mfma_f32_16x16x32_bf16 v[56:59], v[136:139], v[178:181], v[56:59]
	v_mfma_f32_16x16x32_bf16 v[44:47], v[128:131], v[200:203], v[44:47]
	v_mfma_f32_16x16x32_bf16 v[40:43], v[136:139], v[200:203], v[40:43]
	v_mfma_f32_16x16x32_bf16 v[28:31], v[128:131], v[208:211], v[28:31]
	v_mfma_f32_16x16x32_bf16 v[24:27], v[136:139], v[208:211], v[24:27]
	v_mfma_f32_16x16x32_bf16 v[12:15], v[128:131], v[216:219], v[12:15]
	v_mfma_f32_16x16x32_bf16 v[8:11], v[136:139], v[216:219], v[8:11]
	v_mfma_f32_16x16x32_bf16 v[60:63], v[132:135], v[196:199], v[60:63]
	v_mfma_f32_16x16x32_bf16 v[56:59], v[140:143], v[196:199], v[56:59]
	v_mfma_f32_16x16x32_bf16 v[44:47], v[132:135], v[204:207], v[44:47]
	v_mfma_f32_16x16x32_bf16 v[40:43], v[140:143], v[204:207], v[40:43]
	v_mfma_f32_16x16x32_bf16 v[28:31], v[132:135], v[212:215], v[28:31]
	v_mfma_f32_16x16x32_bf16 v[24:27], v[140:143], v[212:215], v[24:27]
	v_mfma_f32_16x16x32_bf16 v[12:15], v[132:135], v[220:223], v[12:15]
	v_mfma_f32_16x16x32_bf16 v[8:11], v[140:143], v[220:223], v[8:11]
	v_mfma_f32_16x16x32_bf16 v[52:55], v[144:147], v[178:181], v[52:55]
	v_mfma_f32_16x16x32_bf16 v[48:51], v[152:155], v[178:181], v[48:51]
	v_mfma_f32_16x16x32_bf16 v[36:39], v[144:147], v[200:203], v[36:39]
	v_mfma_f32_16x16x32_bf16 v[32:35], v[152:155], v[200:203], v[32:35]
	v_mfma_f32_16x16x32_bf16 v[20:23], v[144:147], v[208:211], v[20:23]
	v_mfma_f32_16x16x32_bf16 v[16:19], v[152:155], v[208:211], v[16:19]
	v_mfma_f32_16x16x32_bf16 v[4:7], v[144:147], v[216:219], v[4:7]
	v_mfma_f32_16x16x32_bf16 v[0:3], v[152:155], v[216:219], v[0:3]
	v_mfma_f32_16x16x32_bf16 v[52:55], v[148:151], v[196:199], v[52:55]
	v_mfma_f32_16x16x32_bf16 v[48:51], v[156:159], v[196:199], v[48:51]
	v_mfma_f32_16x16x32_bf16 v[36:39], v[148:151], v[204:207], v[36:39]
	v_mfma_f32_16x16x32_bf16 v[32:35], v[156:159], v[204:207], v[32:35]
	v_mfma_f32_16x16x32_bf16 v[20:23], v[148:151], v[212:215], v[20:23]
	v_mfma_f32_16x16x32_bf16 v[16:19], v[156:159], v[212:215], v[16:19]
	v_mfma_f32_16x16x32_bf16 v[4:7], v[148:151], v[220:223], v[4:7]
	v_mfma_f32_16x16x32_bf16 v[0:3], v[156:159], v[220:223], v[0:3]
	s_barrier
	s_add_i32 s53, s53, 2
	s_add_u32 s0, s0, 0x100
	s_addc_u32 s1, s1, 0
	s_add_u32 s51, s51, 0x100
	s_addc_u32 s52, s52, 0
	s_cmp_gt_u32 s53, 13
	s_cbranch_scc0 .LBB0_1403

.LBB0_1487:
	s_ashr_i32 s15, s14, 31
	s_lshl_b64 s[16:17], s[14:15], 19
	s_add_u32 s16, s66, s16
	s_addc_u32 s17, s67, s17
	s_and_b64 s[18:19], s[4:5], exec
	s_cselect_b32 s15, s17, s1
	s_cselect_b32 s41, s16, s0
	s_ashr_i32 s13, s12, 31
	s_lshl_b64 s[18:19], s[12:13], 19
	s_add_u32 s18, s26, s18
	s_addc_u32 s19, s27, s19
	s_and_b64 s[24:25], s[4:5], exec
	s_cselect_b32 s13, s19, s23
	s_cselect_b32 s42, s18, s22
	s_add_u32 s0, s0, 0x40080
	s_addc_u32 s1, s1, 0
	s_add_u32 s43, s22, 0x100
	s_addc_u32 s44, s23, 0
	s_mov_b32 s45, -2
	v_lshl_add_u32 v248, s20, 8, v156
	v_ashrrev_i32_e32 v249, 31, v248
	v_lshl_add_u64 v[248:249], v[248:249], 2, s[8:9]
	global_load_dword v240, v[248:249], off
	global_load_dword v241, v[248:249], off offset:64
	global_load_dword v242, v[248:249], off offset:128
	global_load_dword v243, v[248:249], off offset:192
	global_load_dword v244, v[248:249], off offset:512
	global_load_dword v245, v[248:249], off offset:576
	global_load_dword v246, v[248:249], off offset:640
	global_load_dword v247, v[248:249], off offset:704
	ds_read_b128 v[144:147], v159
	ds_read_b128 v[148:151], v159 offset:1024
	ds_read_b128 v[152:155], v159 offset:2048
	ds_read_b128 v[166:169], v159 offset:3072
	ds_read_b128 v[170:173], v162
	ds_read_b128 v[174:177], v162 offset:1024
	ds_read_b128 v[178:181], v162 offset:2048
	ds_read_b128 v[188:191], v162 offset:3072
	s_add_u32 s22, s0, 0xfffc0080
	s_addc_u32 s23, s1, -1
	s_cmp_eq_u32 s45, 12
	s_cselect_b32 s25, s15, s23
	s_cselect_b32 s24, s41, s22
	s_cselect_b32 s23, s13, s44
	s_cselect_b32 s22, s42, s43
	v_lshl_add_u64 v[224:225], s[0:1], 0, v[136:137]
	s_add_i32 m0, s21, 0xc000
	ds_read_b128 v[192:195], v163
	ds_read_b128 v[196:199], v163 offset:1024
	ds_read_b128 v[200:203], v163 offset:2048
	ds_read_b128 v[204:207], v163 offset:3072
	ds_read_b128 v[208:211], v163 offset:4096
	ds_read_b128 v[212:215], v163 offset:5120
	ds_read_b128 v[216:219], v163 offset:6144
	ds_read_b128 v[220:223], v163 offset:7168
	global_load_lds_dwordx4 v[224:225], off
	v_lshl_add_u64 v[224:225], s[0:1], 0, v[138:139]
	s_add_i32 m0, s21, 0xe000
	s_nop 0
	global_load_lds_dwordx4 v[224:225], off
	s_waitcnt vmcnt(8) lgkmcnt(0)
	s_barrier
	v_mfma_f32_16x16x32_bf16 v[124:127], v[144:147], v[192:195], 0
	v_mfma_f32_16x16x32_bf16 v[120:123], v[152:155], v[192:195], 0
	v_mfma_f32_16x16x32_bf16 v[116:119], v[144:147], v[200:203], 0
	v_mfma_f32_16x16x32_bf16 v[104:107], v[152:155], v[200:203], 0
	v_mfma_f32_16x16x32_bf16 v[92:95], v[144:147], v[208:211], 0
	v_mfma_f32_16x16x32_bf16 v[88:91], v[152:155], v[208:211], 0
	v_mfma_f32_16x16x32_bf16 v[76:79], v[144:147], v[216:219], 0
	v_mfma_f32_16x16x32_bf16 v[72:75], v[152:155], v[216:219], 0
	v_mfma_f32_16x16x32_bf16 v[124:127], v[148:151], v[196:199], v[124:127]
	v_mfma_f32_16x16x32_bf16 v[120:123], v[166:169], v[196:199], v[120:123]
	v_mfma_f32_16x16x32_bf16 v[116:119], v[148:151], v[204:207], v[116:119]
	v_mfma_f32_16x16x32_bf16 v[104:107], v[166:169], v[204:207], v[104:107]
	v_mfma_f32_16x16x32_bf16 v[92:95], v[148:151], v[212:215], v[92:95]
	v_mfma_f32_16x16x32_bf16 v[88:91], v[166:169], v[212:215], v[88:91]
	v_mfma_f32_16x16x32_bf16 v[76:79], v[148:151], v[220:223], v[76:79]
	v_mfma_f32_16x16x32_bf16 v[72:75], v[166:169], v[220:223], v[72:75]
	v_mfma_f32_16x16x32_bf16 v[112:115], v[170:173], v[192:195], 0
	v_mfma_f32_16x16x32_bf16 v[108:111], v[178:181], v[192:195], 0
	v_mfma_f32_16x16x32_bf16 v[100:103], v[170:173], v[200:203], 0
	v_mfma_f32_16x16x32_bf16 v[96:99], v[178:181], v[200:203], 0
	v_mfma_f32_16x16x32_bf16 v[84:87], v[170:173], v[208:211], 0
	v_mfma_f32_16x16x32_bf16 v[80:83], v[178:181], v[208:211], 0
	v_mfma_f32_16x16x32_bf16 v[68:71], v[170:173], v[216:219], 0
	v_mfma_f32_16x16x32_bf16 v[64:67], v[178:181], v[216:219], 0
	v_mfma_f32_16x16x32_bf16 v[112:115], v[174:177], v[196:199], v[112:115]
	v_mfma_f32_16x16x32_bf16 v[108:111], v[188:191], v[196:199], v[108:111]
	v_mfma_f32_16x16x32_bf16 v[100:103], v[174:177], v[204:207], v[100:103]
	v_mfma_f32_16x16x32_bf16 v[96:99], v[188:191], v[204:207], v[96:99]
	v_mfma_f32_16x16x32_bf16 v[84:87], v[174:177], v[212:215], v[84:87]
	v_mfma_f32_16x16x32_bf16 v[80:83], v[188:191], v[212:215], v[80:83]
	v_mfma_f32_16x16x32_bf16 v[68:71], v[174:177], v[220:223], v[68:71]
	v_mfma_f32_16x16x32_bf16 v[64:67], v[188:191], v[220:223], v[64:67]
	s_barrier
	s_add_i32 s46, s39, s28
	v_lshl_add_u64 v[224:225], s[22:23], 0, v[132:133]
	s_mov_b32 m0, s46
	ds_read_b128 v[192:195], v163 offset:16384
	ds_read_b128 v[196:199], v163 offset:17408
	ds_read_b128 v[200:203], v163 offset:18432
	ds_read_b128 v[204:207], v163 offset:19456
	ds_read_b128 v[208:211], v163 offset:20480
	ds_read_b128 v[212:215], v163 offset:21504
	ds_read_b128 v[216:219], v163 offset:22528
	ds_read_b128 v[220:223], v163 offset:23552
	global_load_lds_dwordx4 v[224:225], off
	s_add_i32 m0, s46, 0x2000
	s_add_u32 s46, s22, 0x40000
	v_lshl_add_u64 v[226:227], s[22:23], 0, v[128:129]
	s_addc_u32 s47, s23, 0
	s_add_i32 s48, s40, s28
	global_load_lds_dwordx4 v[226:227], off
	v_lshl_add_u64 v[228:229], s[46:47], 0, v[132:133]
	s_mov_b32 m0, s48
	v_lshl_add_u64 v[230:231], s[24:25], 0, v[130:131]
	global_load_lds_dwordx4 v[228:229], off
	v_lshl_add_u64 v[228:229], s[46:47], 0, v[128:129]
	s_add_i32 m0, s48, 0x2000
	s_nop 0
	global_load_lds_dwordx4 v[228:229], off
	v_lshl_add_u64 v[228:229], s[24:25], 0, v[134:135]
	s_mov_b32 m0, s21
	s_nop 0
	global_load_lds_dwordx4 v[228:229], off
	s_mov_b32 m0, s31
	s_nop 0
	global_load_lds_dwordx4 v[230:231], off
	s_waitcnt vmcnt(8) lgkmcnt(0)
	s_barrier
	v_mfma_f32_16x16x32_bf16 v[60:63], v[144:147], v[192:195], 0
	v_mfma_f32_16x16x32_bf16 v[56:59], v[152:155], v[192:195], 0
	v_mfma_f32_16x16x32_bf16 v[44:47], v[144:147], v[200:203], 0
	v_mfma_f32_16x16x32_bf16 v[40:43], v[152:155], v[200:203], 0
	v_mfma_f32_16x16x32_bf16 v[28:31], v[144:147], v[208:211], 0
	v_mfma_f32_16x16x32_bf16 v[24:27], v[152:155], v[208:211], 0
	v_mfma_f32_16x16x32_bf16 v[12:15], v[144:147], v[216:219], 0
	v_mfma_f32_16x16x32_bf16 v[8:11], v[152:155], v[216:219], 0
	v_mfma_f32_16x16x32_bf16 v[60:63], v[148:151], v[196:199], v[60:63]
	v_mfma_f32_16x16x32_bf16 v[56:59], v[166:169], v[196:199], v[56:59]
	v_mfma_f32_16x16x32_bf16 v[44:47], v[148:151], v[204:207], v[44:47]
	v_mfma_f32_16x16x32_bf16 v[40:43], v[166:169], v[204:207], v[40:43]
	v_mfma_f32_16x16x32_bf16 v[28:31], v[148:151], v[212:215], v[28:31]
	v_mfma_f32_16x16x32_bf16 v[24:27], v[166:169], v[212:215], v[24:27]
	v_mfma_f32_16x16x32_bf16 v[12:15], v[148:151], v[220:223], v[12:15]
	v_mfma_f32_16x16x32_bf16 v[8:11], v[166:169], v[220:223], v[8:11]
	v_mfma_f32_16x16x32_bf16 v[52:55], v[170:173], v[192:195], 0
	v_mfma_f32_16x16x32_bf16 v[48:51], v[178:181], v[192:195], 0
	v_mfma_f32_16x16x32_bf16 v[36:39], v[170:173], v[200:203], 0
	v_mfma_f32_16x16x32_bf16 v[32:35], v[178:181], v[200:203], 0
	v_mfma_f32_16x16x32_bf16 v[20:23], v[170:173], v[208:211], 0
	v_mfma_f32_16x16x32_bf16 v[16:19], v[178:181], v[208:211], 0
	v_mfma_f32_16x16x32_bf16 v[4:7], v[170:173], v[216:219], 0
	v_mfma_f32_16x16x32_bf16 v[0:3], v[178:181], v[216:219], 0
	v_mfma_f32_16x16x32_bf16 v[52:55], v[174:177], v[196:199], v[52:55]
	v_mfma_f32_16x16x32_bf16 v[48:51], v[188:191], v[196:199], v[48:51]
	v_mfma_f32_16x16x32_bf16 v[36:39], v[174:177], v[204:207], v[36:39]
	v_mfma_f32_16x16x32_bf16 v[32:35], v[188:191], v[204:207], v[32:35]
	v_mfma_f32_16x16x32_bf16 v[20:23], v[174:177], v[212:215], v[20:23]
	v_mfma_f32_16x16x32_bf16 v[16:19], v[188:191], v[212:215], v[16:19]
	v_mfma_f32_16x16x32_bf16 v[4:7], v[174:177], v[220:223], v[4:7]
	v_mfma_f32_16x16x32_bf16 v[0:3], v[188:191], v[220:223], v[0:3]
	s_barrier
	s_add_i32 s46, 0, 0x18000
	v_add_u32_e32 v165, s46, v157
	s_add_i32 s47, 0, 0x1c000
	ds_read_b128 v[144:147], v165
	ds_read_b128 v[148:151], v165 offset:1024
	ds_read_b128 v[152:155], v165 offset:2048
	ds_read_b128 v[166:169], v165 offset:3072
	v_add_u32_e32 v165, s47, v157
	ds_read_b128 v[170:173], v165
	ds_read_b128 v[174:177], v165 offset:1024
	ds_read_b128 v[178:181], v165 offset:2048
	ds_read_b128 v[188:191], v165 offset:3072
	s_add_u32 s24, s24, 0x40000
	s_addc_u32 s25, s25, 0
	s_mov_b32 m0, s34
	v_lshl_add_u64 v[232:233], s[24:25], 0, v[134:135]
	ds_read_b128 v[192:195], v163 offset:32768
	ds_read_b128 v[196:199], v163 offset:33792
	ds_read_b128 v[200:203], v163 offset:34816
	ds_read_b128 v[204:207], v163 offset:35840
	ds_read_b128 v[208:211], v163 offset:36864
	ds_read_b128 v[212:215], v163 offset:37888
	ds_read_b128 v[216:219], v163 offset:38912
	ds_read_b128 v[220:223], v163 offset:39936
	global_load_lds_dwordx4 v[232:233], off
	v_lshl_add_u64 v[232:233], s[24:25], 0, v[130:131]
	s_mov_b32 m0, s35
	s_nop 0
	global_load_lds_dwordx4 v[232:233], off
	s_waitcnt vmcnt(8) lgkmcnt(0)
	s_barrier
	v_mfma_f32_16x16x32_bf16 v[124:127], v[144:147], v[192:195], v[124:127]
	v_mfma_f32_16x16x32_bf16 v[120:123], v[152:155], v[192:195], v[120:123]
	v_mfma_f32_16x16x32_bf16 v[116:119], v[144:147], v[200:203], v[116:119]
	v_mfma_f32_16x16x32_bf16 v[104:107], v[152:155], v[200:203], v[104:107]
	v_mfma_f32_16x16x32_bf16 v[92:95], v[144:147], v[208:211], v[92:95]
	v_mfma_f32_16x16x32_bf16 v[88:91], v[152:155], v[208:211], v[88:91]
	v_mfma_f32_16x16x32_bf16 v[76:79], v[144:147], v[216:219], v[76:79]
	v_mfma_f32_16x16x32_bf16 v[72:75], v[152:155], v[216:219], v[72:75]
	v_mfma_f32_16x16x32_bf16 v[124:127], v[148:151], v[196:199], v[124:127]
	v_mfma_f32_16x16x32_bf16 v[120:123], v[166:169], v[196:199], v[120:123]
	v_mfma_f32_16x16x32_bf16 v[116:119], v[148:151], v[204:207], v[116:119]
	v_mfma_f32_16x16x32_bf16 v[104:107], v[166:169], v[204:207], v[104:107]
	v_mfma_f32_16x16x32_bf16 v[92:95], v[148:151], v[212:215], v[92:95]
	v_mfma_f32_16x16x32_bf16 v[88:91], v[166:169], v[212:215], v[88:91]
	v_mfma_f32_16x16x32_bf16 v[76:79], v[148:151], v[220:223], v[76:79]
	v_mfma_f32_16x16x32_bf16 v[72:75], v[166:169], v[220:223], v[72:75]
	v_mfma_f32_16x16x32_bf16 v[112:115], v[170:173], v[192:195], v[112:115]
	v_mfma_f32_16x16x32_bf16 v[108:111], v[178:181], v[192:195], v[108:111]
	v_mfma_f32_16x16x32_bf16 v[100:103], v[170:173], v[200:203], v[100:103]
	v_mfma_f32_16x16x32_bf16 v[96:99], v[178:181], v[200:203], v[96:99]
	v_mfma_f32_16x16x32_bf16 v[84:87], v[170:173], v[208:211], v[84:87]
	v_mfma_f32_16x16x32_bf16 v[80:83], v[178:181], v[208:211], v[80:83]
	v_mfma_f32_16x16x32_bf16 v[68:71], v[170:173], v[216:219], v[68:71]
	v_mfma_f32_16x16x32_bf16 v[64:67], v[178:181], v[216:219], v[64:67]
	v_mfma_f32_16x16x32_bf16 v[112:115], v[174:177], v[196:199], v[112:115]
	v_mfma_f32_16x16x32_bf16 v[108:111], v[188:191], v[196:199], v[108:111]
	v_mfma_f32_16x16x32_bf16 v[100:103], v[174:177], v[204:207], v[100:103]
	v_mfma_f32_16x16x32_bf16 v[96:99], v[188:191], v[204:207], v[96:99]
	v_mfma_f32_16x16x32_bf16 v[84:87], v[174:177], v[212:215], v[84:87]
	v_mfma_f32_16x16x32_bf16 v[80:83], v[188:191], v[212:215], v[80:83]
	v_mfma_f32_16x16x32_bf16 v[68:71], v[174:177], v[220:223], v[68:71]
	v_mfma_f32_16x16x32_bf16 v[64:67], v[188:191], v[220:223], v[64:67]
	s_barrier
	s_add_i32 s24, s46, s28
	v_lshl_add_u64 v[224:225], v[224:225], 0, s[6:7]
	s_mov_b32 m0, s24
	ds_read_b128 v[192:195], v163 offset:49152
	ds_read_b128 v[196:199], v163 offset:50176
	ds_read_b128 v[200:203], v163 offset:51200
	ds_read_b128 v[204:207], v163 offset:52224
	ds_read_b128 v[208:211], v163 offset:53248
	ds_read_b128 v[212:215], v163 offset:54272
	ds_read_b128 v[216:219], v163 offset:55296
	ds_read_b128 v[220:223], v163 offset:56320
	global_load_lds_dwordx4 v[224:225], off
	s_add_i32 m0, s24, 0x2000
	s_add_u32 s22, s22, 0x40080
	v_lshl_add_u64 v[224:225], v[226:227], 0, s[6:7]
	s_addc_u32 s23, s23, 0
	s_add_i32 s24, s47, s28
	global_load_lds_dwordx4 v[224:225], off
	v_lshl_add_u64 v[224:225], s[22:23], 0, v[132:133]
	s_mov_b32 m0, s24
	s_nop 0
	global_load_lds_dwordx4 v[224:225], off
	v_lshl_add_u64 v[224:225], s[22:23], 0, v[128:129]
	s_add_i32 m0, s24, 0x2000
	s_nop 0
	global_load_lds_dwordx4 v[224:225], off
	v_lshl_add_u64 v[224:225], v[228:229], 0, s[6:7]
	s_mov_b32 m0, s37
	s_nop 0
	global_load_lds_dwordx4 v[224:225], off
	v_lshl_add_u64 v[224:225], v[230:231], 0, s[6:7]
	s_mov_b32 m0, s38
	s_nop 0
	global_load_lds_dwordx4 v[224:225], off
	s_waitcnt vmcnt(8) lgkmcnt(0)
	s_barrier
	v_mfma_f32_16x16x32_bf16 v[60:63], v[144:147], v[192:195], v[60:63]
	v_mfma_f32_16x16x32_bf16 v[56:59], v[152:155], v[192:195], v[56:59]
	v_mfma_f32_16x16x32_bf16 v[44:47], v[144:147], v[200:203], v[44:47]
	v_mfma_f32_16x16x32_bf16 v[40:43], v[152:155], v[200:203], v[40:43]
	v_mfma_f32_16x16x32_bf16 v[28:31], v[144:147], v[208:211], v[28:31]
	v_mfma_f32_16x16x32_bf16 v[24:27], v[152:155], v[208:211], v[24:27]
	v_mfma_f32_16x16x32_bf16 v[12:15], v[144:147], v[216:219], v[12:15]
	v_mfma_f32_16x16x32_bf16 v[8:11], v[152:155], v[216:219], v[8:11]
	v_mfma_f32_16x16x32_bf16 v[60:63], v[148:151], v[196:199], v[60:63]
	v_mfma_f32_16x16x32_bf16 v[56:59], v[166:169], v[196:199], v[56:59]
	v_mfma_f32_16x16x32_bf16 v[44:47], v[148:151], v[204:207], v[44:47]
	v_mfma_f32_16x16x32_bf16 v[40:43], v[166:169], v[204:207], v[40:43]
	v_mfma_f32_16x16x32_bf16 v[28:31], v[148:151], v[212:215], v[28:31]
	v_mfma_f32_16x16x32_bf16 v[24:27], v[166:169], v[212:215], v[24:27]
	v_mfma_f32_16x16x32_bf16 v[12:15], v[148:151], v[220:223], v[12:15]
	v_mfma_f32_16x16x32_bf16 v[8:11], v[166:169], v[220:223], v[8:11]
	v_mfma_f32_16x16x32_bf16 v[52:55], v[170:173], v[192:195], v[52:55]
	v_mfma_f32_16x16x32_bf16 v[48:51], v[178:181], v[192:195], v[48:51]
	v_mfma_f32_16x16x32_bf16 v[36:39], v[170:173], v[200:203], v[36:39]
	v_mfma_f32_16x16x32_bf16 v[32:35], v[178:181], v[200:203], v[32:35]
	v_mfma_f32_16x16x32_bf16 v[20:23], v[170:173], v[208:211], v[20:23]
	v_mfma_f32_16x16x32_bf16 v[16:19], v[178:181], v[208:211], v[16:19]
	v_mfma_f32_16x16x32_bf16 v[4:7], v[170:173], v[216:219], v[4:7]
	v_mfma_f32_16x16x32_bf16 v[0:3], v[178:181], v[216:219], v[0:3]
	v_mfma_f32_16x16x32_bf16 v[52:55], v[174:177], v[196:199], v[52:55]
	v_mfma_f32_16x16x32_bf16 v[48:51], v[188:191], v[196:199], v[48:51]
	v_mfma_f32_16x16x32_bf16 v[36:39], v[174:177], v[204:207], v[36:39]
	v_mfma_f32_16x16x32_bf16 v[32:35], v[188:191], v[204:207], v[32:35]
	v_mfma_f32_16x16x32_bf16 v[20:23], v[174:177], v[212:215], v[20:23]
	v_mfma_f32_16x16x32_bf16 v[16:19], v[188:191], v[212:215], v[16:19]
	v_mfma_f32_16x16x32_bf16 v[4:7], v[174:177], v[220:223], v[4:7]
	v_mfma_f32_16x16x32_bf16 v[0:3], v[188:191], v[220:223], v[0:3]
	s_barrier
	s_add_i32 s45, s45, 2
	s_add_u32 s0, s0, 0x100
	s_addc_u32 s1, s1, 0
	s_add_u32 s43, s43, 0x100
	s_addc_u32 s44, s44, 0
	s_cmp_gt_u32 s45, 13
	s_cbranch_scc0 .LBB0_1488
	s_branch .Lpeel_exit_7
.LBB0_1488:
	ds_read_b128 v[144:147], v159
	ds_read_b128 v[148:151], v159 offset:1024
	ds_read_b128 v[152:155], v159 offset:2048
	ds_read_b128 v[166:169], v159 offset:3072
	ds_read_b128 v[170:173], v162
	ds_read_b128 v[174:177], v162 offset:1024
	ds_read_b128 v[178:181], v162 offset:2048
	ds_read_b128 v[188:191], v162 offset:3072
	s_add_u32 s22, s0, 0xfffc0080
	s_addc_u32 s23, s1, -1
	s_cmp_eq_u32 s45, 12
	s_cselect_b32 s25, s15, s23
	s_cselect_b32 s24, s41, s22
	s_cselect_b32 s23, s13, s44
	s_cselect_b32 s22, s42, s43
	v_lshl_add_u64 v[224:225], s[0:1], 0, v[136:137]
	s_add_i32 m0, s21, 0xc000
	ds_read_b128 v[192:195], v163
	ds_read_b128 v[196:199], v163 offset:1024
	ds_read_b128 v[200:203], v163 offset:2048
	ds_read_b128 v[204:207], v163 offset:3072
	ds_read_b128 v[208:211], v163 offset:4096
	ds_read_b128 v[212:215], v163 offset:5120
	ds_read_b128 v[216:219], v163 offset:6144
	ds_read_b128 v[220:223], v163 offset:7168
	global_load_lds_dwordx4 v[224:225], off
	v_lshl_add_u64 v[224:225], s[0:1], 0, v[138:139]
	s_add_i32 m0, s21, 0xe000
	s_nop 0
	global_load_lds_dwordx4 v[224:225], off
	s_waitcnt vmcnt(8) lgkmcnt(0)
	s_barrier
	v_mfma_f32_16x16x32_bf16 v[124:127], v[144:147], v[192:195], v[124:127]
	v_mfma_f32_16x16x32_bf16 v[120:123], v[152:155], v[192:195], v[120:123]
	v_mfma_f32_16x16x32_bf16 v[116:119], v[144:147], v[200:203], v[116:119]
	v_mfma_f32_16x16x32_bf16 v[104:107], v[152:155], v[200:203], v[104:107]
	v_mfma_f32_16x16x32_bf16 v[92:95], v[144:147], v[208:211], v[92:95]
	v_mfma_f32_16x16x32_bf16 v[88:91], v[152:155], v[208:211], v[88:91]
	v_mfma_f32_16x16x32_bf16 v[76:79], v[144:147], v[216:219], v[76:79]
	v_mfma_f32_16x16x32_bf16 v[72:75], v[152:155], v[216:219], v[72:75]
	v_mfma_f32_16x16x32_bf16 v[124:127], v[148:151], v[196:199], v[124:127]
	v_mfma_f32_16x16x32_bf16 v[120:123], v[166:169], v[196:199], v[120:123]
	v_mfma_f32_16x16x32_bf16 v[116:119], v[148:151], v[204:207], v[116:119]
	v_mfma_f32_16x16x32_bf16 v[104:107], v[166:169], v[204:207], v[104:107]
	v_mfma_f32_16x16x32_bf16 v[92:95], v[148:151], v[212:215], v[92:95]
	v_mfma_f32_16x16x32_bf16 v[88:91], v[166:169], v[212:215], v[88:91]
	v_mfma_f32_16x16x32_bf16 v[76:79], v[148:151], v[220:223], v[76:79]
	v_mfma_f32_16x16x32_bf16 v[72:75], v[166:169], v[220:223], v[72:75]
	v_mfma_f32_16x16x32_bf16 v[112:115], v[170:173], v[192:195], v[112:115]
	v_mfma_f32_16x16x32_bf16 v[108:111], v[178:181], v[192:195], v[108:111]
	v_mfma_f32_16x16x32_bf16 v[100:103], v[170:173], v[200:203], v[100:103]
	v_mfma_f32_16x16x32_bf16 v[96:99], v[178:181], v[200:203], v[96:99]
	v_mfma_f32_16x16x32_bf16 v[84:87], v[170:173], v[208:211], v[84:87]
	v_mfma_f32_16x16x32_bf16 v[80:83], v[178:181], v[208:211], v[80:83]
	v_mfma_f32_16x16x32_bf16 v[68:71], v[170:173], v[216:219], v[68:71]
	v_mfma_f32_16x16x32_bf16 v[64:67], v[178:181], v[216:219], v[64:67]
	v_mfma_f32_16x16x32_bf16 v[112:115], v[174:177], v[196:199], v[112:115]
	v_mfma_f32_16x16x32_bf16 v[108:111], v[188:191], v[196:199], v[108:111]
	v_mfma_f32_16x16x32_bf16 v[100:103], v[174:177], v[204:207], v[100:103]
	v_mfma_f32_16x16x32_bf16 v[96:99], v[188:191], v[204:207], v[96:99]
	v_mfma_f32_16x16x32_bf16 v[84:87], v[174:177], v[212:215], v[84:87]
	v_mfma_f32_16x16x32_bf16 v[80:83], v[188:191], v[212:215], v[80:83]
	v_mfma_f32_16x16x32_bf16 v[68:71], v[174:177], v[220:223], v[68:71]
	v_mfma_f32_16x16x32_bf16 v[64:67], v[188:191], v[220:223], v[64:67]
	s_barrier
	s_add_i32 s46, s39, s28
	v_lshl_add_u64 v[224:225], s[22:23], 0, v[132:133]
	s_mov_b32 m0, s46
	ds_read_b128 v[192:195], v163 offset:16384
	ds_read_b128 v[196:199], v163 offset:17408
	ds_read_b128 v[200:203], v163 offset:18432
	ds_read_b128 v[204:207], v163 offset:19456
	ds_read_b128 v[208:211], v163 offset:20480
	ds_read_b128 v[212:215], v163 offset:21504
	ds_read_b128 v[216:219], v163 offset:22528
	ds_read_b128 v[220:223], v163 offset:23552
	global_load_lds_dwordx4 v[224:225], off
	s_add_i32 m0, s46, 0x2000
	s_add_u32 s46, s22, 0x40000
	v_lshl_add_u64 v[226:227], s[22:23], 0, v[128:129]
	s_addc_u32 s47, s23, 0
	s_add_i32 s48, s40, s28
	global_load_lds_dwordx4 v[226:227], off
	v_lshl_add_u64 v[228:229], s[46:47], 0, v[132:133]
	s_mov_b32 m0, s48
	v_lshl_add_u64 v[230:231], s[24:25], 0, v[130:131]
	global_load_lds_dwordx4 v[228:229], off
	v_lshl_add_u64 v[228:229], s[46:47], 0, v[128:129]
	s_add_i32 m0, s48, 0x2000
	s_nop 0
	global_load_lds_dwordx4 v[228:229], off
	v_lshl_add_u64 v[228:229], s[24:25], 0, v[134:135]
	s_mov_b32 m0, s21
	s_nop 0
	global_load_lds_dwordx4 v[228:229], off
	s_mov_b32 m0, s31
	s_nop 0
	global_load_lds_dwordx4 v[230:231], off
	s_waitcnt vmcnt(8) lgkmcnt(0)
	s_barrier
	v_mfma_f32_16x16x32_bf16 v[60:63], v[144:147], v[192:195], v[60:63]
	v_mfma_f32_16x16x32_bf16 v[56:59], v[152:155], v[192:195], v[56:59]
	v_mfma_f32_16x16x32_bf16 v[44:47], v[144:147], v[200:203], v[44:47]
	v_mfma_f32_16x16x32_bf16 v[40:43], v[152:155], v[200:203], v[40:43]
	v_mfma_f32_16x16x32_bf16 v[28:31], v[144:147], v[208:211], v[28:31]
	v_mfma_f32_16x16x32_bf16 v[24:27], v[152:155], v[208:211], v[24:27]
	v_mfma_f32_16x16x32_bf16 v[12:15], v[144:147], v[216:219], v[12:15]
	v_mfma_f32_16x16x32_bf16 v[8:11], v[152:155], v[216:219], v[8:11]
	v_mfma_f32_16x16x32_bf16 v[60:63], v[148:151], v[196:199], v[60:63]
	v_mfma_f32_16x16x32_bf16 v[56:59], v[166:169], v[196:199], v[56:59]
	v_mfma_f32_16x16x32_bf16 v[44:47], v[148:151], v[204:207], v[44:47]
	v_mfma_f32_16x16x32_bf16 v[40:43], v[166:169], v[204:207], v[40:43]
	v_mfma_f32_16x16x32_bf16 v[28:31], v[148:151], v[212:215], v[28:31]
	v_mfma_f32_16x16x32_bf16 v[24:27], v[166:169], v[212:215], v[24:27]
	v_mfma_f32_16x16x32_bf16 v[12:15], v[148:151], v[220:223], v[12:15]
	v_mfma_f32_16x16x32_bf16 v[8:11], v[166:169], v[220:223], v[8:11]
	v_mfma_f32_16x16x32_bf16 v[52:55], v[170:173], v[192:195], v[52:55]
	v_mfma_f32_16x16x32_bf16 v[48:51], v[178:181], v[192:195], v[48:51]
	v_mfma_f32_16x16x32_bf16 v[36:39], v[170:173], v[200:203], v[36:39]
	v_mfma_f32_16x16x32_bf16 v[32:35], v[178:181], v[200:203], v[32:35]
	v_mfma_f32_16x16x32_bf16 v[20:23], v[170:173], v[208:211], v[20:23]
	v_mfma_f32_16x16x32_bf16 v[16:19], v[178:181], v[208:211], v[16:19]
	v_mfma_f32_16x16x32_bf16 v[4:7], v[170:173], v[216:219], v[4:7]
	v_mfma_f32_16x16x32_bf16 v[0:3], v[178:181], v[216:219], v[0:3]
	v_mfma_f32_16x16x32_bf16 v[52:55], v[174:177], v[196:199], v[52:55]
	v_mfma_f32_16x16x32_bf16 v[48:51], v[188:191], v[196:199], v[48:51]
	v_mfma_f32_16x16x32_bf16 v[36:39], v[174:177], v[204:207], v[36:39]
	v_mfma_f32_16x16x32_bf16 v[32:35], v[188:191], v[204:207], v[32:35]
	v_mfma_f32_16x16x32_bf16 v[20:23], v[174:177], v[212:215], v[20:23]
	v_mfma_f32_16x16x32_bf16 v[16:19], v[188:191], v[212:215], v[16:19]
	v_mfma_f32_16x16x32_bf16 v[4:7], v[174:177], v[220:223], v[4:7]
	v_mfma_f32_16x16x32_bf16 v[0:3], v[188:191], v[220:223], v[0:3]
	s_barrier
	s_add_i32 s46, 0, 0x18000
	v_add_u32_e32 v165, s46, v157
	s_add_i32 s47, 0, 0x1c000
	ds_read_b128 v[144:147], v165
	ds_read_b128 v[148:151], v165 offset:1024
	ds_read_b128 v[152:155], v165 offset:2048
	ds_read_b128 v[166:169], v165 offset:3072
	v_add_u32_e32 v165, s47, v157
	ds_read_b128 v[170:173], v165
	ds_read_b128 v[174:177], v165 offset:1024
	ds_read_b128 v[178:181], v165 offset:2048
	ds_read_b128 v[188:191], v165 offset:3072
	s_add_u32 s24, s24, 0x40000
	s_addc_u32 s25, s25, 0
	s_mov_b32 m0, s34
	v_lshl_add_u64 v[232:233], s[24:25], 0, v[134:135]
	ds_read_b128 v[192:195], v163 offset:32768
	ds_read_b128 v[196:199], v163 offset:33792
	ds_read_b128 v[200:203], v163 offset:34816
	ds_read_b128 v[204:207], v163 offset:35840
	ds_read_b128 v[208:211], v163 offset:36864
	ds_read_b128 v[212:215], v163 offset:37888
	ds_read_b128 v[216:219], v163 offset:38912
	ds_read_b128 v[220:223], v163 offset:39936
	global_load_lds_dwordx4 v[232:233], off
	v_lshl_add_u64 v[232:233], s[24:25], 0, v[130:131]
	s_mov_b32 m0, s35
	s_nop 0
	global_load_lds_dwordx4 v[232:233], off
	s_waitcnt vmcnt(8) lgkmcnt(0)
	s_barrier
	v_mfma_f32_16x16x32_bf16 v[124:127], v[144:147], v[192:195], v[124:127]
	v_mfma_f32_16x16x32_bf16 v[120:123], v[152:155], v[192:195], v[120:123]
	v_mfma_f32_16x16x32_bf16 v[116:119], v[144:147], v[200:203], v[116:119]
	v_mfma_f32_16x16x32_bf16 v[104:107], v[152:155], v[200:203], v[104:107]
	v_mfma_f32_16x16x32_bf16 v[92:95], v[144:147], v[208:211], v[92:95]
	v_mfma_f32_16x16x32_bf16 v[88:91], v[152:155], v[208:211], v[88:91]
	v_mfma_f32_16x16x32_bf16 v[76:79], v[144:147], v[216:219], v[76:79]
	v_mfma_f32_16x16x32_bf16 v[72:75], v[152:155], v[216:219], v[72:75]
	v_mfma_f32_16x16x32_bf16 v[124:127], v[148:151], v[196:199], v[124:127]
	v_mfma_f32_16x16x32_bf16 v[120:123], v[166:169], v[196:199], v[120:123]
	v_mfma_f32_16x16x32_bf16 v[116:119], v[148:151], v[204:207], v[116:119]
	v_mfma_f32_16x16x32_bf16 v[104:107], v[166:169], v[204:207], v[104:107]
	v_mfma_f32_16x16x32_bf16 v[92:95], v[148:151], v[212:215], v[92:95]
	v_mfma_f32_16x16x32_bf16 v[88:91], v[166:169], v[212:215], v[88:91]
	v_mfma_f32_16x16x32_bf16 v[76:79], v[148:151], v[220:223], v[76:79]
	v_mfma_f32_16x16x32_bf16 v[72:75], v[166:169], v[220:223], v[72:75]
	v_mfma_f32_16x16x32_bf16 v[112:115], v[170:173], v[192:195], v[112:115]
	v_mfma_f32_16x16x32_bf16 v[108:111], v[178:181], v[192:195], v[108:111]
	v_mfma_f32_16x16x32_bf16 v[100:103], v[170:173], v[200:203], v[100:103]
	v_mfma_f32_16x16x32_bf16 v[96:99], v[178:181], v[200:203], v[96:99]
	v_mfma_f32_16x16x32_bf16 v[84:87], v[170:173], v[208:211], v[84:87]
	v_mfma_f32_16x16x32_bf16 v[80:83], v[178:181], v[208:211], v[80:83]
	v_mfma_f32_16x16x32_bf16 v[68:71], v[170:173], v[216:219], v[68:71]
	v_mfma_f32_16x16x32_bf16 v[64:67], v[178:181], v[216:219], v[64:67]
	v_mfma_f32_16x16x32_bf16 v[112:115], v[174:177], v[196:199], v[112:115]
	v_mfma_f32_16x16x32_bf16 v[108:111], v[188:191], v[196:199], v[108:111]
	v_mfma_f32_16x16x32_bf16 v[100:103], v[174:177], v[204:207], v[100:103]
	v_mfma_f32_16x16x32_bf16 v[96:99], v[188:191], v[204:207], v[96:99]
	v_mfma_f32_16x16x32_bf16 v[84:87], v[174:177], v[212:215], v[84:87]
	v_mfma_f32_16x16x32_bf16 v[80:83], v[188:191], v[212:215], v[80:83]
	v_mfma_f32_16x16x32_bf16 v[68:71], v[174:177], v[220:223], v[68:71]
	v_mfma_f32_16x16x32_bf16 v[64:67], v[188:191], v[220:223], v[64:67]
	s_barrier
	s_add_i32 s24, s46, s28
	v_lshl_add_u64 v[224:225], v[224:225], 0, s[6:7]
	s_mov_b32 m0, s24
	ds_read_b128 v[192:195], v163 offset:49152
	ds_read_b128 v[196:199], v163 offset:50176
	ds_read_b128 v[200:203], v163 offset:51200
	ds_read_b128 v[204:207], v163 offset:52224
	ds_read_b128 v[208:211], v163 offset:53248
	ds_read_b128 v[212:215], v163 offset:54272
	ds_read_b128 v[216:219], v163 offset:55296
	ds_read_b128 v[220:223], v163 offset:56320
	global_load_lds_dwordx4 v[224:225], off
	s_add_i32 m0, s24, 0x2000
	s_add_u32 s22, s22, 0x40080
	v_lshl_add_u64 v[224:225], v[226:227], 0, s[6:7]
	s_addc_u32 s23, s23, 0
	s_add_i32 s24, s47, s28
	global_load_lds_dwordx4 v[224:225], off
	v_lshl_add_u64 v[224:225], s[22:23], 0, v[132:133]
	s_mov_b32 m0, s24
	s_nop 0
	global_load_lds_dwordx4 v[224:225], off
	v_lshl_add_u64 v[224:225], s[22:23], 0, v[128:129]
	s_add_i32 m0, s24, 0x2000
	s_nop 0
	global_load_lds_dwordx4 v[224:225], off
	v_lshl_add_u64 v[224:225], v[228:229], 0, s[6:7]
	s_mov_b32 m0, s37
	s_nop 0
	global_load_lds_dwordx4 v[224:225], off
	v_lshl_add_u64 v[224:225], v[230:231], 0, s[6:7]
	s_mov_b32 m0, s38
	s_nop 0
	global_load_lds_dwordx4 v[224:225], off
	s_waitcnt vmcnt(8) lgkmcnt(0)
	s_barrier
	v_mfma_f32_16x16x32_bf16 v[60:63], v[144:147], v[192:195], v[60:63]
	v_mfma_f32_16x16x32_bf16 v[56:59], v[152:155], v[192:195], v[56:59]
	v_mfma_f32_16x16x32_bf16 v[44:47], v[144:147], v[200:203], v[44:47]
	v_mfma_f32_16x16x32_bf16 v[40:43], v[152:155], v[200:203], v[40:43]
	v_mfma_f32_16x16x32_bf16 v[28:31], v[144:147], v[208:211], v[28:31]
	v_mfma_f32_16x16x32_bf16 v[24:27], v[152:155], v[208:211], v[24:27]
	v_mfma_f32_16x16x32_bf16 v[12:15], v[144:147], v[216:219], v[12:15]
	v_mfma_f32_16x16x32_bf16 v[8:11], v[152:155], v[216:219], v[8:11]
	v_mfma_f32_16x16x32_bf16 v[60:63], v[148:151], v[196:199], v[60:63]
	v_mfma_f32_16x16x32_bf16 v[56:59], v[166:169], v[196:199], v[56:59]
	v_mfma_f32_16x16x32_bf16 v[44:47], v[148:151], v[204:207], v[44:47]
	v_mfma_f32_16x16x32_bf16 v[40:43], v[166:169], v[204:207], v[40:43]
	v_mfma_f32_16x16x32_bf16 v[28:31], v[148:151], v[212:215], v[28:31]
	v_mfma_f32_16x16x32_bf16 v[24:27], v[166:169], v[212:215], v[24:27]
	v_mfma_f32_16x16x32_bf16 v[12:15], v[148:151], v[220:223], v[12:15]
	v_mfma_f32_16x16x32_bf16 v[8:11], v[166:169], v[220:223], v[8:11]
	v_mfma_f32_16x16x32_bf16 v[52:55], v[170:173], v[192:195], v[52:55]
	v_mfma_f32_16x16x32_bf16 v[48:51], v[178:181], v[192:195], v[48:51]
	v_mfma_f32_16x16x32_bf16 v[36:39], v[170:173], v[200:203], v[36:39]
	v_mfma_f32_16x16x32_bf16 v[32:35], v[178:181], v[200:203], v[32:35]
	v_mfma_f32_16x16x32_bf16 v[20:23], v[170:173], v[208:211], v[20:23]
	v_mfma_f32_16x16x32_bf16 v[16:19], v[178:181], v[208:211], v[16:19]
	v_mfma_f32_16x16x32_bf16 v[4:7], v[170:173], v[216:219], v[4:7]
	v_mfma_f32_16x16x32_bf16 v[0:3], v[178:181], v[216:219], v[0:3]
	v_mfma_f32_16x16x32_bf16 v[52:55], v[174:177], v[196:199], v[52:55]
	v_mfma_f32_16x16x32_bf16 v[48:51], v[188:191], v[196:199], v[48:51]
	v_mfma_f32_16x16x32_bf16 v[36:39], v[174:177], v[204:207], v[36:39]
	v_mfma_f32_16x16x32_bf16 v[32:35], v[188:191], v[204:207], v[32:35]
	v_mfma_f32_16x16x32_bf16 v[20:23], v[174:177], v[212:215], v[20:23]
	v_mfma_f32_16x16x32_bf16 v[16:19], v[188:191], v[212:215], v[16:19]
	v_mfma_f32_16x16x32_bf16 v[4:7], v[174:177], v[220:223], v[4:7]
	v_mfma_f32_16x16x32_bf16 v[0:3], v[188:191], v[220:223], v[0:3]
	s_barrier
	s_add_i32 s45, s45, 2
	s_add_u32 s0, s0, 0x100
	s_addc_u32 s1, s1, 0
	s_add_u32 s43, s43, 0x100
	s_addc_u32 s44, s44, 0
	s_cmp_gt_u32 s45, 13
	s_cbranch_scc0 .LBB0_1488

.LBB0_1562:
	s_ashr_i32 s17, s16, 31
	s_lshl_b64 s[18:19], s[16:17], 21
	s_add_u32 s18, s68, s18
	s_addc_u32 s19, s69, s19
	s_and_b64 s[20:21], s[4:5], exec
	s_cselect_b32 s17, s19, s1
	s_cselect_b32 s33, s18, s0
	s_ashr_i32 s15, s14, 31
	s_lshl_b64 s[20:21], s[14:15], 21
	s_add_u32 s20, s30, s20
	s_addc_u32 s21, s31, s21
	s_and_b64 s[28:29], s[4:5], exec
	s_cselect_b32 s15, s21, s27
	s_cselect_b32 s49, s20, s26
	s_add_u32 s0, s0, 0x100080
	s_addc_u32 s1, s1, 0
	s_add_u32 s50, s26, 0x100
	s_addc_u32 s51, s27, 0
	s_mov_b32 s52, -2
	s_waitcnt lgkmcnt(0)
	ds_read_b128 v[128:131], v193
	ds_read_b128 v[132:135], v193 offset:1024
	ds_read_b128 v[136:139], v193 offset:2048
	ds_read_b128 v[140:143], v193 offset:3072
	ds_read_b128 v[144:147], v194
	ds_read_b128 v[148:151], v194 offset:1024
	ds_read_b128 v[152:155], v194 offset:2048
	ds_read_b128 v[156:159], v194 offset:3072
	s_add_u32 s26, s0, 0xfff00080
	s_addc_u32 s27, s1, -1
	s_cmp_eq_u32 s52, 60
	s_cselect_b32 s29, s17, s27
	s_cselect_b32 s28, s33, s26
	s_cselect_b32 s27, s15, s51
	s_cselect_b32 s26, s49, s50
	v_lshl_add_u64 v[224:225], s[0:1], 0, v[170:171]
	s_add_i32 m0, s23, 0xc000
	ds_read_b128 v[178:181], v195
	ds_read_b128 v[196:199], v195 offset:1024
	ds_read_b128 v[200:203], v195 offset:2048
	ds_read_b128 v[204:207], v195 offset:3072
	ds_read_b128 v[208:211], v195 offset:4096
	ds_read_b128 v[212:215], v195 offset:5120
	ds_read_b128 v[216:219], v195 offset:6144
	ds_read_b128 v[220:223], v195 offset:7168
	global_load_lds_dwordx4 v[224:225], off
	v_lshl_add_u64 v[224:225], s[0:1], 0, v[172:173]
	s_add_i32 m0, s23, 0xe000
	s_nop 0
	global_load_lds_dwordx4 v[224:225], off
	s_waitcnt vmcnt(8) lgkmcnt(0)
	s_barrier
	v_mfma_f32_16x16x32_bf16 v[124:127], v[128:131], v[178:181], 0
	v_mfma_f32_16x16x32_bf16 v[120:123], v[136:139], v[178:181], 0
	v_mfma_f32_16x16x32_bf16 v[108:111], v[128:131], v[200:203], 0
	v_mfma_f32_16x16x32_bf16 v[104:107], v[136:139], v[200:203], 0
	v_mfma_f32_16x16x32_bf16 v[92:95], v[128:131], v[208:211], 0
	v_mfma_f32_16x16x32_bf16 v[88:91], v[136:139], v[208:211], 0
	v_mfma_f32_16x16x32_bf16 v[76:79], v[128:131], v[216:219], 0
	v_mfma_f32_16x16x32_bf16 v[72:75], v[136:139], v[216:219], 0
	v_mfma_f32_16x16x32_bf16 v[124:127], v[132:135], v[196:199], v[124:127]
	v_mfma_f32_16x16x32_bf16 v[120:123], v[140:143], v[196:199], v[120:123]
	v_mfma_f32_16x16x32_bf16 v[108:111], v[132:135], v[204:207], v[108:111]
	v_mfma_f32_16x16x32_bf16 v[104:107], v[140:143], v[204:207], v[104:107]
	v_mfma_f32_16x16x32_bf16 v[92:95], v[132:135], v[212:215], v[92:95]
	v_mfma_f32_16x16x32_bf16 v[88:91], v[140:143], v[212:215], v[88:91]
	v_mfma_f32_16x16x32_bf16 v[76:79], v[132:135], v[220:223], v[76:79]
	v_mfma_f32_16x16x32_bf16 v[72:75], v[140:143], v[220:223], v[72:75]
	v_mfma_f32_16x16x32_bf16 v[116:119], v[144:147], v[178:181], 0
	v_mfma_f32_16x16x32_bf16 v[112:115], v[152:155], v[178:181], 0
	v_mfma_f32_16x16x32_bf16 v[100:103], v[144:147], v[200:203], 0
	v_mfma_f32_16x16x32_bf16 v[96:99], v[152:155], v[200:203], 0
	v_mfma_f32_16x16x32_bf16 v[84:87], v[144:147], v[208:211], 0
	v_mfma_f32_16x16x32_bf16 v[80:83], v[152:155], v[208:211], 0
	v_mfma_f32_16x16x32_bf16 v[68:71], v[144:147], v[216:219], 0
	v_mfma_f32_16x16x32_bf16 v[64:67], v[152:155], v[216:219], 0
	v_mfma_f32_16x16x32_bf16 v[116:119], v[148:151], v[196:199], v[116:119]
	v_mfma_f32_16x16x32_bf16 v[112:115], v[156:159], v[196:199], v[112:115]
	v_mfma_f32_16x16x32_bf16 v[100:103], v[148:151], v[204:207], v[100:103]
	v_mfma_f32_16x16x32_bf16 v[96:99], v[156:159], v[204:207], v[96:99]
	v_mfma_f32_16x16x32_bf16 v[84:87], v[148:151], v[212:215], v[84:87]
	v_mfma_f32_16x16x32_bf16 v[80:83], v[156:159], v[212:215], v[80:83]
	v_mfma_f32_16x16x32_bf16 v[68:71], v[148:151], v[220:223], v[68:71]
	v_mfma_f32_16x16x32_bf16 v[64:67], v[156:159], v[220:223], v[64:67]
	s_barrier
	s_add_i32 s53, s43, s34
	v_lshl_add_u64 v[224:225], s[26:27], 0, v[164:165]
	s_mov_b32 m0, s53
	ds_read_b128 v[178:181], v195 offset:16384
	ds_read_b128 v[196:199], v195 offset:17408
	ds_read_b128 v[200:203], v195 offset:18432
	ds_read_b128 v[204:207], v195 offset:19456
	ds_read_b128 v[208:211], v195 offset:20480
	ds_read_b128 v[212:215], v195 offset:21504
	ds_read_b128 v[216:219], v195 offset:22528
	ds_read_b128 v[220:223], v195 offset:23552
	global_load_lds_dwordx4 v[224:225], off
	s_add_i32 m0, s53, 0x2000
	s_add_u32 s54, s26, 0x100000
	v_lshl_add_u64 v[226:227], s[26:27], 0, v[168:169]
	s_addc_u32 s55, s27, 0
	s_add_i32 s53, s44, s34
	global_load_lds_dwordx4 v[226:227], off
	v_lshl_add_u64 v[228:229], s[54:55], 0, v[164:165]
	s_mov_b32 m0, s53
	v_lshl_add_u64 v[230:231], s[28:29], 0, v[166:167]
	global_load_lds_dwordx4 v[228:229], off
	v_lshl_add_u64 v[228:229], s[54:55], 0, v[168:169]
	s_add_i32 m0, s53, 0x2000
	s_nop 0
	global_load_lds_dwordx4 v[228:229], off
	v_lshl_add_u64 v[228:229], s[28:29], 0, v[162:163]
	s_mov_b32 m0, s23
	s_nop 0
	global_load_lds_dwordx4 v[228:229], off
	s_mov_b32 m0, s25
	s_nop 0
	global_load_lds_dwordx4 v[230:231], off
	s_waitcnt vmcnt(8) lgkmcnt(0)
	s_barrier
	v_mfma_f32_16x16x32_bf16 v[60:63], v[128:131], v[178:181], 0
	v_mfma_f32_16x16x32_bf16 v[56:59], v[136:139], v[178:181], 0
	v_mfma_f32_16x16x32_bf16 v[44:47], v[128:131], v[200:203], 0
	v_mfma_f32_16x16x32_bf16 v[40:43], v[136:139], v[200:203], 0
	v_mfma_f32_16x16x32_bf16 v[28:31], v[128:131], v[208:211], 0
	v_mfma_f32_16x16x32_bf16 v[24:27], v[136:139], v[208:211], 0
	v_mfma_f32_16x16x32_bf16 v[12:15], v[128:131], v[216:219], 0
	v_mfma_f32_16x16x32_bf16 v[8:11], v[136:139], v[216:219], 0
	v_mfma_f32_16x16x32_bf16 v[60:63], v[132:135], v[196:199], v[60:63]
	v_mfma_f32_16x16x32_bf16 v[56:59], v[140:143], v[196:199], v[56:59]
	v_mfma_f32_16x16x32_bf16 v[44:47], v[132:135], v[204:207], v[44:47]
	v_mfma_f32_16x16x32_bf16 v[40:43], v[140:143], v[204:207], v[40:43]
	v_mfma_f32_16x16x32_bf16 v[28:31], v[132:135], v[212:215], v[28:31]
	v_mfma_f32_16x16x32_bf16 v[24:27], v[140:143], v[212:215], v[24:27]
	v_mfma_f32_16x16x32_bf16 v[12:15], v[132:135], v[220:223], v[12:15]
	v_mfma_f32_16x16x32_bf16 v[8:11], v[140:143], v[220:223], v[8:11]
	v_mfma_f32_16x16x32_bf16 v[52:55], v[144:147], v[178:181], 0
	v_mfma_f32_16x16x32_bf16 v[48:51], v[152:155], v[178:181], 0
	v_mfma_f32_16x16x32_bf16 v[36:39], v[144:147], v[200:203], 0
	v_mfma_f32_16x16x32_bf16 v[32:35], v[152:155], v[200:203], 0
	v_mfma_f32_16x16x32_bf16 v[20:23], v[144:147], v[208:211], 0
	v_mfma_f32_16x16x32_bf16 v[16:19], v[152:155], v[208:211], 0
	v_mfma_f32_16x16x32_bf16 v[4:7], v[144:147], v[216:219], 0
	v_mfma_f32_16x16x32_bf16 v[0:3], v[152:155], v[216:219], 0
	v_mfma_f32_16x16x32_bf16 v[52:55], v[148:151], v[196:199], v[52:55]
	v_mfma_f32_16x16x32_bf16 v[48:51], v[156:159], v[196:199], v[48:51]
	v_mfma_f32_16x16x32_bf16 v[36:39], v[148:151], v[204:207], v[36:39]
	v_mfma_f32_16x16x32_bf16 v[32:35], v[156:159], v[204:207], v[32:35]
	v_mfma_f32_16x16x32_bf16 v[20:23], v[148:151], v[212:215], v[20:23]
	v_mfma_f32_16x16x32_bf16 v[16:19], v[156:159], v[212:215], v[16:19]
	v_mfma_f32_16x16x32_bf16 v[4:7], v[148:151], v[220:223], v[4:7]
	v_mfma_f32_16x16x32_bf16 v[0:3], v[156:159], v[220:223], v[0:3]
	s_barrier
	s_add_i32 s53, 0, 0x18000
	s_add_i32 s54, 0, 0x1c000
	v_add_u32_e32 v140, s53, v188
	v_add_u32_e32 v156, s54, v188
	ds_read_b128 v[128:131], v140
	ds_read_b128 v[132:135], v140 offset:1024
	ds_read_b128 v[136:139], v140 offset:2048
	ds_read_b128 v[140:143], v140 offset:3072
	ds_read_b128 v[144:147], v156
	ds_read_b128 v[148:151], v156 offset:1024
	ds_read_b128 v[152:155], v156 offset:2048
	ds_read_b128 v[156:159], v156 offset:3072
	s_add_u32 s28, s28, 0x100000
	s_addc_u32 s29, s29, 0
	s_mov_b32 m0, s35
	v_lshl_add_u64 v[232:233], s[28:29], 0, v[162:163]
	ds_read_b128 v[178:181], v195 offset:32768
	ds_read_b128 v[196:199], v195 offset:33792
	ds_read_b128 v[200:203], v195 offset:34816
	ds_read_b128 v[204:207], v195 offset:35840
	ds_read_b128 v[208:211], v195 offset:36864
	ds_read_b128 v[212:215], v195 offset:37888
	ds_read_b128 v[216:219], v195 offset:38912
	ds_read_b128 v[220:223], v195 offset:39936
	global_load_lds_dwordx4 v[232:233], off
	v_lshl_add_u64 v[232:233], s[28:29], 0, v[166:167]
	s_mov_b32 m0, s36
	s_nop 0
	global_load_lds_dwordx4 v[232:233], off
	s_waitcnt vmcnt(8) lgkmcnt(0)
	s_barrier
	v_mfma_f32_16x16x32_bf16 v[124:127], v[128:131], v[178:181], v[124:127]
	v_mfma_f32_16x16x32_bf16 v[120:123], v[136:139], v[178:181], v[120:123]
	v_mfma_f32_16x16x32_bf16 v[108:111], v[128:131], v[200:203], v[108:111]
	v_mfma_f32_16x16x32_bf16 v[104:107], v[136:139], v[200:203], v[104:107]
	v_mfma_f32_16x16x32_bf16 v[92:95], v[128:131], v[208:211], v[92:95]
	v_mfma_f32_16x16x32_bf16 v[88:91], v[136:139], v[208:211], v[88:91]
	v_mfma_f32_16x16x32_bf16 v[76:79], v[128:131], v[216:219], v[76:79]
	v_mfma_f32_16x16x32_bf16 v[72:75], v[136:139], v[216:219], v[72:75]
	v_mfma_f32_16x16x32_bf16 v[124:127], v[132:135], v[196:199], v[124:127]
	v_mfma_f32_16x16x32_bf16 v[120:123], v[140:143], v[196:199], v[120:123]
	v_mfma_f32_16x16x32_bf16 v[108:111], v[132:135], v[204:207], v[108:111]
	v_mfma_f32_16x16x32_bf16 v[104:107], v[140:143], v[204:207], v[104:107]
	v_mfma_f32_16x16x32_bf16 v[92:95], v[132:135], v[212:215], v[92:95]
	v_mfma_f32_16x16x32_bf16 v[88:91], v[140:143], v[212:215], v[88:91]
	v_mfma_f32_16x16x32_bf16 v[76:79], v[132:135], v[220:223], v[76:79]
	v_mfma_f32_16x16x32_bf16 v[72:75], v[140:143], v[220:223], v[72:75]
	v_mfma_f32_16x16x32_bf16 v[116:119], v[144:147], v[178:181], v[116:119]
	v_mfma_f32_16x16x32_bf16 v[112:115], v[152:155], v[178:181], v[112:115]
	v_mfma_f32_16x16x32_bf16 v[100:103], v[144:147], v[200:203], v[100:103]
	v_mfma_f32_16x16x32_bf16 v[96:99], v[152:155], v[200:203], v[96:99]
	v_mfma_f32_16x16x32_bf16 v[84:87], v[144:147], v[208:211], v[84:87]
	v_mfma_f32_16x16x32_bf16 v[80:83], v[152:155], v[208:211], v[80:83]
	v_mfma_f32_16x16x32_bf16 v[68:71], v[144:147], v[216:219], v[68:71]
	v_mfma_f32_16x16x32_bf16 v[64:67], v[152:155], v[216:219], v[64:67]
	v_mfma_f32_16x16x32_bf16 v[116:119], v[148:151], v[196:199], v[116:119]
	v_mfma_f32_16x16x32_bf16 v[112:115], v[156:159], v[196:199], v[112:115]
	v_mfma_f32_16x16x32_bf16 v[100:103], v[148:151], v[204:207], v[100:103]
	v_mfma_f32_16x16x32_bf16 v[96:99], v[156:159], v[204:207], v[96:99]
	v_mfma_f32_16x16x32_bf16 v[84:87], v[148:151], v[212:215], v[84:87]
	v_mfma_f32_16x16x32_bf16 v[80:83], v[156:159], v[212:215], v[80:83]
	v_mfma_f32_16x16x32_bf16 v[68:71], v[148:151], v[220:223], v[68:71]
	v_mfma_f32_16x16x32_bf16 v[64:67], v[156:159], v[220:223], v[64:67]
	s_barrier
	s_add_i32 s28, s53, s34
	v_lshl_add_u64 v[224:225], v[224:225], 0, s[10:11]
	s_mov_b32 m0, s28
	ds_read_b128 v[178:181], v195 offset:49152
	ds_read_b128 v[196:199], v195 offset:50176
	ds_read_b128 v[200:203], v195 offset:51200
	ds_read_b128 v[204:207], v195 offset:52224
	ds_read_b128 v[208:211], v195 offset:53248
	ds_read_b128 v[212:215], v195 offset:54272
	ds_read_b128 v[216:219], v195 offset:55296
	ds_read_b128 v[220:223], v195 offset:56320
	global_load_lds_dwordx4 v[224:225], off
	s_add_i32 m0, s28, 0x2000
	s_add_u32 s26, s26, 0x100080
	v_lshl_add_u64 v[224:225], v[226:227], 0, s[10:11]
	s_addc_u32 s27, s27, 0
	s_add_i32 s28, s54, s34
	global_load_lds_dwordx4 v[224:225], off
	v_lshl_add_u64 v[224:225], s[26:27], 0, v[164:165]
	s_mov_b32 m0, s28
	s_nop 0
	global_load_lds_dwordx4 v[224:225], off
	v_lshl_add_u64 v[224:225], s[26:27], 0, v[168:169]
	s_add_i32 m0, s28, 0x2000
	s_nop 0
	global_load_lds_dwordx4 v[224:225], off
	v_lshl_add_u64 v[224:225], v[228:229], 0, s[10:11]
	s_mov_b32 m0, s39
	s_nop 0
	global_load_lds_dwordx4 v[224:225], off
	v_lshl_add_u64 v[224:225], v[230:231], 0, s[10:11]
	s_mov_b32 m0, s40
	s_nop 0
	global_load_lds_dwordx4 v[224:225], off
	s_waitcnt vmcnt(8) lgkmcnt(0)
	s_barrier
	v_mfma_f32_16x16x32_bf16 v[60:63], v[128:131], v[178:181], v[60:63]
	v_mfma_f32_16x16x32_bf16 v[56:59], v[136:139], v[178:181], v[56:59]
	v_mfma_f32_16x16x32_bf16 v[44:47], v[128:131], v[200:203], v[44:47]
	v_mfma_f32_16x16x32_bf16 v[40:43], v[136:139], v[200:203], v[40:43]
	v_mfma_f32_16x16x32_bf16 v[28:31], v[128:131], v[208:211], v[28:31]
	v_mfma_f32_16x16x32_bf16 v[24:27], v[136:139], v[208:211], v[24:27]
	v_mfma_f32_16x16x32_bf16 v[12:15], v[128:131], v[216:219], v[12:15]
	v_mfma_f32_16x16x32_bf16 v[8:11], v[136:139], v[216:219], v[8:11]
	v_mfma_f32_16x16x32_bf16 v[60:63], v[132:135], v[196:199], v[60:63]
	v_mfma_f32_16x16x32_bf16 v[56:59], v[140:143], v[196:199], v[56:59]
	v_mfma_f32_16x16x32_bf16 v[44:47], v[132:135], v[204:207], v[44:47]
	v_mfma_f32_16x16x32_bf16 v[40:43], v[140:143], v[204:207], v[40:43]
	v_mfma_f32_16x16x32_bf16 v[28:31], v[132:135], v[212:215], v[28:31]
	v_mfma_f32_16x16x32_bf16 v[24:27], v[140:143], v[212:215], v[24:27]
	v_mfma_f32_16x16x32_bf16 v[12:15], v[132:135], v[220:223], v[12:15]
	v_mfma_f32_16x16x32_bf16 v[8:11], v[140:143], v[220:223], v[8:11]
	v_mfma_f32_16x16x32_bf16 v[52:55], v[144:147], v[178:181], v[52:55]
	v_mfma_f32_16x16x32_bf16 v[48:51], v[152:155], v[178:181], v[48:51]
	v_mfma_f32_16x16x32_bf16 v[36:39], v[144:147], v[200:203], v[36:39]
	v_mfma_f32_16x16x32_bf16 v[32:35], v[152:155], v[200:203], v[32:35]
	v_mfma_f32_16x16x32_bf16 v[20:23], v[144:147], v[208:211], v[20:23]
	v_mfma_f32_16x16x32_bf16 v[16:19], v[152:155], v[208:211], v[16:19]
	v_mfma_f32_16x16x32_bf16 v[4:7], v[144:147], v[216:219], v[4:7]
	v_mfma_f32_16x16x32_bf16 v[0:3], v[152:155], v[216:219], v[0:3]
	v_mfma_f32_16x16x32_bf16 v[52:55], v[148:151], v[196:199], v[52:55]
	v_mfma_f32_16x16x32_bf16 v[48:51], v[156:159], v[196:199], v[48:51]
	v_mfma_f32_16x16x32_bf16 v[36:39], v[148:151], v[204:207], v[36:39]
	v_mfma_f32_16x16x32_bf16 v[32:35], v[156:159], v[204:207], v[32:35]
	v_mfma_f32_16x16x32_bf16 v[20:23], v[148:151], v[212:215], v[20:23]
	v_mfma_f32_16x16x32_bf16 v[16:19], v[156:159], v[212:215], v[16:19]
	v_mfma_f32_16x16x32_bf16 v[4:7], v[148:151], v[220:223], v[4:7]
	v_mfma_f32_16x16x32_bf16 v[0:3], v[156:159], v[220:223], v[0:3]
	s_barrier
	s_add_i32 s52, s52, 2
	s_add_u32 s0, s0, 0x100
	s_addc_u32 s1, s1, 0
	s_add_u32 s50, s50, 0x100
	s_addc_u32 s51, s51, 0
	s_cmp_gt_u32 s52, 61
	s_cbranch_scc0 .LBB0_1563
	s_branch .Lpeel_exit_8
.LBB0_1563:
	ds_read_b128 v[128:131], v193
	ds_read_b128 v[132:135], v193 offset:1024
	ds_read_b128 v[136:139], v193 offset:2048
	ds_read_b128 v[140:143], v193 offset:3072
	ds_read_b128 v[144:147], v194
	ds_read_b128 v[148:151], v194 offset:1024
	ds_read_b128 v[152:155], v194 offset:2048
	ds_read_b128 v[156:159], v194 offset:3072
	s_add_u32 s26, s0, 0xfff00080
	s_addc_u32 s27, s1, -1
	s_cmp_eq_u32 s52, 60
	s_cselect_b32 s29, s17, s27
	s_cselect_b32 s28, s33, s26
	s_cselect_b32 s27, s15, s51
	s_cselect_b32 s26, s49, s50
	v_lshl_add_u64 v[224:225], s[0:1], 0, v[170:171]
	s_add_i32 m0, s23, 0xc000
	ds_read_b128 v[178:181], v195
	ds_read_b128 v[196:199], v195 offset:1024
	ds_read_b128 v[200:203], v195 offset:2048
	ds_read_b128 v[204:207], v195 offset:3072
	ds_read_b128 v[208:211], v195 offset:4096
	ds_read_b128 v[212:215], v195 offset:5120
	ds_read_b128 v[216:219], v195 offset:6144
	ds_read_b128 v[220:223], v195 offset:7168
	global_load_lds_dwordx4 v[224:225], off
	v_lshl_add_u64 v[224:225], s[0:1], 0, v[172:173]
	s_add_i32 m0, s23, 0xe000
	s_nop 0
	global_load_lds_dwordx4 v[224:225], off
	s_waitcnt vmcnt(8) lgkmcnt(0)
	s_barrier
	v_mfma_f32_16x16x32_bf16 v[124:127], v[128:131], v[178:181], v[124:127]
	v_mfma_f32_16x16x32_bf16 v[120:123], v[136:139], v[178:181], v[120:123]
	v_mfma_f32_16x16x32_bf16 v[108:111], v[128:131], v[200:203], v[108:111]
	v_mfma_f32_16x16x32_bf16 v[104:107], v[136:139], v[200:203], v[104:107]
	v_mfma_f32_16x16x32_bf16 v[92:95], v[128:131], v[208:211], v[92:95]
	v_mfma_f32_16x16x32_bf16 v[88:91], v[136:139], v[208:211], v[88:91]
	v_mfma_f32_16x16x32_bf16 v[76:79], v[128:131], v[216:219], v[76:79]
	v_mfma_f32_16x16x32_bf16 v[72:75], v[136:139], v[216:219], v[72:75]
	v_mfma_f32_16x16x32_bf16 v[124:127], v[132:135], v[196:199], v[124:127]
	v_mfma_f32_16x16x32_bf16 v[120:123], v[140:143], v[196:199], v[120:123]
	v_mfma_f32_16x16x32_bf16 v[108:111], v[132:135], v[204:207], v[108:111]
	v_mfma_f32_16x16x32_bf16 v[104:107], v[140:143], v[204:207], v[104:107]
	v_mfma_f32_16x16x32_bf16 v[92:95], v[132:135], v[212:215], v[92:95]
	v_mfma_f32_16x16x32_bf16 v[88:91], v[140:143], v[212:215], v[88:91]
	v_mfma_f32_16x16x32_bf16 v[76:79], v[132:135], v[220:223], v[76:79]
	v_mfma_f32_16x16x32_bf16 v[72:75], v[140:143], v[220:223], v[72:75]
	v_mfma_f32_16x16x32_bf16 v[116:119], v[144:147], v[178:181], v[116:119]
	v_mfma_f32_16x16x32_bf16 v[112:115], v[152:155], v[178:181], v[112:115]
	v_mfma_f32_16x16x32_bf16 v[100:103], v[144:147], v[200:203], v[100:103]
	v_mfma_f32_16x16x32_bf16 v[96:99], v[152:155], v[200:203], v[96:99]
	v_mfma_f32_16x16x32_bf16 v[84:87], v[144:147], v[208:211], v[84:87]
	v_mfma_f32_16x16x32_bf16 v[80:83], v[152:155], v[208:211], v[80:83]
	v_mfma_f32_16x16x32_bf16 v[68:71], v[144:147], v[216:219], v[68:71]
	v_mfma_f32_16x16x32_bf16 v[64:67], v[152:155], v[216:219], v[64:67]
	v_mfma_f32_16x16x32_bf16 v[116:119], v[148:151], v[196:199], v[116:119]
	v_mfma_f32_16x16x32_bf16 v[112:115], v[156:159], v[196:199], v[112:115]
	v_mfma_f32_16x16x32_bf16 v[100:103], v[148:151], v[204:207], v[100:103]
	v_mfma_f32_16x16x32_bf16 v[96:99], v[156:159], v[204:207], v[96:99]
	v_mfma_f32_16x16x32_bf16 v[84:87], v[148:151], v[212:215], v[84:87]
	v_mfma_f32_16x16x32_bf16 v[80:83], v[156:159], v[212:215], v[80:83]
	v_mfma_f32_16x16x32_bf16 v[68:71], v[148:151], v[220:223], v[68:71]
	v_mfma_f32_16x16x32_bf16 v[64:67], v[156:159], v[220:223], v[64:67]
	s_barrier
	s_add_i32 s53, s43, s34
	v_lshl_add_u64 v[224:225], s[26:27], 0, v[164:165]
	s_mov_b32 m0, s53
	ds_read_b128 v[178:181], v195 offset:16384
	ds_read_b128 v[196:199], v195 offset:17408
	ds_read_b128 v[200:203], v195 offset:18432
	ds_read_b128 v[204:207], v195 offset:19456
	ds_read_b128 v[208:211], v195 offset:20480
	ds_read_b128 v[212:215], v195 offset:21504
	ds_read_b128 v[216:219], v195 offset:22528
	ds_read_b128 v[220:223], v195 offset:23552
	global_load_lds_dwordx4 v[224:225], off
	s_add_i32 m0, s53, 0x2000
	s_add_u32 s54, s26, 0x100000
	v_lshl_add_u64 v[226:227], s[26:27], 0, v[168:169]
	s_addc_u32 s55, s27, 0
	s_add_i32 s53, s44, s34
	global_load_lds_dwordx4 v[226:227], off
	v_lshl_add_u64 v[228:229], s[54:55], 0, v[164:165]
	s_mov_b32 m0, s53
	v_lshl_add_u64 v[230:231], s[28:29], 0, v[166:167]
	global_load_lds_dwordx4 v[228:229], off
	v_lshl_add_u64 v[228:229], s[54:55], 0, v[168:169]
	s_add_i32 m0, s53, 0x2000
	s_nop 0
	global_load_lds_dwordx4 v[228:229], off
	v_lshl_add_u64 v[228:229], s[28:29], 0, v[162:163]
	s_mov_b32 m0, s23
	s_nop 0
	global_load_lds_dwordx4 v[228:229], off
	s_mov_b32 m0, s25
	s_nop 0
	global_load_lds_dwordx4 v[230:231], off
	s_waitcnt vmcnt(8) lgkmcnt(0)
	s_barrier
	v_mfma_f32_16x16x32_bf16 v[60:63], v[128:131], v[178:181], v[60:63]
	v_mfma_f32_16x16x32_bf16 v[56:59], v[136:139], v[178:181], v[56:59]
	v_mfma_f32_16x16x32_bf16 v[44:47], v[128:131], v[200:203], v[44:47]
	v_mfma_f32_16x16x32_bf16 v[40:43], v[136:139], v[200:203], v[40:43]
	v_mfma_f32_16x16x32_bf16 v[28:31], v[128:131], v[208:211], v[28:31]
	v_mfma_f32_16x16x32_bf16 v[24:27], v[136:139], v[208:211], v[24:27]
	v_mfma_f32_16x16x32_bf16 v[12:15], v[128:131], v[216:219], v[12:15]
	v_mfma_f32_16x16x32_bf16 v[8:11], v[136:139], v[216:219], v[8:11]
	v_mfma_f32_16x16x32_bf16 v[60:63], v[132:135], v[196:199], v[60:63]
	v_mfma_f32_16x16x32_bf16 v[56:59], v[140:143], v[196:199], v[56:59]
	v_mfma_f32_16x16x32_bf16 v[44:47], v[132:135], v[204:207], v[44:47]
	v_mfma_f32_16x16x32_bf16 v[40:43], v[140:143], v[204:207], v[40:43]
	v_mfma_f32_16x16x32_bf16 v[28:31], v[132:135], v[212:215], v[28:31]
	v_mfma_f32_16x16x32_bf16 v[24:27], v[140:143], v[212:215], v[24:27]
	v_mfma_f32_16x16x32_bf16 v[12:15], v[132:135], v[220:223], v[12:15]
	v_mfma_f32_16x16x32_bf16 v[8:11], v[140:143], v[220:223], v[8:11]
	v_mfma_f32_16x16x32_bf16 v[52:55], v[144:147], v[178:181], v[52:55]
	v_mfma_f32_16x16x32_bf16 v[48:51], v[152:155], v[178:181], v[48:51]
	v_mfma_f32_16x16x32_bf16 v[36:39], v[144:147], v[200:203], v[36:39]
	v_mfma_f32_16x16x32_bf16 v[32:35], v[152:155], v[200:203], v[32:35]
	v_mfma_f32_16x16x32_bf16 v[20:23], v[144:147], v[208:211], v[20:23]
	v_mfma_f32_16x16x32_bf16 v[16:19], v[152:155], v[208:211], v[16:19]
	v_mfma_f32_16x16x32_bf16 v[4:7], v[144:147], v[216:219], v[4:7]
	v_mfma_f32_16x16x32_bf16 v[0:3], v[152:155], v[216:219], v[0:3]
	v_mfma_f32_16x16x32_bf16 v[52:55], v[148:151], v[196:199], v[52:55]
	v_mfma_f32_16x16x32_bf16 v[48:51], v[156:159], v[196:199], v[48:51]
	v_mfma_f32_16x16x32_bf16 v[36:39], v[148:151], v[204:207], v[36:39]
	v_mfma_f32_16x16x32_bf16 v[32:35], v[156:159], v[204:207], v[32:35]
	v_mfma_f32_16x16x32_bf16 v[20:23], v[148:151], v[212:215], v[20:23]
	v_mfma_f32_16x16x32_bf16 v[16:19], v[156:159], v[212:215], v[16:19]
	v_mfma_f32_16x16x32_bf16 v[4:7], v[148:151], v[220:223], v[4:7]
	v_mfma_f32_16x16x32_bf16 v[0:3], v[156:159], v[220:223], v[0:3]
	s_barrier
	s_add_i32 s53, 0, 0x18000
	s_add_i32 s54, 0, 0x1c000
	v_add_u32_e32 v140, s53, v188
	v_add_u32_e32 v156, s54, v188
	ds_read_b128 v[128:131], v140
	ds_read_b128 v[132:135], v140 offset:1024
	ds_read_b128 v[136:139], v140 offset:2048
	ds_read_b128 v[140:143], v140 offset:3072
	ds_read_b128 v[144:147], v156
	ds_read_b128 v[148:151], v156 offset:1024
	ds_read_b128 v[152:155], v156 offset:2048
	ds_read_b128 v[156:159], v156 offset:3072
	s_add_u32 s28, s28, 0x100000
	s_addc_u32 s29, s29, 0
	s_mov_b32 m0, s35
	v_lshl_add_u64 v[232:233], s[28:29], 0, v[162:163]
	ds_read_b128 v[178:181], v195 offset:32768
	ds_read_b128 v[196:199], v195 offset:33792
	ds_read_b128 v[200:203], v195 offset:34816
	ds_read_b128 v[204:207], v195 offset:35840
	ds_read_b128 v[208:211], v195 offset:36864
	ds_read_b128 v[212:215], v195 offset:37888
	ds_read_b128 v[216:219], v195 offset:38912
	ds_read_b128 v[220:223], v195 offset:39936
	global_load_lds_dwordx4 v[232:233], off
	v_lshl_add_u64 v[232:233], s[28:29], 0, v[166:167]
	s_mov_b32 m0, s36
	s_nop 0
	global_load_lds_dwordx4 v[232:233], off
	s_waitcnt vmcnt(8) lgkmcnt(0)
	s_barrier
	v_mfma_f32_16x16x32_bf16 v[124:127], v[128:131], v[178:181], v[124:127]
	v_mfma_f32_16x16x32_bf16 v[120:123], v[136:139], v[178:181], v[120:123]
	v_mfma_f32_16x16x32_bf16 v[108:111], v[128:131], v[200:203], v[108:111]
	v_mfma_f32_16x16x32_bf16 v[104:107], v[136:139], v[200:203], v[104:107]
	v_mfma_f32_16x16x32_bf16 v[92:95], v[128:131], v[208:211], v[92:95]
	v_mfma_f32_16x16x32_bf16 v[88:91], v[136:139], v[208:211], v[88:91]
	v_mfma_f32_16x16x32_bf16 v[76:79], v[128:131], v[216:219], v[76:79]
	v_mfma_f32_16x16x32_bf16 v[72:75], v[136:139], v[216:219], v[72:75]
	v_mfma_f32_16x16x32_bf16 v[124:127], v[132:135], v[196:199], v[124:127]
	v_mfma_f32_16x16x32_bf16 v[120:123], v[140:143], v[196:199], v[120:123]
	v_mfma_f32_16x16x32_bf16 v[108:111], v[132:135], v[204:207], v[108:111]
	v_mfma_f32_16x16x32_bf16 v[104:107], v[140:143], v[204:207], v[104:107]
	v_mfma_f32_16x16x32_bf16 v[92:95], v[132:135], v[212:215], v[92:95]
	v_mfma_f32_16x16x32_bf16 v[88:91], v[140:143], v[212:215], v[88:91]
	v_mfma_f32_16x16x32_bf16 v[76:79], v[132:135], v[220:223], v[76:79]
	v_mfma_f32_16x16x32_bf16 v[72:75], v[140:143], v[220:223], v[72:75]
	v_mfma_f32_16x16x32_bf16 v[116:119], v[144:147], v[178:181], v[116:119]
	v_mfma_f32_16x16x32_bf16 v[112:115], v[152:155], v[178:181], v[112:115]
	v_mfma_f32_16x16x32_bf16 v[100:103], v[144:147], v[200:203], v[100:103]
	v_mfma_f32_16x16x32_bf16 v[96:99], v[152:155], v[200:203], v[96:99]
	v_mfma_f32_16x16x32_bf16 v[84:87], v[144:147], v[208:211], v[84:87]
	v_mfma_f32_16x16x32_bf16 v[80:83], v[152:155], v[208:211], v[80:83]
	v_mfma_f32_16x16x32_bf16 v[68:71], v[144:147], v[216:219], v[68:71]
	v_mfma_f32_16x16x32_bf16 v[64:67], v[152:155], v[216:219], v[64:67]
	v_mfma_f32_16x16x32_bf16 v[116:119], v[148:151], v[196:199], v[116:119]
	v_mfma_f32_16x16x32_bf16 v[112:115], v[156:159], v[196:199], v[112:115]
	v_mfma_f32_16x16x32_bf16 v[100:103], v[148:151], v[204:207], v[100:103]
	v_mfma_f32_16x16x32_bf16 v[96:99], v[156:159], v[204:207], v[96:99]
	v_mfma_f32_16x16x32_bf16 v[84:87], v[148:151], v[212:215], v[84:87]
	v_mfma_f32_16x16x32_bf16 v[80:83], v[156:159], v[212:215], v[80:83]
	v_mfma_f32_16x16x32_bf16 v[68:71], v[148:151], v[220:223], v[68:71]
	v_mfma_f32_16x16x32_bf16 v[64:67], v[156:159], v[220:223], v[64:67]
	s_barrier
	s_add_i32 s28, s53, s34
	v_lshl_add_u64 v[224:225], v[224:225], 0, s[10:11]
	s_mov_b32 m0, s28
	ds_read_b128 v[178:181], v195 offset:49152
	ds_read_b128 v[196:199], v195 offset:50176
	ds_read_b128 v[200:203], v195 offset:51200
	ds_read_b128 v[204:207], v195 offset:52224
	ds_read_b128 v[208:211], v195 offset:53248
	ds_read_b128 v[212:215], v195 offset:54272
	ds_read_b128 v[216:219], v195 offset:55296
	ds_read_b128 v[220:223], v195 offset:56320
	global_load_lds_dwordx4 v[224:225], off
	s_add_i32 m0, s28, 0x2000
	s_add_u32 s26, s26, 0x100080
	v_lshl_add_u64 v[224:225], v[226:227], 0, s[10:11]
	s_addc_u32 s27, s27, 0
	s_add_i32 s28, s54, s34
	global_load_lds_dwordx4 v[224:225], off
	v_lshl_add_u64 v[224:225], s[26:27], 0, v[164:165]
	s_mov_b32 m0, s28
	s_nop 0
	global_load_lds_dwordx4 v[224:225], off
	v_lshl_add_u64 v[224:225], s[26:27], 0, v[168:169]
	s_add_i32 m0, s28, 0x2000
	s_nop 0
	global_load_lds_dwordx4 v[224:225], off
	v_lshl_add_u64 v[224:225], v[228:229], 0, s[10:11]
	s_mov_b32 m0, s39
	s_nop 0
	global_load_lds_dwordx4 v[224:225], off
	v_lshl_add_u64 v[224:225], v[230:231], 0, s[10:11]
	s_mov_b32 m0, s40
	s_nop 0
	global_load_lds_dwordx4 v[224:225], off
	s_waitcnt vmcnt(8) lgkmcnt(0)
	s_barrier
	v_mfma_f32_16x16x32_bf16 v[60:63], v[128:131], v[178:181], v[60:63]
	v_mfma_f32_16x16x32_bf16 v[56:59], v[136:139], v[178:181], v[56:59]
	v_mfma_f32_16x16x32_bf16 v[44:47], v[128:131], v[200:203], v[44:47]
	v_mfma_f32_16x16x32_bf16 v[40:43], v[136:139], v[200:203], v[40:43]
	v_mfma_f32_16x16x32_bf16 v[28:31], v[128:131], v[208:211], v[28:31]
	v_mfma_f32_16x16x32_bf16 v[24:27], v[136:139], v[208:211], v[24:27]
	v_mfma_f32_16x16x32_bf16 v[12:15], v[128:131], v[216:219], v[12:15]
	v_mfma_f32_16x16x32_bf16 v[8:11], v[136:139], v[216:219], v[8:11]
	v_mfma_f32_16x16x32_bf16 v[60:63], v[132:135], v[196:199], v[60:63]
	v_mfma_f32_16x16x32_bf16 v[56:59], v[140:143], v[196:199], v[56:59]
	v_mfma_f32_16x16x32_bf16 v[44:47], v[132:135], v[204:207], v[44:47]
	v_mfma_f32_16x16x32_bf16 v[40:43], v[140:143], v[204:207], v[40:43]
	v_mfma_f32_16x16x32_bf16 v[28:31], v[132:135], v[212:215], v[28:31]
	v_mfma_f32_16x16x32_bf16 v[24:27], v[140:143], v[212:215], v[24:27]
	v_mfma_f32_16x16x32_bf16 v[12:15], v[132:135], v[220:223], v[12:15]
	v_mfma_f32_16x16x32_bf16 v[8:11], v[140:143], v[220:223], v[8:11]
	v_mfma_f32_16x16x32_bf16 v[52:55], v[144:147], v[178:181], v[52:55]
	v_mfma_f32_16x16x32_bf16 v[48:51], v[152:155], v[178:181], v[48:51]
	v_mfma_f32_16x16x32_bf16 v[36:39], v[144:147], v[200:203], v[36:39]
	v_mfma_f32_16x16x32_bf16 v[32:35], v[152:155], v[200:203], v[32:35]
	v_mfma_f32_16x16x32_bf16 v[20:23], v[144:147], v[208:211], v[20:23]
	v_mfma_f32_16x16x32_bf16 v[16:19], v[152:155], v[208:211], v[16:19]
	v_mfma_f32_16x16x32_bf16 v[4:7], v[144:147], v[216:219], v[4:7]
	v_mfma_f32_16x16x32_bf16 v[0:3], v[152:155], v[216:219], v[0:3]
	v_mfma_f32_16x16x32_bf16 v[52:55], v[148:151], v[196:199], v[52:55]
	v_mfma_f32_16x16x32_bf16 v[48:51], v[156:159], v[196:199], v[48:51]
	v_mfma_f32_16x16x32_bf16 v[36:39], v[148:151], v[204:207], v[36:39]
	v_mfma_f32_16x16x32_bf16 v[32:35], v[156:159], v[204:207], v[32:35]
	v_mfma_f32_16x16x32_bf16 v[20:23], v[148:151], v[212:215], v[20:23]
	v_mfma_f32_16x16x32_bf16 v[16:19], v[156:159], v[212:215], v[16:19]
	v_mfma_f32_16x16x32_bf16 v[4:7], v[148:151], v[220:223], v[4:7]
	v_mfma_f32_16x16x32_bf16 v[0:3], v[156:159], v[220:223], v[0:3]
	s_barrier
	s_add_i32 s52, s52, 2
	s_add_u32 s0, s0, 0x100
	s_addc_u32 s1, s1, 0
	s_add_u32 s50, s50, 0x100
	s_addc_u32 s51, s51, 0
	s_cmp_gt_u32 s52, 61
	s_cbranch_scc0 .LBB0_1563
